# removed store-ack drains: scan copy stores before YL/QQ stores; prep per-token vmcnt(0) moved into rare conditional-load paths; fixup tt-loop loads de-waterfalled (ushort loads get own registers, one
# speedup vs baseline: 1.0687x; 1.0388x over previous
; __device__ __forceinline__ void even_prep(const Params& p, int j, LAS unsigned char* lds, const int wave_s) {
;     ...
;                     const float u0 = ur[i + 2];
;                     float um1 = ur[i + 1], um2 = ur[i];
;                     if (t < 1) um1 = samp ? sconv[(b * 2 + 1) * 512 + tid] : 0.f;
;                     if (t < 2) um2 = samp ? sconv[(b * 2 + t) * 512 + tid] : 0.f;
.LBB0_1125:
	v_lshlrev_b32_e32 v76, 16, v157
	v_lshlrev_b32_e32 v77, 16, v158
	s_xor_b64 s[44:45], s[76:77], -1
	s_andn2_b64 vcc, exec, s[44:45]
	v_mul_f32_e32 v157, v76, v77
	s_cbranch_vccnz .LBB0_1127
	v_lshl_add_u32 v76, s27, 10, v104
	v_ashrrev_i32_e32 v77, 31, v76
	v_lshl_add_u64 v[76:77], v[76:77], 2, s[48:49]
	global_load_dword v79, v[76:77], off
	s_waitcnt vmcnt(0)
	s_branch .LBB0_1128

; __device__ __forceinline__ void even_prep(const Params& p, int j, LAS unsigned char* lds, const int wave_s) {
;     ...
;                     if (t < 1) um1 = samp ? sconv[(b * 2 + 1) * 512 + tid] : 0.f;
;                     if (t < 2) um2 = samp ? sconv[(b * 2 + t) * 512 + tid] : 0.f;
.LBB0_1128:
	s_cmp_gt_u32 s25, 1
	s_cselect_b64 s[42:43], -1, 0
	s_or_b64 s[44:45], s[74:75], s[42:43]
	s_and_b64 vcc, exec, s[44:45]
	s_cbranch_vccnz .LBB0_1130
	v_lshl_add_u32 v76, s27, 10, v108
	v_ashrrev_i32_e32 v77, 31, v76
	v_lshl_add_u64 v[76:77], v[76:77], 2, s[48:49]
	global_load_dword v76, v[76:77], off
	s_waitcnt vmcnt(0)
	s_branch .LBB0_1131

; __device__ __forceinline__ unsigned f2bf(float f) { unsigned u = __float_as_uint(f); return (u + 0x7fffu + ((u >> 16) & 1u)) >> 16; }
; __device__ __forceinline__ float silu(float x) { return x / (1.f + __expf(-x)); }
; __device__ __forceinline__ void even_prep(const Params& p, int j, LAS unsigned char* lds, const int wave_s) {
;     ...
;             for (int i = 0; i < 8; ++i) { const int n = nh + i;
;                 if (n < n1) {
;                     int b, t, T; const bool samp = n >= NP;
;                     if (!samp) { b = n >> 11; t = n & 2047; T = SEQ; } else { const int s = n - NP; b = s >> 3; t = s & 7; T = ST; }
;                     const float cr = rr[i + 1], ck = kr[i + 1], cv = vr[i + 1];
;                     float qr = rr[i], qk = kr[i], qv = vr[i];
;                     if (t == 0) { qr = 0.f; qk = 0.f; qv = 0.f; if (samp) { qr = sshift[b * ASW + tid]; qk = sshift[b * ASW + 512 + tid]; qv = sshift[b * ASW + 1024 + tid]; } }
;     ...
;                     if (t < 1) um1 = samp ? sconv[(b * 2 + 1) * 512 + tid] : 0.f;
;                     if (t < 2) um2 = samp ? sconv[(b * 2 + t) * 512 + tid] : 0.f;
;                     const float yc = cw0 * um2 + cw1 * um1 + cw2 * u0;
;                     MIX[(size_t)n * DM + 512 + tid] = (bf16_t)f2bf(bbv[i] * yc * silu(zbv[i]));
;                     if (t >= T - 2) { float* co = p.out + (samp ? O_CV_S + (size_t)((j * SB + b) * 2 + (t - (T - 2))) * 512 : O_CV_P + (size_t)((j * PB + b) * 2 + (t - (T - 2))) * 512); co[tid] = u0; }
.LBB0_1131:
	v_lshlrev_b32_e32 v77, 16, v155
	v_lshlrev_b32_e32 v78, 16, v156
	v_mul_f32_e32 v78, v77, v78
	v_pk_mul_f32 v[154:155], v[68:69], v[78:79]
	v_lshlrev_b32_e32 v77, 16, v162
	v_fma_f32 v76, v103, v76, v155
	v_lshlrev_b32_e32 v153, 16, v163
	v_add_f32_e32 v76, v154, v76
	v_mul_f32_e32 v76, v76, v77
	v_mul_f32_e32 v77, 0xbfb8aa3b, v153
	v_exp_f32_e32 v77, v77
	s_nop 0
	v_add_f32_e32 v77, 1.0, v77
	v_div_scale_f32 v79, s[42:43], v77, v77, v153
	v_rcp_f32_e32 v154, v79
	s_lshl_b64 s[42:43], s[2:3], 11
	s_add_i32 s3, s31, -2
	s_cmp_lt_u32 s25, s3
	v_fma_f32 v155, -v79, v154, 1.0
	v_fmac_f32_e32 v154, v155, v154
	v_div_scale_f32 v155, vcc, v153, v77, v153
	v_mul_f32_e32 v156, v155, v154
	v_fma_f32 v158, -v79, v156, v155
	v_fmac_f32_e32 v156, v158, v154
	v_fma_f32 v79, -v79, v156, v155
	v_div_fmas_f32 v79, v79, v154, v156
	v_div_fixup_f32 v77, v79, v77, v153
	v_mul_f32_e32 v76, v77, v76
	v_bfe_u32 v77, v76, 16, 1
	v_add3_u32 v79, v76, v77, s6
	v_lshl_add_u64 v[76:77], v[72:73], 0, s[42:43]
	global_store_short_d16_hi v[76:77], v79, off
	s_cbranch_scc1 .LBB0_1133
	s_lshl_b32 s3, s65, 1
	s_and_b64 s[42:43], s[74:75], exec
	s_cselect_b32 s27, s34, s5
	s_mov_b32 s42, 0x4b82000
	s_cselect_b32 s96, s42, 0x4b92000
	s_sub_i32 s27, s27, s31
	s_add_i32 s25, s25, s27
	s_add_i32 s3, s25, s3
	s_add_i32 s42, s3, 2
	s_ashr_i32 s43, s42, 31
	s_lshl_b64 s[42:43], s[42:43], 11
	v_lshl_add_u64 v[76:77], v[74:75], 0, s[42:43]
	v_lshl_add_u64 v[76:77], v[76:77], 0, s[96:97]
	global_store_dword v[76:77], v78, off
.LBB0_1133:
	v_lshlrev_b32_e32 v76, 16, v151
	v_lshlrev_b32_e32 v77, 16, v152
	v_mul_f32_e32 v76, v76, v77
	v_lshlrev_b32_e32 v79, 16, v160
	v_lshlrev_b32_e32 v151, 16, v161
	s_cmp_ge_i32 s72, s33
	v_lshlrev_b32_e32 v152, 16, v159
	s_mov_b32 s96, 0x88888889
	s_cbranch_scc1 .LBB0_1151
	s_add_i32 s3, s2, 0xffffc001
	s_lshr_b32 s25, s3, 3
	s_and_b32 s3, s72, 0x7ff
	s_cmpk_lt_i32 s2, 0x3fff
	s_cselect_b64 s[44:45], -1, 0
	s_and_b64 s[42:43], s[44:45], exec
	v_readlane_b32 s27, v254, 30
	s_cselect_b32 s3, s3, s27
	s_cmp_lg_u32 s3, 0
	s_cselect_b64 s[42:43], -1, 0
	s_or_b64 s[74:75], s[44:45], s[42:43]
	s_and_b64 vcc, exec, s[74:75]
	s_cbranch_vccnz .LBB0_1136
	s_mul_i32 s27, s25, 0x680
	v_add_u32_e32 v80, s27, v64
	v_ashrrev_i32_e32 v81, 31, v80
	v_lshl_add_u64 v[80:81], v[80:81], 2, s[46:47]
	global_load_dword v77, v[80:81], off
	v_add_u32_e32 v80, s27, v104
	v_add_u32_e32 v154, s27, v66
	v_ashrrev_i32_e32 v81, 31, v80
	v_ashrrev_i32_e32 v155, 31, v154
	v_lshl_add_u64 v[80:81], v[80:81], 2, s[46:47]
	v_lshl_add_u64 v[154:155], v[154:155], 2, s[46:47]
	global_load_dword v80, v[80:81], off
	s_nop 0
	global_load_dword v81, v[154:155], off
	s_waitcnt vmcnt(0)
	s_branch .LBB0_1137

; __device__ __forceinline__ void even_prep(const Params& p, int j, LAS unsigned char* lds, const int wave_s) {
;     ...
;                     const float sr = cr + (qr - cr) * mu_r, sk = ck + (qk - ck) * mu_k, sv = cv + (qv - cv) * mu_v;
;                     const float wp = w0 + DW[(hh * 8 + i) * 64 + lane], ap = a0 + DA[(hh * 8 + i) * 64 + lane];
;                     const float xs = -wp;
;                     const float sp = xs > 20.f ? xs : __logf(1.f + __expf(xs));
;                     const float decay = __expf(-__expf(-sp - 0.5f));
;                     const float a = 1.f / (1.f + __expf(-ap));
;                     const float kk = sk * k_k;
;                     const float ss = wave_sum(kk * kk);
;                     const float kkn = kk * rsqrtf(fmaxf(ss, 1e-24f));
;                     const float kmod = sk * (1.f + (a - 1.f) * k_a);
;                     const float bon = wave_sum(sr * kmod * r_k);
;                     const size_t o = (size_t)n * 512 + tid;
;                     SR[o] = sr; SW[o] = decay; SK[o] = kmod; SV[o] = sv; SKK[o] = kkn; SBB[o] = kkn * a;
;                     if (lane == 0) BON[(size_t)n * 8 + wave] = bon;
.LBB0_1137:
	ds_read2st64_b32 v[154:155], v86 offset0:65 offset1:81
	s_mov_b32 s27, 0x3f317217
	v_sub_f32_e32 v81, v81, v152
	v_sub_f32_e32 v80, v80, v151
	v_fma_f32 v80, v95, v80, v151
	s_waitcnt lgkmcnt(0)
	v_add_f32_e32 v153, v98, v154
	v_mul_f32_e32 v154, 0xbfb8aa3b, v153
	v_exp_f32_e32 v154, v154
	v_add_f32_e32 v155, v99, v155
	v_mov_b32_e32 v161, 0
	v_sub_f32_e32 v77, v77, v79
	v_add_f32_e32 v154, 1.0, v154
	v_cmp_gt_f32_e32 vcc, s15, v154
	v_fma_f32 v77, v94, v77, v79
	s_ashr_i32 s73, s72, 31
	v_cndmask_b32_e64 v156, 0, 32, vcc
	v_ldexp_f32 v154, v154, v156
	v_log_f32_e32 v154, v154
	v_cndmask_b32_e32 v156, 0, v222, vcc
	v_mul_f32_e32 v158, 0x3f317217, v154
	v_fma_f32 v158, v154, s27, -v158
	v_fmac_f32_e32 v158, 0x3377d1cf, v154
	s_mov_b32 s27, 0x7f800000
	v_fmac_f32_e32 v158, 0x3f317217, v154
	v_cmp_lt_f32_e64 vcc, |v154|, s27
	s_mov_b32 s27, 0xc1a00000
	s_nop 0
	v_cndmask_b32_e32 v154, v154, v158, vcc
	v_sub_f32_e32 v154, v154, v156
	v_cmp_gt_f32_e32 vcc, s27, v153
	v_fma_f32 v158, v96, v81, v152
	s_nop 0
	v_cndmask_b32_e64 v153, v154, -v153, vcc
	v_mul_f32_e32 v154, 0xbfb8aa3b, v155
	v_exp_f32_e32 v154, v154
	v_sub_f32_e32 v153, -0.5, v153
	v_mul_f32_e32 v153, 0x3fb8aa3b, v153
	v_exp_f32_e32 v153, v153
	v_add_f32_e32 v154, 1.0, v154
	v_div_scale_f32 v155, s[76:77], v154, v154, 1.0
	v_rcp_f32_e32 v156, v155
	v_mul_f32_e32 v81, 0xbfb8aa3b, v153
	v_exp_f32_e32 v153, v81
	s_lshl_b64 s[76:77], s[72:73], 9
	v_fma_f32 v81, -v155, v156, 1.0
	v_fmac_f32_e32 v156, v81, v156
	v_div_scale_f32 v81, vcc, 1.0, v154, 1.0
	v_mul_f32_e32 v159, v81, v156
	v_fma_f32 v160, -v155, v159, v81
	v_fmac_f32_e32 v159, v160, v156
	v_fma_f32 v81, -v155, v159, v81
	v_mul_f32_e32 v155, v100, v80
	v_mul_f32_e32 v160, v155, v155
	v_div_fmas_f32 v81, v81, v156, v159
	v_div_fixup_f32 v156, v81, v154, 1.0
	v_mov_b32_dpp v160, v160 row_shr:1 row_mask:0xf bank_mask:0xf bound_ctrl:1
	v_fmac_f32_e32 v160, v155, v155
	v_add_f32_e32 v81, -1.0, v156
	v_fma_f32 v81, v101, v81, 1.0
	v_add_f32_dpp v160, v160, v160 row_shr:2 row_mask:0xf bank_mask:0xf bound_ctrl:1
	s_nop 1
	v_add_f32_dpp v160, v160, v160 row_shr:4 row_mask:0xf bank_mask:0xf bound_ctrl:1
	s_nop 1
	v_add_f32_dpp v160, v160, v160 row_shr:8 row_mask:0xf bank_mask:0xf bound_ctrl:1
	s_nop 1
	v_mov_b32_dpp v161, v160 row_bcast:15 row_mask:0xa bank_mask:0xf
	v_add_f32_e32 v160, v160, v161
	v_mov_b32_e32 v161, 0
	s_nop 1
	v_mov_b32_dpp v161, v160 row_bcast:31 row_mask:0xc bank_mask:0xf
	v_add_f32_e32 v160, v160, v161
	s_nop 0
	v_readlane_b32 s27, v160, 63
	s_nop 1
	v_max_f32_e64 v160, s27, s27
	v_max_f32_e32 v160, 0x179abe15, v160
	v_rsq_f32_e32 v160, v160
	s_nop 0
	v_mul_f32_e32 v159, v155, v160
	v_mul_f32_e32 v160, v80, v81
	v_mul_f32_e32 v80, v77, v160
	v_mul_f32_e32 v81, v102, v80
	s_nop 1
	v_mov_b32_dpp v81, v81 row_shr:1 row_mask:0xf bank_mask:0xf bound_ctrl:1
	v_fmac_f32_e32 v81, v102, v80
	s_nop 1
	v_add_f32_dpp v80, v81, v81 row_shr:2 row_mask:0xf bank_mask:0xf bound_ctrl:1
	v_mov_b32_e32 v81, 0
	s_nop 0
	v_add_f32_dpp v80, v80, v80 row_shr:4 row_mask:0xf bank_mask:0xf bound_ctrl:1
	s_nop 1
	v_add_f32_dpp v80, v80, v80 row_shr:8 row_mask:0xf bank_mask:0xf bound_ctrl:1
	s_nop 1
	v_mov_b32_dpp v81, v80 row_bcast:15 row_mask:0xa bank_mask:0xf
	v_add_f32_e32 v80, v80, v81
	v_mov_b32_e32 v81, 0
	s_nop 1
	v_mov_b32_dpp v81, v80 row_bcast:31 row_mask:0xc bank_mask:0xf
	v_add_f32_e32 v80, v80, v81
	s_nop 0
	v_readlane_b32 s27, v80, 63
	v_lshl_add_u64 v[80:81], s[76:77], 0, v[64:65]
	v_lshlrev_b64 v[80:81], 2, v[80:81]
	v_lshl_add_u64 v[154:155], s[58:59], 0, v[80:81]
	global_store_dword v[154:155], v77, off
	v_lshl_add_u64 v[154:155], s[50:51], 0, v[80:81]
	global_store_dword v[154:155], v153, off
	v_lshl_add_u64 v[154:155], s[56:57], 0, v[80:81]
	global_store_dword v[154:155], v160, off
	v_lshl_add_u64 v[154:155], s[52:53], 0, v[80:81]
	global_store_dword v[154:155], v158, off
	v_lshl_add_u64 v[154:155], s[38:39], 0, v[80:81]
	v_mul_f32_e32 v77, v156, v159
	v_lshl_add_u64 v[80:81], s[54:55], 0, v[80:81]
	global_store_dword v[154:155], v159, off
	global_store_dword v[80:81], v77, off
	s_and_saveexec_b64 s[76:77], s[40:41]
	s_cbranch_execz .LBB0_1139
	s_lshl_b64 vcc, s[72:73], 5
	s_add_u32 vcc_lo, s17, vcc_lo
	s_addc_u32 vcc_hi, s83, vcc_hi
	v_mov_b32_e32 v77, s27
	global_store_dword v185, v77, vcc

; __device__ __forceinline__ void even_prep(const Params& p, int j, LAS unsigned char* lds, const int wave_s) {
;     ...
;                     if (t < 1) um1 = samp ? sconv[(b * 2 + 1) * 512 + tid] : 0.f;
;                     if (t < 2) um2 = samp ? sconv[(b * 2 + t) * 512 + tid] : 0.f;
.LBB0_1143:
	s_xor_b64 s[74:75], s[74:75], -1
	s_andn2_b64 vcc, exec, s[74:75]
	s_cbranch_vccnz .LBB0_1145
	v_lshl_add_u32 v80, s25, 10, v104
	v_ashrrev_i32_e32 v81, 31, v80
	v_lshl_add_u64 v[80:81], v[80:81], 2, s[48:49]
	global_load_dword v77, v[80:81], off
	s_waitcnt vmcnt(0)
	s_branch .LBB0_1146

; __device__ __forceinline__ void even_prep(const Params& p, int j, LAS unsigned char* lds, const int wave_s) {
;     ...
;                     if (t < 1) um1 = samp ? sconv[(b * 2 + 1) * 512 + tid] : 0.f;
;                     if (t < 2) um2 = samp ? sconv[(b * 2 + t) * 512 + tid] : 0.f;
.LBB0_1146:
	s_cmp_gt_u32 s3, 1
	s_cselect_b64 s[42:43], -1, 0
	s_or_b64 s[74:75], s[44:45], s[42:43]
	s_and_b64 vcc, exec, s[74:75]
	s_cbranch_vccnz .LBB0_1148
	v_lshl_add_u32 v80, s25, 10, v109
	v_ashrrev_i32_e32 v81, 31, v80
	v_lshl_add_u64 v[80:81], v[80:81], 2, s[48:49]
	global_load_dword v80, v[80:81], off
	s_waitcnt vmcnt(0)
	s_branch .LBB0_1149

; __device__ __forceinline__ unsigned f2bf(float f) { unsigned u = __float_as_uint(f); return (u + 0x7fffu + ((u >> 16) & 1u)) >> 16; }
; __device__ __forceinline__ float silu(float x) { return x / (1.f + __expf(-x)); }
; __device__ __forceinline__ void even_prep(const Params& p, int j, LAS unsigned char* lds, const int wave_s) {
;     ...
;             for (int i = 0; i < 8; ++i) { const int n = nh + i;
;                 if (n < n1) {
;                     int b, t, T; const bool samp = n >= NP;
;                     if (!samp) { b = n >> 11; t = n & 2047; T = SEQ; } else { const int s = n - NP; b = s >> 3; t = s & 7; T = ST; }
;                     const float cr = rr[i + 1], ck = kr[i + 1], cv = vr[i + 1];
;                     float qr = rr[i], qk = kr[i], qv = vr[i];
;                     if (t == 0) { qr = 0.f; qk = 0.f; qv = 0.f; if (samp) { qr = sshift[b * ASW + tid]; qk = sshift[b * ASW + 512 + tid]; qv = sshift[b * ASW + 1024 + tid]; } }
;     ...
;                     const float yc = cw0 * um2 + cw1 * um1 + cw2 * u0;
;                     MIX[(size_t)n * DM + 512 + tid] = (bf16_t)f2bf(bbv[i] * yc * silu(zbv[i]));
;                     if (t >= T - 2) { float* co = p.out + (samp ? O_CV_S + (size_t)((j * SB + b) * 2 + (t - (T - 2))) * 512 : O_CV_P + (size_t)((j * PB + b) * 2 + (t - (T - 2))) * 512); co[tid] = u0; }
.LBB0_1149:
	v_lshlrev_b32_e32 v81, 16, v82
	v_lshlrev_b32_e32 v153, 16, v83
	v_pk_mul_f32 v[82:83], v[68:69], v[76:77]
	s_add_i32 s25, s27, -2
	v_fma_f32 v77, v103, v80, v83
	v_mul_f32_e32 v80, 0xbfb8aa3b, v153
	v_exp_f32_e32 v80, v80
	v_add_f32_e32 v77, v82, v77
	v_mul_f32_e32 v77, v77, v81
	v_add_f32_e32 v80, 1.0, v80
	v_div_scale_f32 v81, s[42:43], v80, v80, v153
	v_rcp_f32_e32 v82, v81
	s_lshl_b64 s[42:43], s[72:73], 11
	s_cmp_lt_u32 s3, s25
	v_fma_f32 v83, -v81, v82, 1.0
	v_fmac_f32_e32 v82, v83, v82
	v_div_scale_f32 v83, vcc, v153, v80, v153
	v_mul_f32_e32 v154, v83, v82
	v_fma_f32 v155, -v81, v154, v83
	v_fmac_f32_e32 v154, v155, v82
	v_fma_f32 v81, -v81, v154, v83
	v_div_fmas_f32 v81, v81, v82, v154
	v_div_fixup_f32 v80, v81, v80, v153
	v_mul_f32_e32 v77, v80, v77
	v_bfe_u32 v80, v77, 16, 1
	v_add3_u32 v77, v77, v80, s6
	v_lshl_add_u64 v[80:81], v[72:73], 0, s[42:43]
	global_store_short_d16_hi v[80:81], v77, off
	s_cbranch_scc1 .LBB0_1151
	s_lshl_b32 s25, s31, 1
	s_and_b64 s[42:43], s[44:45], exec
	s_cselect_b32 s31, s34, s5
	s_mov_b32 s42, 0x4b82000
	s_cselect_b32 s96, s42, 0x4b92000
	s_sub_i32 s27, s31, s27
	s_add_i32 s3, s3, s27
	s_add_i32 s3, s3, s25
	s_add_i32 s42, s3, 2
	s_ashr_i32 s43, s42, 31
	s_lshl_b64 s[42:43], s[42:43], 11
	v_lshl_add_u64 v[80:81], v[74:75], 0, s[42:43]
	v_lshl_add_u64 v[80:81], v[80:81], 0, s[96:97]
	s_mov_b32 s96, 0x88888889
	global_store_dword v[80:81], v76, off
.LBB0_1151:
	v_lshlrev_b32_e32 v77, 16, v146
	v_lshlrev_b32_e32 v80, 16, v147
	v_mul_f32_e32 v80, v77, v80
	v_lshlrev_b32_e32 v77, 16, v149
	v_lshlrev_b32_e32 v146, 16, v150
	s_cmp_ge_i32 s70, s33
	v_lshlrev_b32_e32 v147, 16, v148
	s_cbranch_scc1 .LBB0_1169
	s_add_i32 s3, s2, 0xffffc002
	s_lshr_b32 s25, s3, 3
	s_and_b32 s3, s70, 0x7ff
	s_cmpk_lt_i32 s2, 0x3ffe
	s_cselect_b64 s[44:45], -1, 0
	s_and_b64 s[42:43], s[44:45], exec
	v_readlane_b32 s27, v254, 32
	s_cselect_b32 s3, s3, s27
	s_cmp_lg_u32 s3, 0
	s_cselect_b64 s[42:43], -1, 0
	s_or_b64 s[72:73], s[44:45], s[42:43]
	s_and_b64 vcc, exec, s[72:73]
	s_cbranch_vccnz .LBB0_1154
	s_mul_i32 s27, s25, 0x680
	v_add_u32_e32 v82, s27, v64
	v_ashrrev_i32_e32 v83, 31, v82
	v_lshl_add_u64 v[82:83], v[82:83], 2, s[46:47]
	global_load_dword v79, v[82:83], off
	v_add_u32_e32 v82, s27, v104
	v_ashrrev_i32_e32 v83, 31, v82
	v_lshl_add_u64 v[82:83], v[82:83], 2, s[46:47]
	global_load_dword v81, v[82:83], off
	v_add_u32_e32 v82, s27, v66
	v_ashrrev_i32_e32 v83, 31, v82
	v_lshl_add_u64 v[82:83], v[82:83], 2, s[46:47]
	global_load_dword v82, v[82:83], off
	s_waitcnt vmcnt(0)
	s_branch .LBB0_1155

; __device__ __forceinline__ void even_prep(const Params& p, int j, LAS unsigned char* lds, const int wave_s) {
;     ...
;                     const float sr = cr + (qr - cr) * mu_r, sk = ck + (qk - ck) * mu_k, sv = cv + (qv - cv) * mu_v;
;                     const float wp = w0 + DW[(hh * 8 + i) * 64 + lane], ap = a0 + DA[(hh * 8 + i) * 64 + lane];
;                     const float xs = -wp;
;                     const float sp = xs > 20.f ? xs : __logf(1.f + __expf(xs));
;                     const float decay = __expf(-__expf(-sp - 0.5f));
;                     const float a = 1.f / (1.f + __expf(-ap));
;                     const float kk = sk * k_k;
;                     const float ss = wave_sum(kk * kk);
;                     const float kkn = kk * rsqrtf(fmaxf(ss, 1e-24f));
;                     const float kmod = sk * (1.f + (a - 1.f) * k_a);
;                     const float bon = wave_sum(sr * kmod * r_k);
;                     const size_t o = (size_t)n * 512 + tid;
;                     SR[o] = sr; SW[o] = decay; SK[o] = kmod; SV[o] = sv; SKK[o] = kkn; SBB[o] = kkn * a;
;                     if (lane == 0) BON[(size_t)n * 8 + wave] = bon;
.LBB0_1155:
	ds_read2st64_b32 v[148:149], v86 offset0:66 offset1:82
	s_mov_b32 s27, 0x3f317217
	v_sub_f32_e32 v82, v82, v147
	v_sub_f32_e32 v81, v81, v146
	v_fma_f32 v81, v95, v81, v146
	s_waitcnt lgkmcnt(0)
	v_add_f32_e32 v83, v98, v148
	v_mul_f32_e32 v148, 0xbfb8aa3b, v83
	v_exp_f32_e32 v148, v148
	v_add_f32_e32 v149, v99, v149
	v_sub_f32_e32 v79, v79, v77
	v_fma_f32 v79, v94, v79, v77
	v_add_f32_e32 v148, 1.0, v148
	v_cmp_gt_f32_e32 vcc, s15, v148
	v_mov_b32_e32 v154, 0
	s_ashr_i32 s71, s70, 31
	v_cndmask_b32_e64 v150, 0, 32, vcc
	v_ldexp_f32 v148, v148, v150
	v_log_f32_e32 v148, v148
	v_cndmask_b32_e32 v150, 0, v222, vcc
	v_mul_f32_e32 v151, 0x3f317217, v148
	v_fma_f32 v151, v148, s27, -v151
	v_fmac_f32_e32 v151, 0x3377d1cf, v148
	s_mov_b32 s27, 0x7f800000
	v_fmac_f32_e32 v151, 0x3f317217, v148
	v_cmp_lt_f32_e64 vcc, |v148|, s27
	s_mov_b32 s27, 0xc1a00000
	s_nop 0
	v_cndmask_b32_e32 v148, v148, v151, vcc
	v_sub_f32_e32 v148, v148, v150
	v_cmp_gt_f32_e32 vcc, s27, v83
	v_fma_f32 v151, v96, v82, v147
	s_nop 0
	v_cndmask_b32_e64 v83, v148, -v83, vcc
	v_mul_f32_e32 v148, 0xbfb8aa3b, v149
	v_exp_f32_e32 v148, v148
	v_sub_f32_e32 v83, -0.5, v83
	v_mul_f32_e32 v83, 0x3fb8aa3b, v83
	v_exp_f32_e32 v83, v83
	v_add_f32_e32 v148, 1.0, v148
	v_div_scale_f32 v149, s[74:75], v148, v148, 1.0
	v_rcp_f32_e32 v150, v149
	v_mul_f32_e32 v82, 0xbfb8aa3b, v83
	v_exp_f32_e32 v152, v82
	s_lshl_b64 s[74:75], s[70:71], 9
	v_fma_f32 v82, -v149, v150, 1.0
	v_fmac_f32_e32 v150, v82, v150
	v_div_scale_f32 v82, vcc, 1.0, v148, 1.0
	v_mul_f32_e32 v83, v82, v150
	v_fma_f32 v153, -v149, v83, v82
	v_fmac_f32_e32 v83, v153, v150
	v_fma_f32 v82, -v149, v83, v82
	v_mul_f32_e32 v149, v100, v81
	v_div_fmas_f32 v82, v82, v150, v83
	v_mul_f32_e32 v153, v149, v149
	v_div_fixup_f32 v150, v82, v148, 1.0
	v_add_f32_e32 v82, -1.0, v150
	v_mov_b32_dpp v153, v153 row_shr:1 row_mask:0xf bank_mask:0xf bound_ctrl:1
	v_fmac_f32_e32 v153, v149, v149
	v_fma_f32 v82, v101, v82, 1.0
	v_mul_f32_e32 v81, v81, v82
	v_add_f32_dpp v153, v153, v153 row_shr:2 row_mask:0xf bank_mask:0xf bound_ctrl:1
	v_mul_f32_e32 v82, v79, v81
	v_mul_f32_e32 v83, v102, v82
	v_add_f32_dpp v153, v153, v153 row_shr:4 row_mask:0xf bank_mask:0xf bound_ctrl:1
	s_nop 0
	v_mov_b32_dpp v83, v83 row_shr:1 row_mask:0xf bank_mask:0xf bound_ctrl:1
	v_add_f32_dpp v153, v153, v153 row_shr:8 row_mask:0xf bank_mask:0xf bound_ctrl:1
	v_fmac_f32_e32 v83, v102, v82
	s_nop 0
	v_mov_b32_dpp v154, v153 row_bcast:15 row_mask:0xa bank_mask:0xf
	v_add_f32_e32 v153, v153, v154
	v_mov_b32_e32 v154, 0
	v_add_f32_dpp v82, v83, v83 row_shr:2 row_mask:0xf bank_mask:0xf bound_ctrl:1
	v_mov_b32_e32 v83, 0
	v_mov_b32_dpp v154, v153 row_bcast:31 row_mask:0xc bank_mask:0xf
	v_add_f32_e32 v153, v153, v154
	v_add_f32_dpp v82, v82, v82 row_shr:4 row_mask:0xf bank_mask:0xf bound_ctrl:1
	v_readlane_b32 s27, v153, 63
	s_nop 0
	v_add_f32_dpp v82, v82, v82 row_shr:8 row_mask:0xf bank_mask:0xf bound_ctrl:1
	v_max_f32_e64 v153, s27, s27
	v_max_f32_e32 v153, 0x179abe15, v153
	v_mov_b32_dpp v83, v82 row_bcast:15 row_mask:0xa bank_mask:0xf
	v_add_f32_e32 v82, v82, v83
	v_mov_b32_e32 v83, 0
	v_rsq_f32_e32 v153, v153
	s_nop 0
	v_mov_b32_dpp v83, v82 row_bcast:31 row_mask:0xc bank_mask:0xf
	v_add_f32_e32 v82, v82, v83
	v_mul_f32_e32 v153, v149, v153
	v_readlane_b32 s27, v82, 63
	v_lshl_add_u64 v[82:83], s[74:75], 0, v[64:65]
	v_lshlrev_b64 v[82:83], 2, v[82:83]
	v_lshl_add_u64 v[148:149], s[58:59], 0, v[82:83]
	global_store_dword v[148:149], v79, off
	v_lshl_add_u64 v[148:149], s[50:51], 0, v[82:83]
	global_store_dword v[148:149], v152, off
	v_lshl_add_u64 v[148:149], s[56:57], 0, v[82:83]
	global_store_dword v[148:149], v81, off
	v_lshl_add_u64 v[148:149], s[52:53], 0, v[82:83]
	global_store_dword v[148:149], v151, off
	v_lshl_add_u64 v[148:149], s[38:39], 0, v[82:83]
	v_mul_f32_e32 v79, v150, v153
	v_lshl_add_u64 v[82:83], s[54:55], 0, v[82:83]
	global_store_dword v[148:149], v153, off
	global_store_dword v[82:83], v79, off
	s_and_saveexec_b64 s[74:75], s[40:41]
	s_cbranch_execz .LBB0_1157
	s_lshl_b64 s[76:77], s[70:71], 5
	s_add_u32 s76, s17, s76
	s_addc_u32 s77, s83, s77
	v_mov_b32_e32 v79, s27
	global_store_dword v185, v79, s[76:77]

; __device__ __forceinline__ void even_prep(const Params& p, int j, LAS unsigned char* lds, const int wave_s) {
;     ...
;                     if (t < 1) um1 = samp ? sconv[(b * 2 + 1) * 512 + tid] : 0.f;
;                     if (t < 2) um2 = samp ? sconv[(b * 2 + t) * 512 + tid] : 0.f;
.LBB0_1161:
	s_xor_b64 s[72:73], s[72:73], -1
	s_andn2_b64 vcc, exec, s[72:73]
	s_cbranch_vccnz .LBB0_1163
	v_lshl_add_u32 v82, s25, 10, v104
	v_ashrrev_i32_e32 v83, 31, v82
	v_lshl_add_u64 v[82:83], v[82:83], 2, s[48:49]
	global_load_dword v81, v[82:83], off
	s_waitcnt vmcnt(0)
	s_branch .LBB0_1164

; __device__ __forceinline__ void even_prep(const Params& p, int j, LAS unsigned char* lds, const int wave_s) {
;     ...
;                     if (t < 1) um1 = samp ? sconv[(b * 2 + 1) * 512 + tid] : 0.f;
;                     if (t < 2) um2 = samp ? sconv[(b * 2 + t) * 512 + tid] : 0.f;
.LBB0_1164:
	s_cmp_gt_u32 s3, 1
	s_cselect_b64 s[42:43], -1, 0
	s_or_b64 s[72:73], s[44:45], s[42:43]
	s_and_b64 vcc, exec, s[72:73]
	s_cbranch_vccnz .LBB0_1166
	v_lshl_add_u32 v78, s25, 10, v110
	v_ashrrev_i32_e32 v79, 31, v78
	v_lshl_add_u64 v[78:79], v[78:79], 2, s[48:49]
	global_load_dword v78, v[78:79], off
	s_waitcnt vmcnt(0)
	s_branch .LBB0_1167

; __device__ __forceinline__ unsigned f2bf(float f) { unsigned u = __float_as_uint(f); return (u + 0x7fffu + ((u >> 16) & 1u)) >> 16; }
; __device__ __forceinline__ float silu(float x) { return x / (1.f + __expf(-x)); }
; __device__ __forceinline__ void even_prep(const Params& p, int j, LAS unsigned char* lds, const int wave_s) {
;     ...
;             for (int i = 0; i < 8; ++i) { const int n = nh + i;
;                 if (n < n1) {
;                     int b, t, T; const bool samp = n >= NP;
;                     if (!samp) { b = n >> 11; t = n & 2047; T = SEQ; } else { const int s = n - NP; b = s >> 3; t = s & 7; T = ST; }
;                     const float cr = rr[i + 1], ck = kr[i + 1], cv = vr[i + 1];
;                     float qr = rr[i], qk = kr[i], qv = vr[i];
;                     if (t == 0) { qr = 0.f; qk = 0.f; qv = 0.f; if (samp) { qr = sshift[b * ASW + tid]; qk = sshift[b * ASW + 512 + tid]; qv = sshift[b * ASW + 1024 + tid]; } }
;     ...
;                     const float yc = cw0 * um2 + cw1 * um1 + cw2 * u0;
;                     MIX[(size_t)n * DM + 512 + tid] = (bf16_t)f2bf(bbv[i] * yc * silu(zbv[i]));
;                     if (t >= T - 2) { float* co = p.out + (samp ? O_CV_S + (size_t)((j * SB + b) * 2 + (t - (T - 2))) * 512 : O_CV_P + (size_t)((j * PB + b) * 2 + (t - (T - 2))) * 512); co[tid] = u0; }
.LBB0_1167:
	v_pk_mul_f32 v[82:83], v[68:69], v[80:81]
	v_lshlrev_b32_e32 v79, 16, v145
	v_fma_f32 v78, v103, v78, v83
	v_lshlrev_b32_e32 v144, 16, v144
	v_add_f32_e32 v78, v82, v78
	v_mul_f32_e32 v78, v78, v79
	v_mul_f32_e32 v79, 0xbfb8aa3b, v144
	v_exp_f32_e32 v79, v79
	s_add_i32 s25, s27, -2
	v_add_f32_e32 v79, 1.0, v79
	v_div_scale_f32 v81, s[42:43], v79, v79, v144
	v_rcp_f32_e32 v82, v81
	s_lshl_b64 s[42:43], s[70:71], 11
	s_cmp_lt_u32 s3, s25
	v_fma_f32 v83, -v81, v82, 1.0
	v_fmac_f32_e32 v82, v83, v82
	v_div_scale_f32 v83, vcc, v144, v79, v144
	v_mul_f32_e32 v145, v83, v82
	v_fma_f32 v148, -v81, v145, v83
	v_fmac_f32_e32 v145, v148, v82
	v_fma_f32 v81, -v81, v145, v83
	v_div_fmas_f32 v81, v81, v82, v145
	v_div_fixup_f32 v79, v81, v79, v144
	v_mul_f32_e32 v78, v79, v78
	v_bfe_u32 v79, v78, 16, 1
	v_add3_u32 v81, v78, v79, s6
	v_lshl_add_u64 v[78:79], v[72:73], 0, s[42:43]
	global_store_short_d16_hi v[78:79], v81, off
	s_cbranch_scc1 .LBB0_1169
	s_lshl_b32 s25, s31, 1
	s_and_b64 s[42:43], s[44:45], exec
	s_cselect_b32 s31, s34, s5
	s_mov_b32 s42, 0x4b82000
	s_cselect_b32 s96, s42, 0x4b92000
	s_sub_i32 s27, s31, s27
	s_add_i32 s3, s3, s27
	s_add_i32 s3, s3, s25
	s_add_i32 s42, s3, 2
	s_ashr_i32 s43, s42, 31
	s_lshl_b64 s[42:43], s[42:43], 11
	v_lshl_add_u64 v[78:79], v[74:75], 0, s[42:43]
	v_lshl_add_u64 v[78:79], v[78:79], 0, s[96:97]
	s_mov_b32 s96, 0x88888889
	global_store_dword v[78:79], v80, off
.LBB0_1169:
	v_lshlrev_b32_e32 v78, 16, v139
	v_lshlrev_b32_e32 v79, 16, v140
	v_mul_f32_e32 v78, v78, v79
	v_lshlrev_b32_e32 v139, 16, v142
	v_lshlrev_b32_e32 v140, 16, v143
	s_cmp_ge_i32 s68, s33
	v_lshlrev_b32_e32 v141, 16, v141
	s_cbranch_scc1 .LBB0_1187
	s_add_i32 s3, s2, 0xffffc003
	s_lshr_b32 s25, s3, 3
	s_and_b32 s3, s68, 0x7ff
	s_cmpk_lt_i32 s2, 0x3ffd
	s_cselect_b64 s[44:45], -1, 0
	s_and_b64 s[42:43], s[44:45], exec
	v_readlane_b32 s27, v254, 34
	s_cselect_b32 s3, s3, s27
	s_cmp_lg_u32 s3, 0
	s_cselect_b64 s[42:43], -1, 0
	s_or_b64 s[70:71], s[44:45], s[42:43]
	s_and_b64 vcc, exec, s[70:71]
	s_cbranch_vccnz .LBB0_1172
	s_mul_i32 s27, s25, 0x680
	v_add_u32_e32 v82, s27, v64
	v_ashrrev_i32_e32 v83, 31, v82
	v_lshl_add_u64 v[82:83], v[82:83], 2, s[46:47]
	global_load_dword v77, v[82:83], off
	v_add_u32_e32 v82, s27, v104
	v_ashrrev_i32_e32 v83, 31, v82
	v_lshl_add_u64 v[82:83], v[82:83], 2, s[46:47]
	global_load_dword v79, v[82:83], off
	v_add_u32_e32 v82, s27, v66
	v_ashrrev_i32_e32 v83, 31, v82
	v_lshl_add_u64 v[82:83], v[82:83], 2, s[46:47]
	global_load_dword v81, v[82:83], off
	s_waitcnt vmcnt(0)
	s_branch .LBB0_1173

; __device__ __forceinline__ void even_prep(const Params& p, int j, LAS unsigned char* lds, const int wave_s) {
;     ...
;                     const float sr = cr + (qr - cr) * mu_r, sk = ck + (qk - ck) * mu_k, sv = cv + (qv - cv) * mu_v;
;                     const float wp = w0 + DW[(hh * 8 + i) * 64 + lane], ap = a0 + DA[(hh * 8 + i) * 64 + lane];
;                     const float xs = -wp;
;                     const float sp = xs > 20.f ? xs : __logf(1.f + __expf(xs));
;                     const float decay = __expf(-__expf(-sp - 0.5f));
;                     const float a = 1.f / (1.f + __expf(-ap));
;                     const float kk = sk * k_k;
;                     const float ss = wave_sum(kk * kk);
;                     const float kkn = kk * rsqrtf(fmaxf(ss, 1e-24f));
;                     const float kmod = sk * (1.f + (a - 1.f) * k_a);
;                     const float bon = wave_sum(sr * kmod * r_k);
;                     const size_t o = (size_t)n * 512 + tid;
;                     SR[o] = sr; SW[o] = decay; SK[o] = kmod; SV[o] = sv; SKK[o] = kkn; SBB[o] = kkn * a;
;                     if (lane == 0) BON[(size_t)n * 8 + wave] = bon;
.LBB0_1173:
	ds_read2st64_b32 v[82:83], v86 offset0:67 offset1:83
	s_mov_b32 s27, 0x3f317217
	v_sub_f32_e32 v79, v79, v140
	v_fma_f32 v79, v95, v79, v140
	v_sub_f32_e32 v77, v77, v139
	s_waitcnt lgkmcnt(0)
	v_add_f32_e32 v82, v98, v82
	v_mul_f32_e32 v142, 0xbfb8aa3b, v82
	v_exp_f32_e32 v142, v142
	v_add_f32_e32 v83, v99, v83
	v_mul_f32_e32 v83, 0xbfb8aa3b, v83
	v_exp_f32_e32 v83, v83
	v_add_f32_e32 v142, 1.0, v142
	v_cmp_gt_f32_e32 vcc, s15, v142
	v_fma_f32 v77, v94, v77, v139
	v_add_f32_e32 v83, 1.0, v83
	v_cndmask_b32_e64 v143, 0, 32, vcc
	v_ldexp_f32 v142, v142, v143
	v_log_f32_e32 v142, v142
	v_cndmask_b32_e32 v143, 0, v222, vcc
	v_mov_b32_e32 v147, 0
	s_ashr_i32 s69, s68, 31
	v_mul_f32_e32 v144, 0x3f317217, v142
	v_fma_f32 v144, v142, s27, -v144
	v_fmac_f32_e32 v144, 0x3377d1cf, v142
	s_mov_b32 s27, 0x7f800000
	v_fmac_f32_e32 v144, 0x3f317217, v142
	v_cmp_lt_f32_e64 vcc, |v142|, s27
	s_mov_b32 s27, 0xc1a00000
	v_sub_f32_e32 v81, v81, v141
	v_cndmask_b32_e32 v142, v142, v144, vcc
	v_sub_f32_e32 v142, v142, v143
	v_cmp_gt_f32_e32 vcc, s27, v82
	v_fma_f32 v81, v96, v81, v141
	s_nop 0
	v_cndmask_b32_e64 v82, v142, -v82, vcc
	v_sub_f32_e32 v82, -0.5, v82
	v_mul_f32_e32 v82, 0x3fb8aa3b, v82
	v_exp_f32_e32 v82, v82
	v_div_scale_f32 v142, s[72:73], v83, v83, 1.0
	v_rcp_f32_e32 v143, v142
	v_mul_f32_e32 v82, 0xbfb8aa3b, v82
	v_exp_f32_e32 v144, v82
	s_lshl_b64 s[72:73], s[68:69], 9
	v_fma_f32 v82, -v142, v143, 1.0
	v_fmac_f32_e32 v143, v82, v143
	v_div_scale_f32 v82, vcc, 1.0, v83, 1.0
	v_mul_f32_e32 v145, v82, v143
	v_fma_f32 v146, -v142, v145, v82
	v_fmac_f32_e32 v145, v146, v143
	v_fma_f32 v82, -v142, v145, v82
	v_mul_f32_e32 v142, v100, v79
	v_div_fmas_f32 v82, v82, v143, v145
	v_mul_f32_e32 v146, v142, v142
	v_div_fixup_f32 v145, v82, v83, 1.0
	v_add_f32_e32 v82, -1.0, v145
	v_mov_b32_dpp v146, v146 row_shr:1 row_mask:0xf bank_mask:0xf bound_ctrl:1
	v_fmac_f32_e32 v146, v142, v142
	v_fma_f32 v82, v101, v82, 1.0
	v_mul_f32_e32 v79, v79, v82
	v_add_f32_dpp v146, v146, v146 row_shr:2 row_mask:0xf bank_mask:0xf bound_ctrl:1
	v_mul_f32_e32 v82, v77, v79
	v_mul_f32_e32 v83, v102, v82
	v_add_f32_dpp v146, v146, v146 row_shr:4 row_mask:0xf bank_mask:0xf bound_ctrl:1
	s_nop 0
	v_mov_b32_dpp v83, v83 row_shr:1 row_mask:0xf bank_mask:0xf bound_ctrl:1
	v_add_f32_dpp v146, v146, v146 row_shr:8 row_mask:0xf bank_mask:0xf bound_ctrl:1
	v_fmac_f32_e32 v83, v102, v82
	s_nop 0
	v_mov_b32_dpp v147, v146 row_bcast:15 row_mask:0xa bank_mask:0xf
	v_add_f32_e32 v146, v146, v147
	v_mov_b32_e32 v147, 0
	v_add_f32_dpp v82, v83, v83 row_shr:2 row_mask:0xf bank_mask:0xf bound_ctrl:1
	v_mov_b32_e32 v83, 0
	v_mov_b32_dpp v147, v146 row_bcast:31 row_mask:0xc bank_mask:0xf
	v_add_f32_e32 v146, v146, v147
	v_add_f32_dpp v82, v82, v82 row_shr:4 row_mask:0xf bank_mask:0xf bound_ctrl:1
	v_readlane_b32 s27, v146, 63
	s_nop 0
	v_add_f32_dpp v82, v82, v82 row_shr:8 row_mask:0xf bank_mask:0xf bound_ctrl:1
	v_max_f32_e64 v146, s27, s27
	v_max_f32_e32 v146, 0x179abe15, v146
	v_mov_b32_dpp v83, v82 row_bcast:15 row_mask:0xa bank_mask:0xf
	v_add_f32_e32 v82, v82, v83
	v_mov_b32_e32 v83, 0
	v_rsq_f32_e32 v146, v146
	s_nop 0
	v_mov_b32_dpp v83, v82 row_bcast:31 row_mask:0xc bank_mask:0xf
	v_add_f32_e32 v82, v82, v83
	v_mul_f32_e32 v146, v142, v146
	v_readlane_b32 s27, v82, 63
	v_lshl_add_u64 v[82:83], s[72:73], 0, v[64:65]
	v_lshlrev_b64 v[82:83], 2, v[82:83]
	v_lshl_add_u64 v[142:143], s[58:59], 0, v[82:83]
	global_store_dword v[142:143], v77, off
	v_lshl_add_u64 v[142:143], s[50:51], 0, v[82:83]
	global_store_dword v[142:143], v144, off
	v_lshl_add_u64 v[142:143], s[56:57], 0, v[82:83]
	global_store_dword v[142:143], v79, off
	v_lshl_add_u64 v[142:143], s[52:53], 0, v[82:83]
	global_store_dword v[142:143], v81, off
	v_lshl_add_u64 v[142:143], s[38:39], 0, v[82:83]
	v_mul_f32_e32 v77, v145, v146
	v_lshl_add_u64 v[82:83], s[54:55], 0, v[82:83]
	global_store_dword v[142:143], v146, off
	global_store_dword v[82:83], v77, off
	s_and_saveexec_b64 s[72:73], s[40:41]
	s_cbranch_execz .LBB0_1175
	s_lshl_b64 s[74:75], s[68:69], 5
	s_add_u32 s74, s17, s74
	s_addc_u32 s75, s83, s75
	v_mov_b32_e32 v77, s27
	global_store_dword v185, v77, s[74:75]

; __device__ __forceinline__ void even_prep(const Params& p, int j, LAS unsigned char* lds, const int wave_s) {
;     ...
;                     if (t < 1) um1 = samp ? sconv[(b * 2 + 1) * 512 + tid] : 0.f;
;                     if (t < 2) um2 = samp ? sconv[(b * 2 + t) * 512 + tid] : 0.f;
.LBB0_1179:
	s_xor_b64 s[70:71], s[70:71], -1
	s_andn2_b64 vcc, exec, s[70:71]
	s_cbranch_vccnz .LBB0_1181
	v_lshl_add_u32 v82, s25, 10, v104
	v_ashrrev_i32_e32 v83, 31, v82
	v_lshl_add_u64 v[82:83], v[82:83], 2, s[48:49]
	global_load_dword v79, v[82:83], off
	s_waitcnt vmcnt(0)
	s_branch .LBB0_1182

; __device__ __forceinline__ void even_prep(const Params& p, int j, LAS unsigned char* lds, const int wave_s) {
;     ...
;                     if (t < 1) um1 = samp ? sconv[(b * 2 + 1) * 512 + tid] : 0.f;
;                     if (t < 2) um2 = samp ? sconv[(b * 2 + t) * 512 + tid] : 0.f;
.LBB0_1182:
	s_cmp_gt_u32 s3, 1
	s_cselect_b64 s[42:43], -1, 0
	s_or_b64 s[70:71], s[44:45], s[42:43]
	s_and_b64 vcc, exec, s[70:71]
	s_cbranch_vccnz .LBB0_1184
	v_lshl_add_u32 v76, s25, 10, v111
	v_ashrrev_i32_e32 v77, 31, v76
	v_lshl_add_u64 v[76:77], v[76:77], 2, s[48:49]
	global_load_dword v76, v[76:77], off
	s_waitcnt vmcnt(0)
	s_branch .LBB0_1185

; __device__ __forceinline__ unsigned f2bf(float f) { unsigned u = __float_as_uint(f); return (u + 0x7fffu + ((u >> 16) & 1u)) >> 16; }
; __device__ __forceinline__ float silu(float x) { return x / (1.f + __expf(-x)); }
; __device__ __forceinline__ void even_prep(const Params& p, int j, LAS unsigned char* lds, const int wave_s) {
;     ...
;             for (int i = 0; i < 8; ++i) { const int n = nh + i;
;                 if (n < n1) {
;                     int b, t, T; const bool samp = n >= NP;
;                     if (!samp) { b = n >> 11; t = n & 2047; T = SEQ; } else { const int s = n - NP; b = s >> 3; t = s & 7; T = ST; }
;                     const float cr = rr[i + 1], ck = kr[i + 1], cv = vr[i + 1];
;                     float qr = rr[i], qk = kr[i], qv = vr[i];
;                     if (t == 0) { qr = 0.f; qk = 0.f; qv = 0.f; if (samp) { qr = sshift[b * ASW + tid]; qk = sshift[b * ASW + 512 + tid]; qv = sshift[b * ASW + 1024 + tid]; } }
;     ...
;                     const float yc = cw0 * um2 + cw1 * um1 + cw2 * u0;
;                     MIX[(size_t)n * DM + 512 + tid] = (bf16_t)f2bf(bbv[i] * yc * silu(zbv[i]));
;                     if (t >= T - 2) { float* co = p.out + (samp ? O_CV_S + (size_t)((j * SB + b) * 2 + (t - (T - 2))) * 512 : O_CV_P + (size_t)((j * PB + b) * 2 + (t - (T - 2))) * 512); co[tid] = u0; }
.LBB0_1185:
	v_pk_mul_f32 v[82:83], v[68:69], v[78:79]
	v_lshlrev_b32_e32 v77, 16, v138
	v_fma_f32 v76, v103, v76, v83
	v_lshlrev_b32_e32 v81, 16, v137
	v_add_f32_e32 v76, v82, v76
	v_mul_f32_e32 v76, v76, v77
	v_mul_f32_e32 v77, 0xbfb8aa3b, v81
	v_exp_f32_e32 v77, v77
	s_add_i32 s25, s27, -2
	v_add_f32_e32 v77, 1.0, v77
	v_div_scale_f32 v79, s[42:43], v77, v77, v81
	v_rcp_f32_e32 v82, v79
	s_lshl_b64 s[42:43], s[68:69], 11
	s_cmp_lt_u32 s3, s25
	v_fma_f32 v83, -v79, v82, 1.0
	v_fmac_f32_e32 v82, v83, v82
	v_div_scale_f32 v83, vcc, v81, v77, v81
	v_mul_f32_e32 v137, v83, v82
	v_fma_f32 v138, -v79, v137, v83
	v_fmac_f32_e32 v137, v138, v82
	v_fma_f32 v79, -v79, v137, v83
	v_div_fmas_f32 v79, v79, v82, v137
	v_div_fixup_f32 v77, v79, v77, v81
	v_mul_f32_e32 v76, v77, v76
	v_bfe_u32 v77, v76, 16, 1
	v_add3_u32 v79, v76, v77, s6
	v_lshl_add_u64 v[76:77], v[72:73], 0, s[42:43]
	global_store_short_d16_hi v[76:77], v79, off
	s_cbranch_scc1 .LBB0_1187
	s_lshl_b32 s25, s31, 1
	s_and_b64 s[42:43], s[44:45], exec
	s_cselect_b32 s31, s34, s5
	s_mov_b32 s42, 0x4b82000
	s_cselect_b32 s96, s42, 0x4b92000
	s_sub_i32 s27, s31, s27
	s_add_i32 s3, s3, s27
	s_add_i32 s3, s3, s25
	s_add_i32 s42, s3, 2
	s_ashr_i32 s43, s42, 31
	s_lshl_b64 s[42:43], s[42:43], 11
	v_lshl_add_u64 v[76:77], v[74:75], 0, s[42:43]
	v_lshl_add_u64 v[76:77], v[76:77], 0, s[96:97]
	s_mov_b32 s96, 0x88888889
	global_store_dword v[76:77], v78, off
.LBB0_1187:
	v_lshlrev_b32_e32 v76, 16, v132
	v_lshlrev_b32_e32 v77, 16, v133
	v_mul_f32_e32 v76, v76, v77
	v_lshlrev_b32_e32 v79, 16, v135
	v_lshlrev_b32_e32 v81, 16, v136
	s_cmp_ge_i32 s24, s33
	v_lshlrev_b32_e32 v132, 16, v134
	s_cbranch_scc1 .LBB0_1205
	s_add_i32 s3, s2, 0xffffc004
	s_lshr_b32 s27, s3, 3
	s_and_b32 s3, s24, 0x7ff
	s_cmpk_lt_i32 s2, 0x3ffc
	s_cselect_b64 s[44:45], -1, 0
	s_and_b64 s[42:43], s[44:45], exec
	v_readlane_b32 s25, v254, 36
	s_cselect_b32 s3, s3, s25
	s_cmp_lg_u32 s3, 0
	s_cselect_b64 s[42:43], -1, 0
	s_or_b64 s[68:69], s[44:45], s[42:43]
	s_and_b64 vcc, exec, s[68:69]
	s_cbranch_vccnz .LBB0_1190
	s_mul_i32 s25, s27, 0x680
	v_add_u32_e32 v82, s25, v64
	v_add_u32_e32 v134, s25, v104
	v_ashrrev_i32_e32 v83, 31, v82
	v_ashrrev_i32_e32 v135, 31, v134
	v_lshl_add_u64 v[82:83], v[82:83], 2, s[46:47]
	v_lshl_add_u64 v[134:135], v[134:135], 2, s[46:47]
	global_load_dword v82, v[82:83], off
	s_nop 0
	global_load_dword v77, v[134:135], off
	v_add_u32_e32 v134, s25, v66
	v_ashrrev_i32_e32 v135, 31, v134
	v_lshl_add_u64 v[134:135], v[134:135], 2, s[46:47]
	global_load_dword v83, v[134:135], off
	s_waitcnt vmcnt(0)
	s_branch .LBB0_1191

; __device__ __forceinline__ void even_prep(const Params& p, int j, LAS unsigned char* lds, const int wave_s) {
;     ...
;                     const float sr = cr + (qr - cr) * mu_r, sk = ck + (qk - ck) * mu_k, sv = cv + (qv - cv) * mu_v;
;                     const float wp = w0 + DW[(hh * 8 + i) * 64 + lane], ap = a0 + DA[(hh * 8 + i) * 64 + lane];
;                     const float xs = -wp;
;                     const float sp = xs > 20.f ? xs : __logf(1.f + __expf(xs));
;                     const float decay = __expf(-__expf(-sp - 0.5f));
;                     const float a = 1.f / (1.f + __expf(-ap));
;                     const float kk = sk * k_k;
;                     const float ss = wave_sum(kk * kk);
;                     const float kkn = kk * rsqrtf(fmaxf(ss, 1e-24f));
;                     const float kmod = sk * (1.f + (a - 1.f) * k_a);
;                     const float bon = wave_sum(sr * kmod * r_k);
;                     const size_t o = (size_t)n * 512 + tid;
;                     SR[o] = sr; SW[o] = decay; SK[o] = kmod; SV[o] = sv; SKK[o] = kkn; SBB[o] = kkn * a;
;                     if (lane == 0) BON[(size_t)n * 8 + wave] = bon;
.LBB0_1191:
	ds_read2st64_b32 v[134:135], v86 offset0:68 offset1:84
	v_sub_f32_e32 v82, v82, v79
	v_fma_f32 v136, v94, v82, v79
	s_mov_b32 s25, 0x3f317217
	v_sub_f32_e32 v83, v83, v132
	s_waitcnt lgkmcnt(0)
	v_add_f32_e32 v133, v98, v134
	v_mul_f32_e32 v134, 0xbfb8aa3b, v133
	v_exp_f32_e32 v134, v134
	v_sub_f32_e32 v77, v77, v81
	v_fma_f32 v77, v95, v77, v81
	v_mov_b32_e32 v140, 0
	v_add_f32_e32 v82, 1.0, v134
	v_cmp_gt_f32_e32 vcc, s15, v82
	s_nop 1
	v_cndmask_b32_e64 v134, 0, 32, vcc
	v_ldexp_f32 v82, v82, v134
	v_log_f32_e32 v82, v82
	v_add_f32_e32 v134, v99, v135
	v_cndmask_b32_e32 v135, 0, v222, vcc
	v_mul_f32_e32 v137, 0x3f317217, v82
	v_fma_f32 v137, v82, s25, -v137
	v_fmac_f32_e32 v137, 0x3377d1cf, v82
	s_mov_b32 s25, 0x7f800000
	v_fmac_f32_e32 v137, 0x3f317217, v82
	v_cmp_lt_f32_e64 vcc, |v82|, s25
	s_mov_b32 s25, 0xc1a00000
	s_nop 0
	v_cndmask_b32_e32 v82, v82, v137, vcc
	v_sub_f32_e32 v82, v82, v135
	v_cmp_gt_f32_e32 vcc, s25, v133
	v_fma_f32 v137, v96, v83, v132
	s_nop 0
	v_cndmask_b32_e64 v82, v82, -v133, vcc
	v_mul_f32_e32 v133, 0xbfb8aa3b, v134
	v_exp_f32_e32 v133, v133
	v_sub_f32_e32 v82, -0.5, v82
	v_mul_f32_e32 v82, 0x3fb8aa3b, v82
	v_exp_f32_e32 v82, v82
	v_add_f32_e32 v133, 1.0, v133
	v_div_scale_f32 v134, s[70:71], v133, v133, 1.0
	v_rcp_f32_e32 v135, v134
	v_mul_f32_e32 v82, 0xbfb8aa3b, v82
	v_exp_f32_e32 v138, v82
	v_fma_f32 v82, -v134, v135, 1.0
	v_fmac_f32_e32 v135, v82, v135
	v_div_scale_f32 v82, vcc, 1.0, v133, 1.0
	v_mul_f32_e32 v83, v82, v135
	v_fma_f32 v139, -v134, v83, v82
	v_fmac_f32_e32 v83, v139, v135
	v_fma_f32 v82, -v134, v83, v82
	v_mul_f32_e32 v134, v100, v77
	v_div_fmas_f32 v82, v82, v135, v83
	v_mul_f32_e32 v139, v134, v134
	v_div_fixup_f32 v133, v82, v133, 1.0
	v_add_f32_e32 v82, -1.0, v133
	v_mov_b32_dpp v139, v139 row_shr:1 row_mask:0xf bank_mask:0xf bound_ctrl:1
	v_fmac_f32_e32 v139, v134, v134
	v_fma_f32 v82, v101, v82, 1.0
	v_mul_f32_e32 v77, v77, v82
	v_add_f32_dpp v139, v139, v139 row_shr:2 row_mask:0xf bank_mask:0xf bound_ctrl:1
	v_mul_f32_e32 v82, v136, v77
	v_mul_f32_e32 v83, v102, v82
	v_add_f32_dpp v139, v139, v139 row_shr:4 row_mask:0xf bank_mask:0xf bound_ctrl:1
	s_nop 0
	v_mov_b32_dpp v83, v83 row_shr:1 row_mask:0xf bank_mask:0xf bound_ctrl:1
	v_add_f32_dpp v139, v139, v139 row_shr:8 row_mask:0xf bank_mask:0xf bound_ctrl:1
	v_fmac_f32_e32 v83, v102, v82
	s_nop 0
	v_mov_b32_dpp v140, v139 row_bcast:15 row_mask:0xa bank_mask:0xf
	v_add_f32_e32 v139, v139, v140
	v_mov_b32_e32 v140, 0
	v_add_f32_dpp v82, v83, v83 row_shr:2 row_mask:0xf bank_mask:0xf bound_ctrl:1
	v_mov_b32_e32 v83, 0
	v_mov_b32_dpp v140, v139 row_bcast:31 row_mask:0xc bank_mask:0xf
	v_add_f32_e32 v139, v139, v140
	v_add_f32_dpp v82, v82, v82 row_shr:4 row_mask:0xf bank_mask:0xf bound_ctrl:1
	v_readlane_b32 s25, v139, 63
	s_nop 0
	v_add_f32_dpp v82, v82, v82 row_shr:8 row_mask:0xf bank_mask:0xf bound_ctrl:1
	v_max_f32_e64 v139, s25, s25
	v_max_f32_e32 v139, 0x179abe15, v139
	v_mov_b32_dpp v83, v82 row_bcast:15 row_mask:0xa bank_mask:0xf
	v_add_f32_e32 v82, v82, v83
	v_mov_b32_e32 v83, 0
	v_rsq_f32_e32 v139, v139
	s_ashr_i32 s25, s24, 31
	v_mov_b32_dpp v83, v82 row_bcast:31 row_mask:0xc bank_mask:0xf
	v_add_f32_e32 v82, v82, v83
	s_lshl_b64 s[70:71], s[24:25], 9
	v_readlane_b32 s31, v82, 63
	v_lshl_add_u64 v[82:83], s[70:71], 0, v[64:65]
	v_lshlrev_b64 v[82:83], 2, v[82:83]
	v_mul_f32_e32 v139, v134, v139
	v_lshl_add_u64 v[134:135], s[58:59], 0, v[82:83]
	global_store_dword v[134:135], v136, off
	v_lshl_add_u64 v[134:135], s[50:51], 0, v[82:83]
	global_store_dword v[134:135], v138, off
	v_lshl_add_u64 v[134:135], s[56:57], 0, v[82:83]
	global_store_dword v[134:135], v77, off
	v_lshl_add_u64 v[134:135], s[52:53], 0, v[82:83]
	global_store_dword v[134:135], v137, off
	v_lshl_add_u64 v[134:135], s[38:39], 0, v[82:83]
	v_mul_f32_e32 v77, v133, v139
	v_lshl_add_u64 v[82:83], s[54:55], 0, v[82:83]
	global_store_dword v[134:135], v139, off
	global_store_dword v[82:83], v77, off
	s_and_saveexec_b64 s[70:71], s[40:41]
	s_cbranch_execz .LBB0_1193
	s_lshl_b64 s[72:73], s[24:25], 5
	s_add_u32 s72, s17, s72
	s_addc_u32 s73, s83, s73
	v_mov_b32_e32 v77, s31
	global_store_dword v185, v77, s[72:73]

; __device__ __forceinline__ void even_prep(const Params& p, int j, LAS unsigned char* lds, const int wave_s) {
;     ...
;                     if (t < 1) um1 = samp ? sconv[(b * 2 + 1) * 512 + tid] : 0.f;
;                     if (t < 2) um2 = samp ? sconv[(b * 2 + t) * 512 + tid] : 0.f;
.LBB0_1197:
	s_xor_b64 s[68:69], s[68:69], -1
	s_andn2_b64 vcc, exec, s[68:69]
	s_cbranch_vccnz .LBB0_1199
	v_lshl_add_u32 v82, s27, 10, v104
	v_ashrrev_i32_e32 v83, 31, v82
	v_lshl_add_u64 v[82:83], v[82:83], 2, s[48:49]
	global_load_dword v77, v[82:83], off
	s_waitcnt vmcnt(0)
	s_branch .LBB0_1200

; __device__ __forceinline__ void even_prep(const Params& p, int j, LAS unsigned char* lds, const int wave_s) {
;     ...
;                     if (t < 1) um1 = samp ? sconv[(b * 2 + 1) * 512 + tid] : 0.f;
;                     if (t < 2) um2 = samp ? sconv[(b * 2 + t) * 512 + tid] : 0.f;
.LBB0_1200:
	s_cmp_gt_u32 s3, 1
	s_cselect_b64 s[42:43], -1, 0
	s_or_b64 s[68:69], s[44:45], s[42:43]
	s_and_b64 vcc, exec, s[68:69]
	s_cbranch_vccnz .LBB0_1202
	v_lshl_add_u32 v82, s27, 10, v112
	v_ashrrev_i32_e32 v83, 31, v82
	v_lshl_add_u64 v[82:83], v[82:83], 2, s[48:49]
	global_load_dword v80, v[82:83], off
	s_waitcnt vmcnt(0)
	s_branch .LBB0_1203

; __device__ __forceinline__ unsigned f2bf(float f) { unsigned u = __float_as_uint(f); return (u + 0x7fffu + ((u >> 16) & 1u)) >> 16; }
; __device__ __forceinline__ float silu(float x) { return x / (1.f + __expf(-x)); }
; __device__ __forceinline__ void even_prep(const Params& p, int j, LAS unsigned char* lds, const int wave_s) {
;     ...
;             for (int i = 0; i < 8; ++i) { const int n = nh + i;
;                 if (n < n1) {
;                     int b, t, T; const bool samp = n >= NP;
;                     if (!samp) { b = n >> 11; t = n & 2047; T = SEQ; } else { const int s = n - NP; b = s >> 3; t = s & 7; T = ST; }
;                     const float cr = rr[i + 1], ck = kr[i + 1], cv = vr[i + 1];
;                     float qr = rr[i], qk = kr[i], qv = vr[i];
;                     if (t == 0) { qr = 0.f; qk = 0.f; qv = 0.f; if (samp) { qr = sshift[b * ASW + tid]; qk = sshift[b * ASW + 512 + tid]; qv = sshift[b * ASW + 1024 + tid]; } }
;     ...
;                     const float yc = cw0 * um2 + cw1 * um1 + cw2 * u0;
;                     MIX[(size_t)n * DM + 512 + tid] = (bf16_t)f2bf(bbv[i] * yc * silu(zbv[i]));
;                     if (t >= T - 2) { float* co = p.out + (samp ? O_CV_S + (size_t)((j * SB + b) * 2 + (t - (T - 2))) * 512 : O_CV_P + (size_t)((j * PB + b) * 2 + (t - (T - 2))) * 512); co[tid] = u0; }
.LBB0_1203:
	v_lshlrev_b32_e32 v91, 16, v91
	v_pk_mul_f32 v[82:83], v[68:69], v[76:77]
	v_lshlrev_b32_e32 v131, 16, v131
	v_fma_f32 v77, v103, v80, v83
	v_mul_f32_e32 v80, 0xbfb8aa3b, v91
	v_exp_f32_e32 v80, v80
	v_add_f32_e32 v77, v82, v77
	v_mul_f32_e32 v77, v77, v131
	s_lshl_b64 s[24:25], s[24:25], 11
	v_add_f32_e32 v80, 1.0, v80
	v_div_scale_f32 v82, s[42:43], v80, v80, v91
	v_rcp_f32_e32 v83, v82
	s_nop 0
	v_fma_f32 v131, -v82, v83, 1.0
	v_fmac_f32_e32 v83, v131, v83
	v_div_scale_f32 v131, vcc, v91, v80, v91
	v_mul_f32_e32 v133, v131, v83
	v_fma_f32 v134, -v82, v133, v131
	v_fmac_f32_e32 v133, v134, v83
	v_fma_f32 v82, -v82, v133, v131
	v_div_fmas_f32 v82, v82, v83, v133
	v_div_fixup_f32 v80, v82, v80, v91
	v_mul_f32_e32 v77, v80, v77
	v_bfe_u32 v80, v77, 16, 1
	v_lshl_add_u64 v[82:83], v[72:73], 0, s[24:25]
	s_add_i32 s24, s31, -2
	v_add3_u32 v77, v77, v80, s6
	s_cmp_lt_u32 s3, s24
	global_store_short_d16_hi v[82:83], v77, off
	s_cbranch_scc1 .LBB0_1205
	s_lshl_b32 s27, s65, 1
	s_and_b64 s[24:25], s[44:45], exec
	s_cselect_b32 s24, s34, s5
	s_mov_b32 s25, 0x4b82000
	s_cselect_b32 s96, s25, 0x4b92000
	s_sub_i32 s24, s24, s31
	s_add_i32 s3, s3, s24
	s_add_i32 s3, s3, s27
	s_add_i32 s24, s3, 2
	s_ashr_i32 s25, s24, 31
	s_lshl_b64 s[24:25], s[24:25], 11
	v_lshl_add_u64 v[82:83], v[74:75], 0, s[24:25]
	v_lshl_add_u64 v[82:83], v[82:83], 0, s[96:97]
	s_mov_b32 s96, 0x88888889
	global_store_dword v[82:83], v76, off
.LBB0_1205:
	v_lshlrev_b32_e32 v77, 16, v126
	v_lshlrev_b32_e32 v80, 16, v127
	v_mul_f32_e32 v80, v77, v80
	v_lshlrev_b32_e32 v77, 16, v129
	v_lshlrev_b32_e32 v91, 16, v130
	s_cmp_ge_i32 s26, s33
	v_lshlrev_b32_e32 v126, 16, v128
	s_cbranch_scc1 .LBB0_1223
	s_add_i32 s3, s2, 0xffffc005
	s_lshr_b32 s31, s3, 3
	s_and_b32 s3, s26, 0x7ff
	s_cmpk_lt_i32 s2, 0x3ffb
	s_cselect_b64 s[24:25], -1, 0
	s_and_b64 s[42:43], s[24:25], exec
	v_readlane_b32 s27, v254, 38
	s_cselect_b32 s3, s3, s27
	s_cmp_lg_u32 s3, 0
	s_cselect_b64 s[42:43], -1, 0
	s_or_b64 s[44:45], s[24:25], s[42:43]
	s_and_b64 vcc, exec, s[44:45]
	s_cbranch_vccnz .LBB0_1208
	s_mul_i32 s27, s31, 0x680
	v_add_u32_e32 v82, s27, v64
	v_ashrrev_i32_e32 v83, 31, v82
	v_lshl_add_u64 v[82:83], v[82:83], 2, s[46:47]
	global_load_dword v79, v[82:83], off
	v_add_u32_e32 v82, s27, v104
	v_ashrrev_i32_e32 v83, 31, v82
	v_lshl_add_u64 v[82:83], v[82:83], 2, s[46:47]
	global_load_dword v81, v[82:83], off
	v_add_u32_e32 v82, s27, v66
	v_ashrrev_i32_e32 v83, 31, v82
	v_lshl_add_u64 v[82:83], v[82:83], 2, s[46:47]
	global_load_dword v82, v[82:83], off
	s_waitcnt vmcnt(0)
	s_branch .LBB0_1209

; __device__ __forceinline__ void even_prep(const Params& p, int j, LAS unsigned char* lds, const int wave_s) {
;     ...
;                     const float sr = cr + (qr - cr) * mu_r, sk = ck + (qk - ck) * mu_k, sv = cv + (qv - cv) * mu_v;
;                     const float wp = w0 + DW[(hh * 8 + i) * 64 + lane], ap = a0 + DA[(hh * 8 + i) * 64 + lane];
;                     const float xs = -wp;
;                     const float sp = xs > 20.f ? xs : __logf(1.f + __expf(xs));
;                     const float decay = __expf(-__expf(-sp - 0.5f));
;                     const float a = 1.f / (1.f + __expf(-ap));
;                     const float kk = sk * k_k;
;                     const float ss = wave_sum(kk * kk);
;                     const float kkn = kk * rsqrtf(fmaxf(ss, 1e-24f));
;                     const float kmod = sk * (1.f + (a - 1.f) * k_a);
;                     const float bon = wave_sum(sr * kmod * r_k);
;                     const size_t o = (size_t)n * 512 + tid;
;                     SR[o] = sr; SW[o] = decay; SK[o] = kmod; SV[o] = sv; SKK[o] = kkn; SBB[o] = kkn * a;
;                     if (lane == 0) BON[(size_t)n * 8 + wave] = bon;
.LBB0_1209:
	ds_read2st64_b32 v[128:129], v86 offset0:69 offset1:85
	s_mov_b32 s27, 0x3f317217
	v_sub_f32_e32 v82, v82, v126
	v_sub_f32_e32 v81, v81, v91
	v_fma_f32 v81, v95, v81, v91
	s_waitcnt lgkmcnt(0)
	v_add_f32_e32 v83, v98, v128
	v_mul_f32_e32 v127, 0xbfb8aa3b, v83
	v_exp_f32_e32 v127, v127
	v_sub_f32_e32 v79, v79, v77
	v_fma_f32 v79, v94, v79, v77
	v_mov_b32_e32 v133, 0
	v_add_f32_e32 v127, 1.0, v127
	v_cmp_gt_f32_e32 vcc, s15, v127
	s_nop 1
	v_cndmask_b32_e64 v128, 0, 32, vcc
	v_ldexp_f32 v127, v127, v128
	v_log_f32_e32 v127, v127
	v_add_f32_e32 v128, v99, v129
	v_cndmask_b32_e32 v129, 0, v222, vcc
	v_mul_f32_e32 v130, 0x3f317217, v127
	v_fma_f32 v130, v127, s27, -v130
	v_fmac_f32_e32 v130, 0x3377d1cf, v127
	s_mov_b32 s27, 0x7f800000
	v_fmac_f32_e32 v130, 0x3f317217, v127
	v_cmp_lt_f32_e64 vcc, |v127|, s27
	s_mov_b32 s27, 0xc1a00000
	s_nop 0
	v_cndmask_b32_e32 v127, v127, v130, vcc
	v_sub_f32_e32 v127, v127, v129
	v_cmp_gt_f32_e32 vcc, s27, v83
	v_fma_f32 v130, v96, v82, v126
	s_nop 0
	v_cndmask_b32_e64 v83, v127, -v83, vcc
	v_mul_f32_e32 v127, 0xbfb8aa3b, v128
	v_exp_f32_e32 v127, v127
	v_sub_f32_e32 v83, -0.5, v83
	v_mul_f32_e32 v83, 0x3fb8aa3b, v83
	v_exp_f32_e32 v83, v83
	v_add_f32_e32 v127, 1.0, v127
	v_div_scale_f32 v128, s[68:69], v127, v127, 1.0
	v_rcp_f32_e32 v129, v128
	v_mul_f32_e32 v82, 0xbfb8aa3b, v83
	v_exp_f32_e32 v131, v82
	v_fma_f32 v82, -v128, v129, 1.0
	v_fmac_f32_e32 v129, v82, v129
	v_div_scale_f32 v82, vcc, 1.0, v127, 1.0
	v_mul_f32_e32 v83, v82, v129
	v_fma_f32 v132, -v128, v83, v82
	v_fmac_f32_e32 v83, v132, v129
	v_fma_f32 v82, -v128, v83, v82
	v_mul_f32_e32 v128, v100, v81
	v_div_fmas_f32 v82, v82, v129, v83
	v_mul_f32_e32 v132, v128, v128
	v_div_fixup_f32 v127, v82, v127, 1.0
	v_add_f32_e32 v82, -1.0, v127
	v_mov_b32_dpp v132, v132 row_shr:1 row_mask:0xf bank_mask:0xf bound_ctrl:1
	v_fmac_f32_e32 v132, v128, v128
	v_fma_f32 v82, v101, v82, 1.0
	v_mul_f32_e32 v81, v81, v82
	v_add_f32_dpp v132, v132, v132 row_shr:2 row_mask:0xf bank_mask:0xf bound_ctrl:1
	v_mul_f32_e32 v82, v79, v81
	v_mul_f32_e32 v83, v102, v82
	v_add_f32_dpp v132, v132, v132 row_shr:4 row_mask:0xf bank_mask:0xf bound_ctrl:1
	s_nop 0
	v_mov_b32_dpp v83, v83 row_shr:1 row_mask:0xf bank_mask:0xf bound_ctrl:1
	v_add_f32_dpp v132, v132, v132 row_shr:8 row_mask:0xf bank_mask:0xf bound_ctrl:1
	v_fmac_f32_e32 v83, v102, v82
	s_nop 0
	v_mov_b32_dpp v133, v132 row_bcast:15 row_mask:0xa bank_mask:0xf
	v_add_f32_e32 v132, v132, v133
	v_mov_b32_e32 v133, 0
	v_add_f32_dpp v82, v83, v83 row_shr:2 row_mask:0xf bank_mask:0xf bound_ctrl:1
	v_mov_b32_e32 v83, 0
	v_mov_b32_dpp v133, v132 row_bcast:31 row_mask:0xc bank_mask:0xf
	v_add_f32_e32 v132, v132, v133
	v_add_f32_dpp v82, v82, v82 row_shr:4 row_mask:0xf bank_mask:0xf bound_ctrl:1
	v_readlane_b32 s27, v132, 63
	s_nop 0
	v_add_f32_dpp v82, v82, v82 row_shr:8 row_mask:0xf bank_mask:0xf bound_ctrl:1
	v_max_f32_e64 v132, s27, s27
	v_max_f32_e32 v132, 0x179abe15, v132
	v_mov_b32_dpp v83, v82 row_bcast:15 row_mask:0xa bank_mask:0xf
	v_add_f32_e32 v82, v82, v83
	v_mov_b32_e32 v83, 0
	v_rsq_f32_e32 v132, v132
	s_ashr_i32 s27, s26, 31
	v_mov_b32_dpp v83, v82 row_bcast:31 row_mask:0xc bank_mask:0xf
	v_add_f32_e32 v82, v82, v83
	s_lshl_b64 s[68:69], s[26:27], 9
	v_readlane_b32 s65, v82, 63
	v_lshl_add_u64 v[82:83], s[68:69], 0, v[64:65]
	v_lshlrev_b64 v[82:83], 2, v[82:83]
	v_mul_f32_e32 v132, v128, v132
	v_lshl_add_u64 v[128:129], s[58:59], 0, v[82:83]
	global_store_dword v[128:129], v79, off
	v_lshl_add_u64 v[128:129], s[50:51], 0, v[82:83]
	global_store_dword v[128:129], v131, off
	v_lshl_add_u64 v[128:129], s[56:57], 0, v[82:83]
	global_store_dword v[128:129], v81, off
	v_lshl_add_u64 v[128:129], s[52:53], 0, v[82:83]
	global_store_dword v[128:129], v130, off
	v_lshl_add_u64 v[128:129], s[38:39], 0, v[82:83]
	v_mul_f32_e32 v79, v127, v132
	v_lshl_add_u64 v[82:83], s[54:55], 0, v[82:83]
	global_store_dword v[128:129], v132, off
	global_store_dword v[82:83], v79, off
	s_and_saveexec_b64 s[68:69], s[40:41]
	s_cbranch_execz .LBB0_1211
	s_lshl_b64 s[70:71], s[26:27], 5
	s_add_u32 s70, s17, s70
	s_addc_u32 s71, s83, s71
	v_mov_b32_e32 v79, s65
	global_store_dword v185, v79, s[70:71]

; __device__ __forceinline__ void even_prep(const Params& p, int j, LAS unsigned char* lds, const int wave_s) {
;     ...
;                     if (t < 1) um1 = samp ? sconv[(b * 2 + 1) * 512 + tid] : 0.f;
;                     if (t < 2) um2 = samp ? sconv[(b * 2 + t) * 512 + tid] : 0.f;
.LBB0_1215:
	s_xor_b64 s[44:45], s[44:45], -1
	s_andn2_b64 vcc, exec, s[44:45]
	s_cbranch_vccnz .LBB0_1217
	v_lshl_add_u32 v82, s31, 10, v104
	v_ashrrev_i32_e32 v83, 31, v82
	v_lshl_add_u64 v[82:83], v[82:83], 2, s[48:49]
	global_load_dword v81, v[82:83], off
	s_waitcnt vmcnt(0)
	s_branch .LBB0_1218

; __device__ __forceinline__ void even_prep(const Params& p, int j, LAS unsigned char* lds, const int wave_s) {
;     ...
;                     if (t < 1) um1 = samp ? sconv[(b * 2 + 1) * 512 + tid] : 0.f;
;                     if (t < 2) um2 = samp ? sconv[(b * 2 + t) * 512 + tid] : 0.f;
.LBB0_1218:
	s_cmp_gt_u32 s3, 1
	s_cselect_b64 s[42:43], -1, 0
	s_or_b64 s[44:45], s[24:25], s[42:43]
	s_and_b64 vcc, exec, s[44:45]
	s_cbranch_vccnz .LBB0_1220
	v_lshl_add_u32 v78, s31, 10, v113
	v_ashrrev_i32_e32 v79, 31, v78
	v_lshl_add_u64 v[78:79], v[78:79], 2, s[48:49]
	global_load_dword v78, v[78:79], off
	s_waitcnt vmcnt(0)
	s_branch .LBB0_1221

; __device__ __forceinline__ unsigned f2bf(float f) { unsigned u = __float_as_uint(f); return (u + 0x7fffu + ((u >> 16) & 1u)) >> 16; }
; __device__ __forceinline__ float silu(float x) { return x / (1.f + __expf(-x)); }
; __device__ __forceinline__ void even_prep(const Params& p, int j, LAS unsigned char* lds, const int wave_s) {
;     ...
;             for (int i = 0; i < 8; ++i) { const int n = nh + i;
;                 if (n < n1) {
;                     int b, t, T; const bool samp = n >= NP;
;                     if (!samp) { b = n >> 11; t = n & 2047; T = SEQ; } else { const int s = n - NP; b = s >> 3; t = s & 7; T = ST; }
;                     const float cr = rr[i + 1], ck = kr[i + 1], cv = vr[i + 1];
;                     float qr = rr[i], qk = kr[i], qv = vr[i];
;                     if (t == 0) { qr = 0.f; qk = 0.f; qv = 0.f; if (samp) { qr = sshift[b * ASW + tid]; qk = sshift[b * ASW + 512 + tid]; qv = sshift[b * ASW + 1024 + tid]; } }
;     ...
;                     const float yc = cw0 * um2 + cw1 * um1 + cw2 * u0;
;                     MIX[(size_t)n * DM + 512 + tid] = (bf16_t)f2bf(bbv[i] * yc * silu(zbv[i]));
;                     if (t >= T - 2) { float* co = p.out + (samp ? O_CV_S + (size_t)((j * SB + b) * 2 + (t - (T - 2))) * 512 : O_CV_P + (size_t)((j * PB + b) * 2 + (t - (T - 2))) * 512); co[tid] = u0; }
.LBB0_1221:
	v_pk_mul_f32 v[82:83], v[68:69], v[80:81]
	v_lshlrev_b32_e32 v79, 16, v90
	v_fma_f32 v78, v103, v78, v83
	v_lshlrev_b32_e32 v89, 16, v89
	v_add_f32_e32 v78, v82, v78
	v_mul_f32_e32 v78, v78, v79
	v_mul_f32_e32 v79, 0xbfb8aa3b, v89
	v_exp_f32_e32 v79, v79
	s_lshl_b64 s[26:27], s[26:27], 11
	v_add_f32_e32 v79, 1.0, v79
	v_div_scale_f32 v81, s[42:43], v79, v79, v89
	v_rcp_f32_e32 v82, v81
	s_nop 0
	v_fma_f32 v83, -v81, v82, 1.0
	v_fmac_f32_e32 v82, v83, v82
	v_div_scale_f32 v83, vcc, v89, v79, v89
	v_mul_f32_e32 v90, v83, v82
	v_fma_f32 v127, -v81, v90, v83
	v_fmac_f32_e32 v90, v127, v82
	v_fma_f32 v81, -v81, v90, v83
	v_div_fmas_f32 v81, v81, v82, v90
	v_div_fixup_f32 v79, v81, v79, v89
	v_mul_f32_e32 v78, v79, v78
	v_bfe_u32 v79, v78, 16, 1
	v_add3_u32 v81, v78, v79, s6
	v_lshl_add_u64 v[78:79], v[72:73], 0, s[26:27]
	s_add_i32 s26, s65, -2
	s_cmp_lt_u32 s3, s26
	global_store_short_d16_hi v[78:79], v81, off
	s_cbranch_scc1 .LBB0_1223
	s_lshl_b32 s26, s70, 1
	s_and_b64 s[24:25], s[24:25], exec
	s_cselect_b32 s24, s34, s5
	s_mov_b32 s25, 0x4b82000
	s_cselect_b32 s96, s25, 0x4b92000
	s_sub_i32 s24, s24, s65
	s_add_i32 s3, s3, s24
	s_add_i32 s3, s3, s26
	s_add_i32 s24, s3, 2
	s_ashr_i32 s25, s24, 31
	s_lshl_b64 s[24:25], s[24:25], 11
	v_lshl_add_u64 v[78:79], v[74:75], 0, s[24:25]
	v_lshl_add_u64 v[78:79], v[78:79], 0, s[96:97]
	s_mov_b32 s96, 0x88888889
	global_store_dword v[78:79], v80, off
.LBB0_1223:
	v_lshlrev_b32_e32 v78, 16, v121
	v_lshlrev_b32_e32 v79, 16, v122
	v_mul_f32_e32 v78, v78, v79
	v_lshlrev_b32_e32 v81, 16, v124
	v_lshlrev_b32_e32 v89, 16, v125
	s_cmp_ge_i32 s30, s33
	v_lshlrev_b32_e32 v90, 16, v123
	s_cbranch_scc1 .LBB0_1241
	s_add_i32 s3, s2, 0xffffc006
	s_lshr_b32 s65, s3, 3
	s_and_b32 s3, s30, 0x7ff
	s_cmpk_lt_i32 s2, 0x3ffa
	s_cselect_b64 s[24:25], -1, 0
	s_and_b64 s[26:27], s[24:25], exec
	v_readlane_b32 s26, v254, 40
	s_cselect_b32 s3, s3, s26
	s_cmp_lg_u32 s3, 0
	s_cselect_b64 s[42:43], -1, 0
	s_or_b64 s[26:27], s[24:25], s[42:43]
	s_and_b64 vcc, exec, s[26:27]
	s_cbranch_vccnz .LBB0_1226
	s_mul_i32 s31, s65, 0x680
	v_add_u32_e32 v82, s31, v64
	v_ashrrev_i32_e32 v83, 31, v82
	v_lshl_add_u64 v[82:83], v[82:83], 2, s[46:47]
	global_load_dword v77, v[82:83], off
	v_add_u32_e32 v82, s31, v104
	v_ashrrev_i32_e32 v83, 31, v82
	v_lshl_add_u64 v[82:83], v[82:83], 2, s[46:47]
	global_load_dword v79, v[82:83], off
	v_add_u32_e32 v82, s31, v66
	v_ashrrev_i32_e32 v83, 31, v82
	v_lshl_add_u64 v[82:83], v[82:83], 2, s[46:47]
	global_load_dword v82, v[82:83], off
	s_waitcnt vmcnt(0)
	s_branch .LBB0_1227

; __device__ __forceinline__ void even_prep(const Params& p, int j, LAS unsigned char* lds, const int wave_s) {
;     ...
;                     const float sr = cr + (qr - cr) * mu_r, sk = ck + (qk - ck) * mu_k, sv = cv + (qv - cv) * mu_v;
;                     const float wp = w0 + DW[(hh * 8 + i) * 64 + lane], ap = a0 + DA[(hh * 8 + i) * 64 + lane];
;                     const float xs = -wp;
;                     const float sp = xs > 20.f ? xs : __logf(1.f + __expf(xs));
;                     const float decay = __expf(-__expf(-sp - 0.5f));
;                     const float a = 1.f / (1.f + __expf(-ap));
;                     const float kk = sk * k_k;
;                     const float ss = wave_sum(kk * kk);
;                     const float kkn = kk * rsqrtf(fmaxf(ss, 1e-24f));
;                     const float kmod = sk * (1.f + (a - 1.f) * k_a);
;                     const float bon = wave_sum(sr * kmod * r_k);
;                     const size_t o = (size_t)n * 512 + tid;
;                     SR[o] = sr; SW[o] = decay; SK[o] = kmod; SV[o] = sv; SKK[o] = kkn; SBB[o] = kkn * a;
;                     if (lane == 0) BON[(size_t)n * 8 + wave] = bon;
.LBB0_1227:
	ds_read2st64_b32 v[122:123], v86 offset0:70 offset1:86
	s_mov_b32 s31, 0x3f317217
	v_sub_f32_e32 v82, v82, v90
	v_fma_f32 v124, v96, v82, v90
	v_sub_f32_e32 v79, v79, v89
	s_waitcnt lgkmcnt(0)
	v_add_f32_e32 v83, v98, v122
	v_mul_f32_e32 v91, 0xbfb8aa3b, v83
	v_exp_f32_e32 v91, v91
	v_fma_f32 v79, v95, v79, v89
	v_sub_f32_e32 v77, v77, v81
	v_fma_f32 v77, v94, v77, v81
	v_add_f32_e32 v91, 1.0, v91
	v_cmp_gt_f32_e32 vcc, s15, v91
	v_mov_b32_e32 v126, 0
	s_nop 0
	v_cndmask_b32_e64 v121, 0, 32, vcc
	v_ldexp_f32 v91, v91, v121
	v_log_f32_e32 v91, v91
	v_add_f32_e32 v121, v99, v123
	v_cndmask_b32_e32 v122, 0, v222, vcc
	v_mul_f32_e32 v123, 0x3f317217, v91
	v_fma_f32 v123, v91, s31, -v123
	v_fmac_f32_e32 v123, 0x3377d1cf, v91
	s_mov_b32 s31, 0x7f800000
	v_fmac_f32_e32 v123, 0x3f317217, v91
	v_cmp_lt_f32_e64 vcc, |v91|, s31
	s_mov_b32 s31, 0xc1a00000
	s_nop 0
	v_cndmask_b32_e32 v91, v91, v123, vcc
	v_sub_f32_e32 v91, v91, v122
	v_cmp_gt_f32_e32 vcc, s31, v83
	s_nop 1
	v_cndmask_b32_e64 v83, v91, -v83, vcc
	v_mul_f32_e32 v91, 0xbfb8aa3b, v121
	v_exp_f32_e32 v91, v91
	v_sub_f32_e32 v83, -0.5, v83
	v_mul_f32_e32 v83, 0x3fb8aa3b, v83
	v_exp_f32_e32 v83, v83
	v_add_f32_e32 v91, 1.0, v91
	v_div_scale_f32 v121, s[44:45], v91, v91, 1.0
	v_rcp_f32_e32 v122, v121
	v_mul_f32_e32 v82, 0xbfb8aa3b, v83
	v_exp_f32_e32 v125, v82
	v_fma_f32 v82, -v121, v122, 1.0
	v_fmac_f32_e32 v122, v82, v122
	v_div_scale_f32 v82, vcc, 1.0, v91, 1.0
	v_mul_f32_e32 v83, v82, v122
	v_fma_f32 v123, -v121, v83, v82
	v_fmac_f32_e32 v83, v123, v122
	v_fma_f32 v82, -v121, v83, v82
	v_mul_f32_e32 v121, v100, v79
	v_div_fmas_f32 v82, v82, v122, v83
	v_mul_f32_e32 v123, v121, v121
	v_div_fixup_f32 v91, v82, v91, 1.0
	v_add_f32_e32 v82, -1.0, v91
	v_mov_b32_dpp v123, v123 row_shr:1 row_mask:0xf bank_mask:0xf bound_ctrl:1
	v_fmac_f32_e32 v123, v121, v121
	v_fma_f32 v82, v101, v82, 1.0
	v_mul_f32_e32 v79, v79, v82
	v_add_f32_dpp v123, v123, v123 row_shr:2 row_mask:0xf bank_mask:0xf bound_ctrl:1
	v_mul_f32_e32 v82, v77, v79
	v_mul_f32_e32 v83, v102, v82
	v_add_f32_dpp v123, v123, v123 row_shr:4 row_mask:0xf bank_mask:0xf bound_ctrl:1
	s_nop 0
	v_mov_b32_dpp v83, v83 row_shr:1 row_mask:0xf bank_mask:0xf bound_ctrl:1
	v_add_f32_dpp v123, v123, v123 row_shr:8 row_mask:0xf bank_mask:0xf bound_ctrl:1
	v_fmac_f32_e32 v83, v102, v82
	s_nop 0
	v_mov_b32_dpp v126, v123 row_bcast:15 row_mask:0xa bank_mask:0xf
	v_add_f32_e32 v123, v123, v126
	v_mov_b32_e32 v126, 0
	v_add_f32_dpp v82, v83, v83 row_shr:2 row_mask:0xf bank_mask:0xf bound_ctrl:1
	v_mov_b32_e32 v83, 0
	v_mov_b32_dpp v126, v123 row_bcast:31 row_mask:0xc bank_mask:0xf
	v_add_f32_e32 v123, v123, v126
	v_add_f32_dpp v82, v82, v82 row_shr:4 row_mask:0xf bank_mask:0xf bound_ctrl:1
	v_readlane_b32 s31, v123, 63
	s_nop 0
	v_add_f32_dpp v82, v82, v82 row_shr:8 row_mask:0xf bank_mask:0xf bound_ctrl:1
	v_max_f32_e64 v123, s31, s31
	v_max_f32_e32 v123, 0x179abe15, v123
	v_mov_b32_dpp v83, v82 row_bcast:15 row_mask:0xa bank_mask:0xf
	v_add_f32_e32 v82, v82, v83
	v_mov_b32_e32 v83, 0
	v_rsq_f32_e32 v123, v123
	s_ashr_i32 s31, s30, 31
	v_mov_b32_dpp v83, v82 row_bcast:31 row_mask:0xc bank_mask:0xf
	v_add_f32_e32 v82, v82, v83
	s_lshl_b64 s[44:45], s[30:31], 9
	v_readlane_b32 s68, v82, 63
	v_lshl_add_u64 v[82:83], s[44:45], 0, v[64:65]
	v_lshlrev_b64 v[82:83], 2, v[82:83]
	v_mul_f32_e32 v121, v121, v123
	v_lshl_add_u64 v[122:123], s[58:59], 0, v[82:83]
	global_store_dword v[122:123], v77, off
	v_lshl_add_u64 v[122:123], s[50:51], 0, v[82:83]
	global_store_dword v[122:123], v125, off
	v_lshl_add_u64 v[122:123], s[56:57], 0, v[82:83]
	global_store_dword v[122:123], v79, off
	v_lshl_add_u64 v[122:123], s[52:53], 0, v[82:83]
	global_store_dword v[122:123], v124, off
	v_lshl_add_u64 v[122:123], s[38:39], 0, v[82:83]
	v_mul_f32_e32 v77, v91, v121
	v_lshl_add_u64 v[82:83], s[54:55], 0, v[82:83]
	global_store_dword v[122:123], v121, off
	global_store_dword v[82:83], v77, off
	s_and_saveexec_b64 s[44:45], s[40:41]
	s_cbranch_execz .LBB0_1229
	s_lshl_b64 s[70:71], s[30:31], 5
	s_add_u32 s70, s17, s70
	s_addc_u32 s71, s83, s71
	v_mov_b32_e32 v77, s68
	global_store_dword v185, v77, s[70:71]

; __device__ __forceinline__ void even_prep(const Params& p, int j, LAS unsigned char* lds, const int wave_s) {
;     ...
;                     if (t < 1) um1 = samp ? sconv[(b * 2 + 1) * 512 + tid] : 0.f;
;                     if (t < 2) um2 = samp ? sconv[(b * 2 + t) * 512 + tid] : 0.f;
.LBB0_1233:
	s_xor_b64 s[26:27], s[26:27], -1
	s_andn2_b64 vcc, exec, s[26:27]
	s_cbranch_vccnz .LBB0_1235
	v_lshl_add_u32 v82, s65, 10, v104
	v_ashrrev_i32_e32 v83, 31, v82
	v_lshl_add_u64 v[82:83], v[82:83], 2, s[48:49]
	global_load_dword v79, v[82:83], off
	s_waitcnt vmcnt(0)
	s_branch .LBB0_1236

; __device__ __forceinline__ void even_prep(const Params& p, int j, LAS unsigned char* lds, const int wave_s) {
;     ...
;                     if (t < 1) um1 = samp ? sconv[(b * 2 + 1) * 512 + tid] : 0.f;
;                     if (t < 2) um2 = samp ? sconv[(b * 2 + t) * 512 + tid] : 0.f;
.LBB0_1236:
	s_cmp_gt_u32 s3, 1
	s_cselect_b64 s[42:43], -1, 0
	s_or_b64 s[26:27], s[24:25], s[42:43]
	s_and_b64 vcc, exec, s[26:27]
	s_cbranch_vccnz .LBB0_1238
	v_lshl_add_u32 v76, s65, 10, v114
	v_ashrrev_i32_e32 v77, 31, v76
	v_lshl_add_u64 v[76:77], v[76:77], 2, s[48:49]
	global_load_dword v76, v[76:77], off
	s_waitcnt vmcnt(0)
	s_branch .LBB0_1239

; __device__ __forceinline__ unsigned f2bf(float f) { unsigned u = __float_as_uint(f); return (u + 0x7fffu + ((u >> 16) & 1u)) >> 16; }
; __device__ __forceinline__ float silu(float x) { return x / (1.f + __expf(-x)); }
; __device__ __forceinline__ void even_prep(const Params& p, int j, LAS unsigned char* lds, const int wave_s) {
;     ...
;             for (int i = 0; i < 8; ++i) { const int n = nh + i;
;                 if (n < n1) {
;                     int b, t, T; const bool samp = n >= NP;
;                     if (!samp) { b = n >> 11; t = n & 2047; T = SEQ; } else { const int s = n - NP; b = s >> 3; t = s & 7; T = ST; }
;                     const float cr = rr[i + 1], ck = kr[i + 1], cv = vr[i + 1];
;                     float qr = rr[i], qk = kr[i], qv = vr[i];
;                     if (t == 0) { qr = 0.f; qk = 0.f; qv = 0.f; if (samp) { qr = sshift[b * ASW + tid]; qk = sshift[b * ASW + 512 + tid]; qv = sshift[b * ASW + 1024 + tid]; } }
;     ...
;                     const float yc = cw0 * um2 + cw1 * um1 + cw2 * u0;
;                     MIX[(size_t)n * DM + 512 + tid] = (bf16_t)f2bf(bbv[i] * yc * silu(zbv[i]));
;                     if (t >= T - 2) { float* co = p.out + (samp ? O_CV_S + (size_t)((j * SB + b) * 2 + (t - (T - 2))) * 512 : O_CV_P + (size_t)((j * PB + b) * 2 + (t - (T - 2))) * 512); co[tid] = u0; }
.LBB0_1239:
	v_pk_mul_f32 v[82:83], v[68:69], v[78:79]
	v_lshlrev_b32_e32 v77, 16, v87
	v_fma_f32 v76, v103, v76, v83
	v_lshlrev_b32_e32 v87, 16, v88
	v_add_f32_e32 v76, v82, v76
	v_mul_f32_e32 v76, v76, v77
	v_mul_f32_e32 v77, 0xbfb8aa3b, v87
	v_exp_f32_e32 v77, v77
	s_nop 0
	v_add_f32_e32 v77, 1.0, v77
	v_div_scale_f32 v79, s[26:27], v77, v77, v87
	v_rcp_f32_e32 v82, v79
	s_lshl_b64 s[26:27], s[30:31], 11
	v_fma_f32 v83, -v79, v82, 1.0
	v_fmac_f32_e32 v82, v83, v82
	v_div_scale_f32 v83, vcc, v87, v77, v87
	v_mul_f32_e32 v88, v83, v82
	v_fma_f32 v91, -v79, v88, v83
	v_fmac_f32_e32 v88, v91, v82
	v_fma_f32 v79, -v79, v88, v83
	v_div_fmas_f32 v79, v79, v82, v88
	v_div_fixup_f32 v77, v79, v77, v87
	v_mul_f32_e32 v76, v77, v76
	v_bfe_u32 v77, v76, 16, 1
	v_add3_u32 v79, v76, v77, s6
	v_lshl_add_u64 v[76:77], v[72:73], 0, s[26:27]
	s_add_i32 s26, s68, -2
	s_cmp_lt_u32 s3, s26
	global_store_short_d16_hi v[76:77], v79, off
	s_cbranch_scc1 .LBB0_1241
	s_lshl_b32 s26, s69, 1
	s_and_b64 s[24:25], s[24:25], exec
	s_cselect_b32 s24, s34, s5
	s_mov_b32 s25, 0x4b82000
	s_cselect_b32 s96, s25, 0x4b92000
	s_sub_i32 s24, s24, s68
	s_add_i32 s3, s3, s24
	s_add_i32 s3, s3, s26
	s_add_i32 s24, s3, 2
	s_ashr_i32 s25, s24, 31
	s_lshl_b64 s[24:25], s[24:25], 11
	v_lshl_add_u64 v[76:77], v[74:75], 0, s[24:25]
	v_lshl_add_u64 v[76:77], v[76:77], 0, s[96:97]
	s_mov_b32 s96, 0x88888889
	global_store_dword v[76:77], v78, off
.LBB0_1241:
	s_xor_b64 s[24:25], s[12:13], -1
	s_cmp_ge_i32 s64, s33
	s_cbranch_scc1 .LBB0_1114
	s_add_i32 s3, s2, 0xffffc007
	s_lshr_b32 s31, s3, 3
	s_and_b32 s26, s64, 0x7ff
	s_cmpk_lt_i32 s2, 0x3ff9
	s_cselect_b64 s[2:3], -1, 0
	s_and_b64 s[12:13], s[2:3], exec
	v_readlane_b32 s12, v254, 42
	s_cselect_b32 s30, s26, s12
	s_cmp_lg_u32 s30, 0
	s_cselect_b64 s[42:43], -1, 0
	s_or_b64 s[12:13], s[2:3], s[42:43]
	s_and_b64 vcc, exec, s[12:13]
	s_cbranch_vccnz .LBB0_1244
	s_mul_i32 s26, s31, 0x680
	v_add_u32_e32 v76, s26, v64
	v_add_u32_e32 v82, s26, v104
	v_ashrrev_i32_e32 v77, 31, v76
	v_ashrrev_i32_e32 v83, 31, v82
	v_lshl_add_u64 v[76:77], v[76:77], 2, s[46:47]
	v_lshl_add_u64 v[82:83], v[82:83], 2, s[46:47]
	global_load_dword v76, v[76:77], off
	s_nop 0
	global_load_dword v77, v[82:83], off
	v_add_u32_e32 v82, s26, v66
	v_ashrrev_i32_e32 v83, 31, v82
	v_lshl_add_u64 v[82:83], v[82:83], 2, s[46:47]
	global_load_dword v83, v[82:83], off
	s_waitcnt vmcnt(0)
	s_branch .LBB0_1245

; __device__ __forceinline__ void even_prep(const Params& p, int j, LAS unsigned char* lds, const int wave_s) {
;     ...
;                     const float sr = cr + (qr - cr) * mu_r, sk = ck + (qk - ck) * mu_k, sv = cv + (qv - cv) * mu_v;
;                     const float wp = w0 + DW[(hh * 8 + i) * 64 + lane], ap = a0 + DA[(hh * 8 + i) * 64 + lane];
;                     const float xs = -wp;
;                     const float sp = xs > 20.f ? xs : __logf(1.f + __expf(xs));
;                     const float decay = __expf(-__expf(-sp - 0.5f));
;                     const float a = 1.f / (1.f + __expf(-ap));
;                     const float kk = sk * k_k;
;                     const float ss = wave_sum(kk * kk);
;                     const float kkn = kk * rsqrtf(fmaxf(ss, 1e-24f));
;                     const float kmod = sk * (1.f + (a - 1.f) * k_a);
;                     const float bon = wave_sum(sr * kmod * r_k);
;                     const size_t o = (size_t)n * 512 + tid;
;                     SR[o] = sr; SW[o] = decay; SK[o] = kmod; SV[o] = sv; SKK[o] = kkn; SBB[o] = kkn * a;
;                     if (lane == 0) BON[(size_t)n * 8 + wave] = bon;
.LBB0_1245:
	ds_read2st64_b32 v[86:87], v86 offset0:71 offset1:87
	v_lshlrev_b32_e32 v81, 16, v118
	v_lshlrev_b32_e32 v82, 16, v119
	v_sub_f32_e32 v76, v76, v81
	v_sub_f32_e32 v77, v77, v82
	s_waitcnt lgkmcnt(0)
	v_add_f32_e32 v86, v98, v86
	v_mul_f32_e32 v88, 0xbfb8aa3b, v86
	v_exp_f32_e32 v88, v88
	s_mov_b32 s26, 0x3f317217
	v_mov_b32_e32 v119, 0
	s_ashr_i32 s65, s64, 31
	v_add_f32_e32 v88, 1.0, v88
	v_cmp_gt_f32_e32 vcc, s15, v88
	v_lshlrev_b32_e32 v79, 16, v120
	v_sub_f32_e32 v83, v83, v79
	v_cndmask_b32_e64 v89, 0, 32, vcc
	v_ldexp_f32 v88, v88, v89
	v_log_f32_e32 v88, v88
	v_fma_f32 v89, v94, v76, v81
	v_fma_f32 v76, v95, v77, v82
	v_add_f32_e32 v77, v99, v87
	v_mul_f32_e32 v87, 0x3f317217, v88
	v_fma_f32 v87, v88, s26, -v87
	v_fmac_f32_e32 v87, 0x3377d1cf, v88
	s_mov_b32 s26, 0x7f800000
	v_fmac_f32_e32 v87, 0x3f317217, v88
	v_cmp_lt_f32_e64 s[44:45], |v88|, s26
	v_mul_f32_e32 v77, 0xbfb8aa3b, v77
	s_mov_b32 s26, 0xc1a00000
	v_cndmask_b32_e64 v87, v88, v87, s[44:45]
	v_cndmask_b32_e32 v88, 0, v222, vcc
	v_exp_f32_e32 v77, v77
	v_sub_f32_e32 v87, v87, v88
	v_cmp_gt_f32_e32 vcc, s26, v86
	v_fma_f32 v83, v96, v83, v79
	v_add_f32_e32 v77, 1.0, v77
	v_cndmask_b32_e64 v86, v87, -v86, vcc
	v_sub_f32_e32 v86, -0.5, v86
	v_mul_f32_e32 v86, 0x3fb8aa3b, v86
	v_exp_f32_e32 v86, v86
	v_div_scale_f32 v87, s[26:27], v77, v77, 1.0
	v_rcp_f32_e32 v88, v87
	v_mul_f32_e32 v86, 0xbfb8aa3b, v86
	v_exp_f32_e32 v90, v86
	v_fma_f32 v86, -v87, v88, 1.0
	v_fmac_f32_e32 v88, v86, v88
	v_div_scale_f32 v86, vcc, 1.0, v77, 1.0
	v_mul_f32_e32 v91, v86, v88
	v_fma_f32 v118, -v87, v91, v86
	v_fmac_f32_e32 v91, v118, v88
	v_fma_f32 v86, -v87, v91, v86
	v_mul_f32_e32 v87, v100, v76
	v_mul_f32_e32 v118, v87, v87
	v_div_fmas_f32 v86, v86, v88, v91
	v_div_fixup_f32 v88, v86, v77, 1.0
	v_mov_b32_dpp v118, v118 row_shr:1 row_mask:0xf bank_mask:0xf bound_ctrl:1
	v_fmac_f32_e32 v118, v87, v87
	v_add_f32_e32 v77, -1.0, v88
	v_fma_f32 v77, v101, v77, 1.0
	v_add_f32_dpp v118, v118, v118 row_shr:2 row_mask:0xf bank_mask:0xf bound_ctrl:1
	s_nop 1
	v_add_f32_dpp v118, v118, v118 row_shr:4 row_mask:0xf bank_mask:0xf bound_ctrl:1
	s_nop 1
	v_add_f32_dpp v118, v118, v118 row_shr:8 row_mask:0xf bank_mask:0xf bound_ctrl:1
	s_nop 1
	v_mov_b32_dpp v119, v118 row_bcast:15 row_mask:0xa bank_mask:0xf
	v_add_f32_e32 v118, v118, v119
	v_mov_b32_e32 v119, 0
	s_nop 1
	v_mov_b32_dpp v119, v118 row_bcast:31 row_mask:0xc bank_mask:0xf
	v_add_f32_e32 v118, v118, v119
	s_nop 0
	v_readlane_b32 s26, v118, 63
	s_nop 1
	v_max_f32_e64 v118, s26, s26
	v_max_f32_e32 v118, 0x179abe15, v118
	v_rsq_f32_e32 v118, v118
	s_lshl_b64 s[26:27], s[64:65], 9
	v_mul_f32_e32 v91, v87, v118
	v_mul_f32_e32 v118, v76, v77
	v_mul_f32_e32 v76, v89, v118
	v_mul_f32_e32 v77, v102, v76
	s_nop 1
	v_mov_b32_dpp v77, v77 row_shr:1 row_mask:0xf bank_mask:0xf bound_ctrl:1
	v_fmac_f32_e32 v77, v102, v76
	s_nop 1
	v_add_f32_dpp v76, v77, v77 row_shr:2 row_mask:0xf bank_mask:0xf bound_ctrl:1
	v_mov_b32_e32 v77, 0
	s_nop 0
	v_add_f32_dpp v76, v76, v76 row_shr:4 row_mask:0xf bank_mask:0xf bound_ctrl:1
	s_nop 1
	v_add_f32_dpp v76, v76, v76 row_shr:8 row_mask:0xf bank_mask:0xf bound_ctrl:1
	s_nop 1
	v_mov_b32_dpp v77, v76 row_bcast:15 row_mask:0xa bank_mask:0xf
	v_add_f32_e32 v76, v76, v77
	v_mov_b32_e32 v77, 0
	s_nop 1
	v_mov_b32_dpp v77, v76 row_bcast:31 row_mask:0xc bank_mask:0xf
	v_add_f32_e32 v76, v76, v77
	s_nop 0
	v_readlane_b32 s44, v76, 63
	v_lshl_add_u64 v[76:77], s[26:27], 0, v[64:65]
	v_lshlrev_b64 v[76:77], 2, v[76:77]
	v_lshl_add_u64 v[86:87], s[58:59], 0, v[76:77]
	global_store_dword v[86:87], v89, off
	v_lshl_add_u64 v[86:87], s[50:51], 0, v[76:77]
	global_store_dword v[86:87], v90, off
	v_lshl_add_u64 v[86:87], s[56:57], 0, v[76:77]
	global_store_dword v[86:87], v118, off
	v_lshl_add_u64 v[86:87], s[52:53], 0, v[76:77]
	global_store_dword v[86:87], v83, off
	v_lshl_add_u64 v[86:87], s[38:39], 0, v[76:77]
	v_mul_f32_e32 v83, v88, v91
	v_lshl_add_u64 v[76:77], s[54:55], 0, v[76:77]
	global_store_dword v[86:87], v91, off
	global_store_dword v[76:77], v83, off
	s_and_saveexec_b64 s[26:27], s[40:41]
	s_cbranch_execz .LBB0_1247
	s_lshl_b64 s[68:69], s[64:65], 5
	s_add_u32 s68, s17, s68
	s_addc_u32 s69, s83, s69
	v_mov_b32_e32 v76, s44
	global_store_dword v185, v76, s[68:69]

; __device__ __forceinline__ void even_prep(const Params& p, int j, LAS unsigned char* lds, const int wave_s) {
;     ...
;                     if (t < 1) um1 = samp ? sconv[(b * 2 + 1) * 512 + tid] : 0.f;
;                     if (t < 2) um2 = samp ? sconv[(b * 2 + t) * 512 + tid] : 0.f;
.LBB0_1251:
	s_xor_b64 s[12:13], s[12:13], -1
	s_andn2_b64 vcc, exec, s[12:13]
	s_cbranch_vccnz .LBB0_1253
	v_lshl_add_u32 v76, s31, 10, v104
	v_ashrrev_i32_e32 v77, 31, v76
	v_lshl_add_u64 v[76:77], v[76:77], 2, s[48:49]
	global_load_dword v77, v[76:77], off
	s_waitcnt vmcnt(0)
	s_branch .LBB0_1254

; __device__ __forceinline__ void even_prep(const Params& p, int j, LAS unsigned char* lds, const int wave_s) {
;     ...
;                     if (t < 1) um1 = samp ? sconv[(b * 2 + 1) * 512 + tid] : 0.f;
;                     if (t < 2) um2 = samp ? sconv[(b * 2 + t) * 512 + tid] : 0.f;
.LBB0_1254:
	s_cmp_gt_u32 s30, 1
	s_cselect_b64 s[42:43], -1, 0
	s_or_b64 s[12:13], s[2:3], s[42:43]
	s_and_b64 vcc, exec, s[12:13]
	s_cbranch_vccnz .LBB0_1256
	v_lshl_add_u32 v78, s31, 10, v115
	v_ashrrev_i32_e32 v79, 31, v78
	v_lshl_add_u64 v[78:79], v[78:79], 2, s[48:49]
	global_load_dword v78, v[78:79], off
	s_waitcnt vmcnt(0)
	s_branch .LBB0_1257

; __device__ __forceinline__ unsigned f2bf(float f) { unsigned u = __float_as_uint(f); return (u + 0x7fffu + ((u >> 16) & 1u)) >> 16; }
; __device__ __forceinline__ float silu(float x) { return x / (1.f + __expf(-x)); }
; __device__ __forceinline__ void even_prep(const Params& p, int j, LAS unsigned char* lds, const int wave_s) {
;     ...
;                     const float yc = cw0 * um2 + cw1 * um1 + cw2 * u0;
;                     MIX[(size_t)n * DM + 512 + tid] = (bf16_t)f2bf(bbv[i] * yc * silu(zbv[i]));
;                     if (t >= T - 2) { float* co = p.out + (samp ? O_CV_S + (size_t)((j * SB + b) * 2 + (t - (T - 2))) * 512 : O_CV_P + (size_t)((j * PB + b) * 2 + (t - (T - 2))) * 512); co[tid] = u0; }
.LBB0_1257:
	v_lshlrev_b32_e32 v76, 16, v116
	v_lshlrev_b32_e32 v79, 16, v117
	v_mul_f32_e32 v76, v76, v79
	v_lshlrev_b32_e32 v82, 16, v85
	v_pk_mul_f32 v[80:81], v[68:69], v[76:77]
	v_lshlrev_b32_e32 v79, 16, v84
	v_fma_f32 v77, v103, v78, v81
	v_mul_f32_e32 v78, 0xbfb8aa3b, v82
	v_exp_f32_e32 v78, v78
	v_add_f32_e32 v77, v80, v77
	v_mul_f32_e32 v77, v77, v79
	v_add_f32_e32 v78, 1.0, v78
	v_div_scale_f32 v79, s[12:13], v78, v78, v82
	v_rcp_f32_e32 v80, v79
	s_lshl_b64 s[12:13], s[64:65], 11
	v_fma_f32 v81, -v79, v80, 1.0
	v_fmac_f32_e32 v80, v81, v80
	v_div_scale_f32 v81, vcc, v82, v78, v82
	v_mul_f32_e32 v83, v81, v80
	v_fma_f32 v84, -v79, v83, v81
	v_fmac_f32_e32 v83, v84, v80
	v_fma_f32 v79, -v79, v83, v81
	v_div_fmas_f32 v79, v79, v80, v83
	v_div_fixup_f32 v78, v79, v78, v82
	v_mul_f32_e32 v77, v78, v77
	v_bfe_u32 v78, v77, 16, 1
	v_add3_u32 v77, v77, v78, s6
	v_lshl_add_u64 v[78:79], v[72:73], 0, s[12:13]
	s_add_i32 s12, s44, -2
	s_cmp_lt_u32 s30, s12
	global_store_short_d16_hi v[78:79], v77, off
	s_cbranch_scc1 .LBB0_1114
	s_lshl_b32 s12, s45, 1
	s_and_b64 s[2:3], s[2:3], exec
	s_cselect_b32 s2, s34, s5
	s_mov_b32 s3, 0x4b82000
	s_cselect_b32 s96, s3, 0x4b92000
	s_sub_i32 s2, s2, s44
	s_add_i32 s2, s30, s2
	s_add_i32 s2, s2, s12
	s_add_i32 s2, s2, 2
	s_ashr_i32 s3, s2, 31
	s_lshl_b64 s[2:3], s[2:3], 11
	v_lshl_add_u64 v[78:79], v[74:75], 0, s[2:3]
	v_lshl_add_u64 v[78:79], v[78:79], 0, s[96:97]
	s_mov_b32 s96, 0x88888889
	global_store_dword v[78:79], v76, off
	s_branch .LBB0_1114

; #define LAS __attribute__((address_space(3)))
; __device__ __forceinline__ void swap16_(float& a, float& b) { asm volatile("s_nop 1\n\tv_permlane16_swap_b32 %0, %1" : "+v"(a), "+v"(b)); }
; __device__ __forceinline__ void swap32_(float& a, float& b) { asm volatile("s_nop 1\n\tv_permlane32_swap_b32 %0, %1" : "+v"(a), "+v"(b)); }
; __device__ __forceinline__ void even_scan(const Params& p, int j, LAS unsigned char* lds, int gw, int NGW, int wave, int lane) {
;     ...
;             for (int s = 0; s < TS; ++s) {
;                 const LAS float* sb = bb + s * 384 + cq * 16;
;                 f32x4 cbuf[CPS];
; #pragma unroll
;                 for (int c = 0; c < CPS; ++c) { const int li = cli + c * NGW * 64;
;                     if (li < KVC_N2 && ((li >> 8) & 2047) >= 8) cbuf[c] = __builtin_nontemporal_load(csrc + c * NGW * 64); }
;                 float saL[4], saP[4];
; #pragma unroll
;                 for (int rr = 0; rr < 4; ++rr) { saL[rr] = 0.f; saP[rr] = 0.f; }
; #pragma unroll
;                 for (int c = 0; c < 16; c += 4) { const f32x4 k4 = *(const LAS f32x4*)(sb + c);
; #pragma unroll
;                     for (int rr = 0; rr < 4; ++rr)
; #pragma unroll
;                         for (int e = 0; e < 4; ++e) { saL[rr] = fnma_s(SL[rr][c + e], k4[e], saL[rr]); saP[rr] = fnma_s(SP[rr][c + e], k4[e], saP[rr]); } }
;                 float vv[4];
; #pragma unroll
;                 for (int rr = 0; rr < 4; ++rr) { vv[rr] = bb[s * 384 + 320 + i16 + 16 * rr];
;                 }
;                 {
;                     float a = saL[0], b = saL[1], c = saL[2], d = saL[3]; swap16_(a, b); swap16_(c, d); float s01 = a + b, s23 = c + d; swap32_(s01, s23); const float T = s01 + s23;
;                     float u = T, w = T; swap16_(u, w); float x0 = u, x2 = u, x1 = w, x3 = w; swap32_(x0, x2); swap32_(x1, x3); saL[0] = x0; saL[1] = x1; saL[2] = x2; saL[3] = x3;
;                 }
;                 {
;                     float a = saP[0], b = saP[1], c = saP[2], d = saP[3]; swap16_(a, b); swap16_(c, d); float s01 = a + b, s23 = c + d; swap32_(s01, s23); const float T = s01 + s23;
;                     float u = T, w = T; swap16_(u, w); float x0 = u, x2 = u, x1 = w, x3 = w; swap32_(x0, x2); swap32_(x1, x3); saP[0] = x0; saP[1] = x1; saP[2] = x2; saP[3] = x3;
;                 }
.LBB0_1335:
	s_or_b64 exec, exec, s[24:25]
	ds_read_b128 v[168:171], v234
	ds_read_b128 v[172:175], v234 offset:16
	ds_read_b128 v[164:167], v234 offset:32
	ds_read_b128 v[160:163], v234 offset:48
	ds_read2_b32 v[218:219], v184 offset1:16
	ds_read2_b32 v[216:217], v184 offset0:32 offset1:48
	s_waitcnt lgkmcnt(5)
	v_fma_f32 v176, -v80, v168, v185
	v_fma_f32 v177, -v132, v168, v185
	v_fma_f32 v178, -v52, v168, v185
	v_fma_f32 v179, -v116, v168, v185
	v_fma_f32 v180, -v36, v168, v185
	v_fma_f32 v181, -v100, v168, v185
	v_fma_f32 v176, -v81, v169, v176
	v_fma_f32 v182, -v16, v168, v185
	v_fma_f32 v168, -v84, v168, v185
	v_fma_f32 v177, -v133, v169, v177
	v_fma_f32 v178, -v53, v169, v178
	v_fma_f32 v179, -v117, v169, v179
	v_fma_f32 v176, -v82, v170, v176
	v_fma_f32 v180, -v37, v169, v180
	v_fma_f32 v181, -v101, v169, v181
	v_fma_f32 v168, -v85, v169, v168
	v_fma_f32 v177, -v134, v170, v177
	v_fma_f32 v178, -v54, v170, v178
	v_fma_f32 v176, -v83, v171, v176
	v_fma_f32 v179, -v118, v170, v179
	v_fma_f32 v180, -v38, v170, v180
	v_fma_f32 v181, -v102, v170, v181
	v_fma_f32 v182, -v17, v169, v182
	v_fma_f32 v168, -v86, v170, v168
	v_fma_f32 v177, -v135, v171, v177
	v_fma_f32 v178, -v55, v171, v178
	v_fma_f32 v179, -v119, v171, v179
	v_fma_f32 v180, -v39, v171, v180
	v_fma_f32 v169, -v18, v170, v182
	s_waitcnt lgkmcnt(4)
	v_fma_f32 v170, -v68, v172, v176
	v_fma_f32 v181, -v103, v171, v181
	v_fma_f32 v168, -v87, v171, v168
	v_fma_f32 v176, -v48, v172, v178
	v_fma_f32 v178, -v32, v172, v180
	v_fma_f32 v169, -v19, v171, v169
	v_fma_f32 v171, -v128, v172, v177
	v_fma_f32 v170, -v69, v173, v170
	v_fma_f32 v177, -v112, v172, v179
	v_fma_f32 v176, -v49, v173, v176
	v_fma_f32 v179, -v96, v172, v181
	v_fma_f32 v169, -v12, v172, v169
	v_fma_f32 v171, -v129, v173, v171
	v_fma_f32 v170, -v70, v174, v170
	v_fma_f32 v178, -v33, v173, v178
	v_fma_f32 v168, -v76, v172, v168
	v_fma_f32 v177, -v113, v173, v177
	v_fma_f32 v169, -v13, v173, v169
	v_fma_f32 v171, -v130, v174, v171
	v_fma_f32 v170, -v71, v175, v170
	v_fma_f32 v176, -v50, v174, v176
	v_fma_f32 v179, -v97, v173, v179
	v_fma_f32 v178, -v34, v174, v178
	v_fma_f32 v168, -v77, v173, v168
	v_fma_f32 v171, -v131, v175, v171
	v_fma_f32 v169, -v14, v174, v169
	s_waitcnt lgkmcnt(3)
	v_fma_f32 v170, -v60, v164, v170
	v_fma_f32 v177, -v114, v174, v177
	v_fma_f32 v176, -v51, v175, v176
	v_fma_f32 v179, -v98, v174, v179
	v_fma_f32 v178, -v35, v175, v178
	v_fma_f32 v168, -v78, v174, v168
	v_fma_f32 v169, -v15, v175, v169
	v_fma_f32 v171, -v124, v164, v171
	v_fma_f32 v170, -v61, v165, v170
	v_fma_f32 v172, -v44, v164, v176
	v_fma_f32 v174, -v28, v164, v178
	v_fma_f32 v177, -v115, v175, v177
	v_fma_f32 v179, -v99, v175, v179
	v_fma_f32 v168, -v79, v175, v168
	v_fma_f32 v171, -v125, v165, v171
	v_fma_f32 v170, -v62, v166, v170
	v_fma_f32 v172, -v45, v165, v172
	v_fma_f32 v173, -v108, v164, v177
	v_fma_f32 v175, -v92, v164, v179
	v_fma_f32 v174, -v29, v165, v174
	v_fma_f32 v169, -v8, v164, v169
	v_fma_f32 v164, -v72, v164, v168
	v_fma_f32 v171, -v126, v166, v171
	v_fma_f32 v170, -v63, v167, v170
	v_fma_f32 v173, -v109, v165, v173
	v_fma_f32 v172, -v46, v166, v172
	v_fma_f32 v175, -v93, v165, v175
	v_fma_f32 v174, -v30, v166, v174
	v_fma_f32 v168, -v9, v165, v169
	v_fma_f32 v164, -v73, v165, v164
	v_fma_f32 v171, -v127, v167, v171
	v_fma_f32 v173, -v110, v166, v173
	v_fma_f32 v172, -v47, v167, v172
	v_fma_f32 v175, -v94, v166, v175
	v_fma_f32 v165, -v10, v166, v168
	v_fma_f32 v174, -v31, v167, v174
	v_fma_f32 v164, -v74, v166, v164
	s_waitcnt lgkmcnt(2)
	v_fma_f32 v166, -v56, v160, v170
	v_fma_f32 v168, -v40, v160, v172
	v_fma_f32 v173, -v111, v167, v173
	v_fma_f32 v165, -v11, v167, v165
	v_fma_f32 v170, -v24, v160, v174
	v_fma_f32 v175, -v95, v167, v175
	v_fma_f32 v164, -v75, v167, v164
	v_fma_f32 v167, -v120, v160, v171
	v_fma_f32 v166, -v57, v161, v166
	v_fma_f32 v169, -v104, v160, v173
	v_fma_f32 v168, -v41, v161, v168
	v_fma_f32 v171, -v88, v160, v175
	v_fma_f32 v170, -v25, v161, v170
	v_fma_f32 v165, -v20, v160, v165
	v_fma_f32 v160, -v64, v160, v164
	v_fma_f32 v167, -v121, v161, v167
	v_fma_f32 v166, -v58, v162, v166
	v_fma_f32 v169, -v105, v161, v169
	v_fma_f32 v168, -v42, v162, v168
	v_fma_f32 v171, -v89, v161, v171
	v_fma_f32 v170, -v26, v162, v170
	v_fma_f32 v164, -v21, v161, v165
	v_fma_f32 v160, -v65, v161, v160
	v_fma_f32 v166, -v59, v163, v166
	v_fma_f32 v168, -v43, v163, v168
	v_fma_f32 v167, -v122, v162, v167
	v_fma_f32 v170, -v27, v163, v170
	v_fma_f32 v161, -v22, v162, v164
	v_fma_f32 v169, -v106, v162, v169
	v_fma_f32 v171, -v90, v162, v171
	s_nop 0
	s_nop 1
	v_permlane16_swap_b32 v166, v168
	v_fma_f32 v160, -v66, v162, v160
	v_fma_f32 v167, -v123, v163, v167
	v_fma_f32 v161, -v23, v163, v161
	v_fma_f32 v169, -v107, v163, v169
	v_fma_f32 v171, -v91, v163, v171
	s_nop 0
	v_add_f32_e32 v162, v166, v168
	s_nop 1
	v_permlane16_swap_b32 v170, v161
	v_fma_f32 v160, -v67, v163, v160
	s_nop 0
	v_add_f32_e32 v161, v170, v161
	s_nop 1
	v_permlane32_swap_b32 v162, v161
	s_nop 0
	v_add_f32_e32 v242, v162, v161
	v_mov_b32_e32 v240, v242
	s_nop 1
	v_permlane16_swap_b32 v242, v240
	s_nop 0
	v_mov_b32_e32 v238, v242
	v_mov_b32_e32 v236, v240
	s_nop 1
	v_permlane32_swap_b32 v242, v238
	s_nop 1
	v_permlane32_swap_b32 v240, v236
	s_nop 1
	v_permlane16_swap_b32 v167, v169
	s_nop 1
	v_permlane16_swap_b32 v171, v160
	s_nop 0
	v_add_f32_e32 v161, v167, v169
	v_add_f32_e32 v160, v171, v160
	s_nop 1
	v_permlane32_swap_b32 v161, v160
	s_nop 0
	v_add_f32_e32 v243, v161, v160
	v_mov_b32_e32 v241, v243
	s_nop 1
	v_permlane16_swap_b32 v243, v241
	s_nop 0
	v_mov_b32_e32 v239, v243
	v_mov_b32_e32 v237, v241
	s_nop 1
	v_permlane32_swap_b32 v243, v239
	s_nop 1
	v_permlane32_swap_b32 v241, v237
	ds_read_b128 v[172:175], v234 offset:512
	ds_read_b128 v[176:179], v234 offset:768
	ds_read_b128 v[180:183], v234 offset:1024
	s_waitcnt lgkmcnt(2)
; #define LAS __attribute__((address_space(3)))
; __device__ __forceinline__ float fma_s(float a, float b, float c) { float d; asm("v_fma_f32 %0, %1, %2, %3" : "=v"(d) : "v"(a), "v"(b), "v"(c)); return d; }
; __device__ __forceinline__ float mul_s(float a, float b) { float d; asm("v_mul_f32 %0, %1, %2" : "=v"(d) : "v"(a), "v"(b)); return d; }
; __device__ __forceinline__ void even_scan(const Params& p, int j, LAS unsigned char* lds, int gw, int NGW, int wave, int lane) {
;     ...
; #pragma unroll
;                 for (int c = 0; c < 16; c += 4) {
;                     const f32x4 w4 = *(const LAS f32x4*)(sb + 64 + c), b4 = *(const LAS f32x4*)(sb + 128 + c), k4 = *(const LAS f32x4*)(sb + 192 + c), r4 = *(const LAS f32x4*)(sb + 256 + c);
; #pragma unroll
;                     for (int rr = 0; rr < 4; ++rr)
; #pragma unroll
;                         for (int e = 0; e < 4; ++e) {
;                             float tL = mul_s(saL[rr], b4[e]); tL = fma_s(vv[rr], k4[e], tL); SL[rr][c + e] = fma_s(SL[rr][c + e], w4[e], tL); yL[rr] = fma_s(SL[rr][c + e], r4[e], yL[rr]);
;                             const float tP = mul_s(saP[rr], b4[e]); SP[rr][c + e] = fma_s(SP[rr][c + e], w4[e], tP); yP[rr] = fma_s(SP[rr][c + e], r4[e], yP[rr]); }
;                 }
	v_mul_f32 v160, v242, v172
	s_waitcnt lgkmcnt(1)
	v_fma_f32 v190, v218, v176, v160
	ds_read_b128 v[186:189], v234 offset:256
	ds_read_b128 v[168:171], v234 offset:272
	ds_read_b128 v[164:167], v234 offset:288
	ds_read_b128 v[160:163], v234 offset:304
	v_mul_f32 v244, v242, v173
	v_mul_f32 v191, v243, v172
	v_mul_f32 v245, v240, v173
	s_waitcnt lgkmcnt(3)
	v_fma_f32 v80, v80, v186, v190
	v_fma_f32 v244, v218, v177, v244
	v_fma_f32 v132, v132, v186, v191
	v_fma_f32 v245, v219, v177, v245
	v_fma_f32 v190, v80, v180, v185
	v_fma_f32 v81, v81, v187, v244
	v_mul_f32 v244, v243, v173
	v_fma_f32 v191, v132, v180, v185
	v_fma_f32 v53, v53, v187, v245
	v_mul_f32 v245, v241, v173
	v_fma_f32 v133, v133, v187, v244
	v_mul_f32 v244, v242, v174
	v_fma_f32 v117, v117, v187, v245
	v_mul_f32 v245, v240, v174
	v_fma_f32 v190, v81, v181, v190
	v_fma_f32 v244, v218, v178, v244
	v_fma_f32 v191, v133, v181, v191
	v_fma_f32 v245, v219, v178, v245
	v_fma_f32 v82, v82, v188, v244
	v_mul_f32 v244, v243, v174
	v_fma_f32 v54, v54, v188, v245
	v_mul_f32 v245, v241, v174
	v_fma_f32 v134, v134, v188, v244
	v_mul_f32 v244, v242, v175
	v_fma_f32 v118, v118, v188, v245
	v_mul_f32 v245, v240, v175
	v_fma_f32 v190, v82, v182, v190
	v_fma_f32 v191, v134, v182, v191
	v_fma_f32 v244, v218, v179, v244
	v_fma_f32 v245, v219, v179, v245
	v_fma_f32 v83, v83, v189, v244
	v_mul_f32 v244, v243, v175
	v_fma_f32 v55, v55, v189, v245
	v_mul_f32 v245, v238, v173
	v_fma_f32 v135, v135, v189, v244
	v_fma_f32 v245, v216, v177, v245
	v_mul_f32 v244, v241, v172
	v_fma_f32 v190, v83, v183, v190
	v_fma_f32 v250, v135, v183, v191
	v_mul_f32 v191, v240, v172
	v_fma_f32 v37, v37, v187, v245
	v_mul_f32 v245, v239, v173
	v_fma_f32 v116, v116, v186, v244
	v_fma_f32 v191, v219, v176, v191
	v_fma_f32 v101, v101, v187, v245
	v_mul_f32 v245, v238, v174
	v_fma_f32 v244, v116, v180, v185
	v_fma_f32 v52, v52, v186, v191
	v_fma_f32 v245, v216, v178, v245
	v_fma_f32 v244, v117, v181, v244
	v_fma_f32 v191, v52, v180, v185
	v_fma_f32 v38, v38, v188, v245
	v_mul_f32 v245, v239, v174
	v_fma_f32 v244, v118, v182, v244
	v_fma_f32 v191, v53, v181, v191
	v_fma_f32 v102, v102, v188, v245
	v_mul_f32 v245, v238, v175
	v_fma_f32 v191, v54, v182, v191
	v_fma_f32 v245, v216, v179, v245
	v_fma_f32 v249, v55, v183, v191
	v_mul_f32 v191, v241, v175
	v_fma_f32 v39, v39, v189, v245
	v_fma_f32 v119, v119, v189, v191
	v_mul_f32 v191, v238, v172
	v_fma_f32 v191, v216, v176, v191
	v_fma_f32 v248, v119, v183, v244
	v_mul_f32 v244, v239, v172
	v_fma_f32 v36, v36, v186, v191
	v_fma_f32 v100, v100, v186, v244
	v_fma_f32 v191, v36, v180, v185
	v_fma_f32 v244, v100, v180, v185
	v_fma_f32 v191, v37, v181, v191
	v_fma_f32 v244, v101, v181, v244
	v_fma_f32 v191, v38, v182, v191
	v_fma_f32 v244, v102, v182, v244
	v_fma_f32 v247, v39, v183, v191
	v_mul_f32 v191, v239, v175
	v_fma_f32 v103, v103, v189, v191
	v_mul_f32 v191, v236, v172
	v_mul_f32 v172, v237, v172
	v_fma_f32 v176, v217, v176, v191
	v_fma_f32 v84, v84, v186, v172
	v_fma_f32 v246, v103, v183, v244
	v_fma_f32 v16, v16, v186, v176
	v_fma_f32 v172, v84, v180, v185
	v_fma_f32 v176, v16, v180, v185
	v_mul_f32 v180, v236, v173
	v_mul_f32 v173, v237, v173
	v_fma_f32 v85, v85, v187, v173
	v_mul_f32 v173, v236, v174
	v_mul_f32 v174, v237, v174
	v_fma_f32 v177, v217, v177, v180
	v_fma_f32 v173, v217, v178, v173
	v_fma_f32 v17, v17, v187, v177
	v_fma_f32 v172, v85, v181, v172
	v_fma_f32 v86, v86, v188, v174
	v_mul_f32 v174, v236, v175
	v_fma_f32 v176, v17, v181, v176
	v_fma_f32 v18, v18, v188, v173
	v_fma_f32 v172, v86, v182, v172
	v_fma_f32 v174, v217, v179, v174
	v_fma_f32 v173, v18, v182, v176
	v_fma_f32 v19, v19, v189, v174
	v_fma_f32 v245, v19, v183, v173
	v_mul_f32 v173, v237, v175
	v_fma_f32 v87, v87, v189, v173
	v_fma_f32 v244, v87, v183, v172
	ds_read_b128 v[172:175], v234 offset:528
	ds_read_b128 v[176:179], v234 offset:784
	ds_read_b128 v[180:183], v234 offset:1040
	s_waitcnt lgkmcnt(2)
	v_mul_f32 v188, v242, v173
	s_waitcnt lgkmcnt(1)
	v_fma_f32 v188, v218, v177, v188
	v_mul_f32 v186, v242, v172
	v_mul_f32 v187, v243, v172
	v_fma_f32 v69, v69, v169, v188
	v_mul_f32 v188, v243, v173
	v_fma_f32 v186, v218, v176, v186
	v_fma_f32 v128, v128, v168, v187
	v_fma_f32 v129, v129, v169, v188
	v_mul_f32 v188, v242, v174
	v_fma_f32 v68, v68, v168, v186
	s_waitcnt lgkmcnt(0)
; #define LAS __attribute__((address_space(3)))
; __device__ __forceinline__ float fma_s(float a, float b, float c) { float d; asm("v_fma_f32 %0, %1, %2, %3" : "=v"(d) : "v"(a), "v"(b), "v"(c)); return d; }
; __device__ __forceinline__ float mul_s(float a, float b) { float d; asm("v_mul_f32 %0, %1, %2" : "=v"(d) : "v"(a), "v"(b)); return d; }
; __device__ __forceinline__ void even_scan(const Params& p, int j, LAS unsigned char* lds, int gw, int NGW, int wave, int lane) {
;     ...
; #pragma unroll
;                 for (int c = 0; c < 16; c += 4) {
;                     const f32x4 w4 = *(const LAS f32x4*)(sb + 64 + c), b4 = *(const LAS f32x4*)(sb + 128 + c), k4 = *(const LAS f32x4*)(sb + 192 + c), r4 = *(const LAS f32x4*)(sb + 256 + c);
; #pragma unroll
;                     for (int rr = 0; rr < 4; ++rr)
; #pragma unroll
;                         for (int e = 0; e < 4; ++e) {
;                             float tL = mul_s(saL[rr], b4[e]); tL = fma_s(vv[rr], k4[e], tL); SL[rr][c + e] = fma_s(SL[rr][c + e], w4[e], tL); yL[rr] = fma_s(SL[rr][c + e], r4[e], yL[rr]);
;                             const float tP = mul_s(saP[rr], b4[e]); SP[rr][c + e] = fma_s(SP[rr][c + e], w4[e], tP); yP[rr] = fma_s(SP[rr][c + e], r4[e], yP[rr]); }
;                 }
	v_fma_f32 v187, v128, v180, v250
	v_fma_f32 v188, v218, v178, v188
	v_fma_f32 v186, v68, v180, v190
	v_fma_f32 v187, v129, v181, v187
	v_fma_f32 v70, v70, v170, v188
	v_mul_f32 v188, v243, v174
	v_fma_f32 v186, v69, v181, v186
	v_fma_f32 v130, v130, v170, v188
	v_mul_f32 v188, v242, v175
	v_fma_f32 v186, v70, v182, v186
	v_fma_f32 v188, v218, v179, v188
	v_fma_f32 v187, v130, v182, v187
	v_fma_f32 v71, v71, v171, v188
	v_mul_f32 v188, v240, v173
	v_fma_f32 v188, v219, v177, v188
	v_fma_f32 v190, v71, v183, v186
	v_mul_f32 v186, v243, v175
	v_fma_f32 v49, v49, v169, v188
	v_mul_f32 v188, v241, v173
	v_fma_f32 v131, v131, v171, v186
	v_mul_f32 v186, v240, v172
	v_fma_f32 v113, v113, v169, v188
	v_mul_f32 v188, v240, v174
	v_fma_f32 v186, v219, v176, v186
	v_fma_f32 v191, v131, v183, v187
	v_mul_f32 v187, v241, v172
	v_fma_f32 v188, v219, v178, v188
	v_fma_f32 v48, v48, v168, v186
	v_fma_f32 v112, v112, v168, v187
	v_fma_f32 v50, v50, v170, v188
	v_mul_f32 v188, v241, v174
	v_fma_f32 v186, v48, v180, v249
	v_fma_f32 v187, v112, v180, v248
	v_fma_f32 v114, v114, v170, v188
	v_mul_f32 v188, v240, v175
	v_fma_f32 v186, v49, v181, v186
	v_fma_f32 v187, v113, v181, v187
	v_fma_f32 v188, v219, v179, v188
	v_fma_f32 v186, v50, v182, v186
	v_fma_f32 v187, v114, v182, v187
	v_fma_f32 v51, v51, v171, v188
	v_mul_f32 v188, v238, v173
	v_fma_f32 v248, v51, v183, v186
	v_mul_f32 v186, v241, v175
	v_fma_f32 v188, v216, v177, v188
	v_fma_f32 v115, v115, v171, v186
	v_mul_f32 v186, v238, v172
	v_fma_f32 v33, v33, v169, v188
	v_mul_f32 v188, v239, v173
	v_fma_f32 v186, v216, v176, v186
	v_fma_f32 v97, v97, v169, v188
	v_mul_f32 v188, v238, v174
	v_fma_f32 v249, v115, v183, v187
	v_mul_f32 v187, v239, v172
	v_fma_f32 v32, v32, v168, v186
	v_fma_f32 v188, v216, v178, v188
	v_fma_f32 v96, v96, v168, v187
	v_fma_f32 v186, v32, v180, v247
	v_fma_f32 v34, v34, v170, v188
	v_mul_f32 v188, v239, v174
	v_fma_f32 v187, v96, v180, v246
	v_fma_f32 v186, v33, v181, v186
	v_fma_f32 v98, v98, v170, v188
	v_mul_f32 v188, v238, v175
	v_fma_f32 v187, v97, v181, v187
	v_fma_f32 v186, v34, v182, v186
	v_fma_f32 v188, v216, v179, v188
	v_fma_f32 v187, v98, v182, v187
	v_fma_f32 v35, v35, v171, v188
	v_fma_f32 v246, v35, v183, v186
	v_mul_f32 v186, v239, v175
	v_fma_f32 v99, v99, v171, v186
	v_mul_f32 v186, v236, v172
	v_mul_f32 v172, v237, v172
	v_fma_f32 v76, v76, v168, v172
	v_mul_f32 v172, v236, v173
	v_fma_f32 v176, v217, v176, v186
	v_mul_f32 v173, v237, v173
	v_fma_f32 v247, v99, v183, v187
	v_fma_f32 v172, v217, v177, v172
	v_fma_f32 v77, v77, v169, v173
	v_fma_f32 v12, v12, v168, v176
	v_fma_f32 v168, v76, v180, v244
	v_fma_f32 v13, v13, v169, v172
	v_mul_f32 v169, v236, v174
	v_fma_f32 v176, v12, v180, v245
	v_fma_f32 v168, v77, v181, v168
	v_fma_f32 v172, v13, v181, v176
	v_fma_f32 v169, v217, v178, v169
	v_fma_f32 v14, v14, v170, v169
	v_fma_f32 v169, v14, v182, v172
	v_mul_f32 v172, v237, v174
	v_fma_f32 v78, v78, v170, v172
	v_mul_f32 v170, v236, v175
	v_fma_f32 v168, v78, v182, v168
	v_fma_f32 v170, v217, v179, v170
	v_fma_f32 v15, v15, v171, v170
	v_fma_f32 v176, v15, v183, v169
	v_mul_f32 v169, v237, v175
	v_fma_f32 v79, v79, v171, v169
	v_fma_f32 v177, v79, v183, v168
	ds_read_b128 v[168:171], v234 offset:544
	ds_read_b128 v[172:175], v234 offset:800
	ds_read_b128 v[186:189], v234 offset:1056
	s_waitcnt lgkmcnt(2)
	v_mul_f32 v180, v242, v169
	s_waitcnt lgkmcnt(1)
	v_fma_f32 v180, v218, v173, v180
	v_mul_f32 v178, v242, v168
	v_mul_f32 v179, v243, v168
	v_fma_f32 v61, v61, v165, v180
	v_mul_f32 v180, v243, v169
	v_fma_f32 v178, v218, v172, v178
	v_fma_f32 v124, v124, v164, v179
	v_fma_f32 v125, v125, v165, v180
	v_mul_f32 v180, v242, v170
	v_fma_f32 v60, v60, v164, v178
	s_waitcnt lgkmcnt(0)
	v_fma_f32 v179, v124, v186, v191
	v_fma_f32 v180, v218, v174, v180
	v_fma_f32 v178, v60, v186, v190
	v_fma_f32 v179, v125, v187, v179
	v_mul_f32 v190, v238, v169
	v_fma_f32 v62, v62, v166, v180
	v_mul_f32 v180, v243, v170
	v_fma_f32 v178, v61, v187, v178
	v_fma_f32 v190, v216, v173, v190
	v_fma_f32 v126, v126, v166, v180
	v_mul_f32 v180, v242, v171
	v_fma_f32 v178, v62, v188, v178
	v_fma_f32 v29, v29, v165, v190
	v_mul_f32 v190, v239, v169
	v_fma_f32 v180, v218, v175, v180
	v_fma_f32 v179, v126, v188, v179
	v_fma_f32 v93, v93, v165, v190
	v_mul_f32 v190, v238, v170
	v_fma_f32 v63, v63, v167, v180
	v_mul_f32 v180, v240, v169
	v_fma_f32 v190, v216, v174, v190
	v_fma_f32 v183, v63, v189, v178
	v_mul_f32 v178, v243, v171
	v_fma_f32 v180, v219, v173, v180
	v_fma_f32 v30, v30, v166, v190
	v_mul_f32 v190, v239, v170
	v_fma_f32 v127, v127, v167, v178
	v_mul_f32 v178, v240, v168
	v_fma_f32 v45, v45, v165, v180
	v_mul_f32 v180, v241, v169
	v_fma_f32 v94, v94, v166, v190
	v_fma_f32 v178, v219, v172, v178
	v_fma_f32 v109, v109, v165, v180
	v_mul_f32 v180, v240, v170
	v_fma_f32 v182, v127, v189, v179
	v_mul_f32 v179, v241, v168
	v_fma_f32 v44, v44, v164, v178
	v_fma_f32 v180, v219, v174, v180
	v_fma_f32 v108, v108, v164, v179
	v_fma_f32 v178, v44, v186, v248
	v_fma_f32 v179, v108, v186, v249
	v_fma_f32 v46, v46, v166, v180
	v_mul_f32 v180, v241, v170
	v_fma_f32 v178, v45, v187, v178
	v_fma_f32 v179, v109, v187, v179
	v_fma_f32 v110, v110, v166, v180
	v_mul_f32 v180, v240, v171
	v_fma_f32 v178, v46, v188, v178
	v_fma_f32 v179, v110, v188, v179
	v_fma_f32 v180, v219, v175, v180
	v_fma_f32 v47, v47, v167, v180
	v_fma_f32 v181, v47, v189, v178
	v_mul_f32 v178, v241, v171
	v_fma_f32 v111, v111, v167, v178
	v_mul_f32 v178, v238, v168
	v_fma_f32 v180, v111, v189, v179
	v_mul_f32 v179, v239, v168
	v_fma_f32 v178, v216, v172, v178
	v_fma_f32 v92, v92, v164, v179
	v_fma_f32 v28, v28, v164, v178
; #define LAS __attribute__((address_space(3)))
; __device__ __forceinline__ void swap16_(float& a, float& b) { asm volatile("s_nop 1\n\tv_permlane16_swap_b32 %0, %1" : "+v"(a), "+v"(b)); }
; __device__ __forceinline__ void swap32_(float& a, float& b) { asm volatile("s_nop 1\n\tv_permlane32_swap_b32 %0, %1" : "+v"(a), "+v"(b)); }
; __device__ __forceinline__ float fma_s(float a, float b, float c) { float d; asm("v_fma_f32 %0, %1, %2, %3" : "=v"(d) : "v"(a), "v"(b), "v"(c)); return d; }
; __device__ __forceinline__ float mul_s(float a, float b) { float d; asm("v_mul_f32 %0, %1, %2" : "=v"(d) : "v"(a), "v"(b)); return d; }
; __device__ __forceinline__ void even_scan(const Params& p, int j, LAS unsigned char* lds, int gw, int NGW, int wave, int lane) {
;     ...
;                 for (int c = 0; c < 16; c += 4) {
;                     const f32x4 w4 = *(const LAS f32x4*)(sb + 64 + c), b4 = *(const LAS f32x4*)(sb + 128 + c), k4 = *(const LAS f32x4*)(sb + 192 + c), r4 = *(const LAS f32x4*)(sb + 256 + c);
; #pragma unroll
;                     for (int rr = 0; rr < 4; ++rr)
; #pragma unroll
;                         for (int e = 0; e < 4; ++e) {
;                             float tL = mul_s(saL[rr], b4[e]); tL = fma_s(vv[rr], k4[e], tL); SL[rr][c + e] = fma_s(SL[rr][c + e], w4[e], tL); yL[rr] = fma_s(SL[rr][c + e], r4[e], yL[rr]);
;                             const float tP = mul_s(saP[rr], b4[e]); SP[rr][c + e] = fma_s(SP[rr][c + e], w4[e], tP); yP[rr] = fma_s(SP[rr][c + e], r4[e], yP[rr]); }
;                 }
;                 float yoL, yoP;
;                 { float a = yL[0], b = yL[1], c = yL[2], d = yL[3]; swap16_(a, b); swap16_(c, d); float s01 = a + b, s23 = c + d; swap32_(s01, s23); yoL = s01 + s23; }
;                 { float a = yP[0], b = yP[1], c = yP[2], d = yP[3]; swap16_(a, b); swap16_(c, d); float s01 = a + b, s23 = c + d; swap32_(s01, s23); yoP = s01 + s23; }
;                 const size_t oo = base + (size_t)(st * TS + s) * 512 + lane;
;                 YL[oo] = yoL; if (!samp) QQ[oo] = yoP;
; #pragma unroll
;                 for (int c = 0; c < CPS; ++c) { const int li = cli + c * NGW * 64;
;                     if (li < KVC_N2 && ((li >> 8) & 2047) >= 8) __builtin_nontemporal_store(cbuf[c], (f32x4*)((char*)(csrc + c * NGW * 64) + cdelta)); }
	v_fma_f32 v179, v92, v186, v247
	v_fma_f32 v178, v28, v186, v246
	v_fma_f32 v179, v93, v187, v179
	v_fma_f32 v178, v29, v187, v178
	v_fma_f32 v190, v94, v188, v179
	v_mul_f32 v179, v238, v171
	v_fma_f32 v178, v30, v188, v178
	v_fma_f32 v179, v216, v175, v179
	v_fma_f32 v31, v31, v167, v179
	v_fma_f32 v179, v31, v189, v178
	v_mul_f32 v178, v239, v171
	v_fma_f32 v95, v95, v167, v178
	v_fma_f32 v178, v95, v189, v190
	v_mul_f32 v190, v236, v168
	v_mul_f32 v168, v237, v168
	v_fma_f32 v72, v72, v164, v168
	v_mul_f32 v168, v236, v169
	v_fma_f32 v172, v217, v172, v190
	v_mul_f32 v169, v237, v169
	v_fma_f32 v168, v217, v173, v168
	v_fma_f32 v73, v73, v165, v169
	v_fma_f32 v8, v8, v164, v172
	v_fma_f32 v164, v72, v186, v177
	v_fma_f32 v9, v9, v165, v168
	v_mul_f32 v165, v236, v170
	v_fma_f32 v172, v8, v186, v176
	v_fma_f32 v164, v73, v187, v164
	v_fma_f32 v168, v9, v187, v172
	v_fma_f32 v165, v217, v174, v165
	v_fma_f32 v10, v10, v166, v165
	v_fma_f32 v165, v10, v188, v168
	v_mul_f32 v168, v237, v170
	v_fma_f32 v74, v74, v166, v168
	v_mul_f32 v166, v236, v171
	v_fma_f32 v164, v74, v188, v164
	v_fma_f32 v166, v217, v175, v166
	v_fma_f32 v11, v11, v167, v166
	v_fma_f32 v177, v11, v189, v165
	v_mul_f32 v165, v237, v171
	v_fma_f32 v75, v75, v167, v165
	v_fma_f32 v176, v75, v189, v164
	ds_read_b128 v[164:167], v234 offset:560
	ds_read_b128 v[172:175], v234 offset:816
	ds_read_b128 v[168:171], v234 offset:1072
	s_waitcnt lgkmcnt(2)
	v_mul_f32 v186, v242, v164
	s_waitcnt lgkmcnt(1)
	v_fma_f32 v186, v218, v172, v186
	v_fma_f32 v56, v56, v160, v186
	v_mul_f32 v186, v243, v164
	v_fma_f32 v120, v120, v160, v186
	v_mul_f32 v186, v242, v165
	s_waitcnt lgkmcnt(0)
	v_fma_f32 v183, v56, v168, v183
	v_fma_f32 v186, v218, v173, v186
	v_fma_f32 v182, v120, v168, v182
	v_fma_f32 v57, v57, v161, v186
	v_mul_f32 v186, v243, v165
	v_fma_f32 v121, v121, v161, v186
	v_mul_f32 v186, v242, v166
	v_fma_f32 v183, v57, v169, v183
	v_fma_f32 v186, v218, v174, v186
	v_fma_f32 v182, v121, v169, v182
	v_fma_f32 v58, v58, v162, v186
	v_mul_f32 v186, v243, v166
	v_fma_f32 v122, v122, v162, v186
	v_mul_f32 v186, v242, v167
	v_fma_f32 v183, v58, v170, v183
	v_fma_f32 v186, v218, v175, v186
	v_fma_f32 v182, v122, v170, v182
	v_fma_f32 v59, v59, v163, v186
	v_mul_f32 v186, v243, v167
	v_fma_f32 v123, v123, v163, v186
	v_mul_f32 v186, v240, v164
	v_fma_f32 v183, v59, v171, v183
	v_fma_f32 v186, v219, v172, v186
	v_fma_f32 v182, v123, v171, v182
	v_fma_f32 v40, v40, v160, v186
	v_mul_f32 v186, v241, v164
	v_fma_f32 v104, v104, v160, v186
	v_mul_f32 v186, v240, v165
	v_fma_f32 v181, v40, v168, v181
	v_fma_f32 v186, v219, v173, v186
	v_fma_f32 v180, v104, v168, v180
	v_fma_f32 v41, v41, v161, v186
	v_mul_f32 v186, v241, v165
	v_fma_f32 v105, v105, v161, v186
	v_mul_f32 v186, v240, v166
	v_fma_f32 v181, v41, v169, v181
	v_fma_f32 v186, v219, v174, v186
	v_fma_f32 v180, v105, v169, v180
	v_fma_f32 v42, v42, v162, v186
	v_mul_f32 v186, v241, v166
	v_fma_f32 v106, v106, v162, v186
	v_mul_f32 v186, v240, v167
	v_fma_f32 v181, v42, v170, v181
	v_fma_f32 v186, v219, v175, v186
	v_fma_f32 v180, v106, v170, v180
	v_fma_f32 v43, v43, v163, v186
	v_mul_f32 v186, v241, v167
	v_fma_f32 v107, v107, v163, v186
	v_mul_f32 v186, v238, v164
	v_fma_f32 v181, v43, v171, v181
	v_fma_f32 v186, v216, v172, v186
	s_nop 1
	v_permlane16_swap_b32 v183, v181
	v_fma_f32 v180, v107, v171, v180
	v_fma_f32 v24, v24, v160, v186
	v_mul_f32 v186, v239, v164
	v_fma_f32 v88, v88, v160, v186
	v_mul_f32 v186, v238, v165
	v_fma_f32 v179, v24, v168, v179
	v_fma_f32 v186, v216, v173, v186
	v_fma_f32 v178, v88, v168, v178
	v_fma_f32 v25, v25, v161, v186
	v_mul_f32 v186, v239, v165
	v_fma_f32 v89, v89, v161, v186
	v_mul_f32 v186, v238, v166
	v_fma_f32 v179, v25, v169, v179
	v_fma_f32 v186, v216, v174, v186
	v_fma_f32 v178, v89, v169, v178
	v_fma_f32 v26, v26, v162, v186
	v_mul_f32 v186, v239, v166
	v_fma_f32 v90, v90, v162, v186
	v_mul_f32 v186, v238, v167
	v_fma_f32 v179, v26, v170, v179
	v_fma_f32 v186, v216, v175, v186
	v_fma_f32 v178, v90, v170, v178
	v_fma_f32 v27, v27, v163, v186
	v_mul_f32 v186, v239, v167
	v_fma_f32 v91, v91, v163, v186
	v_mul_f32 v186, v236, v164
	v_mul_f32 v164, v237, v164
	v_fma_f32 v179, v27, v171, v179
	v_fma_f32 v64, v64, v160, v164
	v_mul_f32 v164, v236, v165
	v_fma_f32 v172, v217, v172, v186
	v_mul_f32 v165, v237, v165
	v_fma_f32 v178, v91, v171, v178
	v_fma_f32 v164, v217, v173, v164
	v_fma_f32 v65, v65, v161, v165
	v_fma_f32 v20, v20, v160, v172
	v_fma_f32 v160, v64, v168, v176
	v_fma_f32 v21, v21, v161, v164
	v_mul_f32 v161, v236, v166
	v_fma_f32 v172, v20, v168, v177
	v_fma_f32 v160, v65, v169, v160
	v_fma_f32 v164, v21, v169, v172
	v_fma_f32 v161, v217, v174, v161
	v_fma_f32 v22, v22, v162, v161
	v_fma_f32 v161, v22, v170, v164
	v_mul_f32 v164, v237, v166
	v_fma_f32 v66, v66, v162, v164
	v_mul_f32 v162, v236, v167
	v_fma_f32 v162, v217, v175, v162
	v_fma_f32 v160, v66, v170, v160
	v_fma_f32 v23, v23, v163, v162
	v_mul_f32 v162, v237, v167
	v_fma_f32 v161, v23, v171, v161
	v_fma_f32 v67, v67, v163, v162
	s_nop 0
	s_nop 1
	v_permlane16_swap_b32 v179, v161
	v_fma_f32 v162, v67, v171, v160
	v_add_f32_e32 v160, v183, v181
	v_add_f32_e32 v161, v179, v161
	s_nop 1
	v_permlane32_swap_b32 v160, v161
	s_nop 1
	v_permlane16_swap_b32 v182, v180
	s_nop 1
	v_permlane16_swap_b32 v178, v162
	s_nop 0
	v_add_f32_e32 v164, v160, v161
	v_add_f32_e32 v161, v178, v162
	s_waitcnt vmcnt(0)
	s_and_saveexec_b64 s[24:25], s[26:27]
	s_cbranch_execz .Lscan_sta_skip
	v_lshl_add_u64 v[236:237], v[212:213], 0, s[12:13]
	global_store_dwordx4 v[236:237], v[4:7], off nt
.Lscan_sta_skip:
	s_or_b64 exec, exec, s[24:25]
	s_and_saveexec_b64 s[24:25], s[30:31]
	s_cbranch_execz .Lscan_stb_skip
	v_lshl_add_u64 v[236:237], v[214:215], 0, s[12:13]
	global_store_dwordx4 v[236:237], v[0:3], off nt
.Lscan_stb_skip:
	s_or_b64 exec, exec, s[24:25]
	v_lshl_add_u64 v[162:163], v[206:207], 0, s[38:39]
	v_add_co_u32_e32 v162, vcc, 0x37500000, v162
	v_add_f32_e32 v160, v182, v180
	s_nop 0
	v_addc_co_u32_e32 v163, vcc, 0, v163, vcc
	s_nop 1
	v_permlane32_swap_b32 v160, v161
	global_store_dword v[162:163], v164, off
	v_cndmask_b32_e64 v162, 0, 1, s[62:63]
	v_cmp_ne_u32_e64 s[36:37], 1, v162
	s_andn2_b64 vcc, exec, s[62:63]
	s_cbranch_vccz .LBB0_1338
	s_branch .LBB0_1330
.LBB0_1338:
	v_add_f32_e32 v162, v160, v161
	v_lshl_add_u64 v[160:161], v[208:209], 0, s[38:39]
	global_store_dword v[160:161], v162, off
	s_branch .LBB0_1330

; __device__ __forceinline__ float bf2f(bf16_t h) { return __uint_as_float(((unsigned)h) << 16); }
; __device__ __forceinline__ void even_fixup(const Params& p, int j, LAS unsigned char* lds, int gw, int NGW, int wave, int lane) {
;     ...
;             for (int r = 0; r < 4; ++r) { const size_t n = (size_t)(nb + tt * 16 + g4 * 4 + r); bon[r] = BON[n * 8 + h];
; #pragma unroll
;                 for (int it = 0; it < 4; ++it) { const int ch = h * 64 + it * 16 + fr; yl[r][it] = YL[n * 512 + ch]; vv[r][it] = SV[n * 512 + ch]; za[r][it] = bf2f(P[n * EINP + ASW + ch]); } }
.LBB0_1501:
	v_add_u32_e32 v84, s13, v16
	v_ashrrev_i32_e32 v85, 31, v84
	v_lshlrev_b64 v[0:1], 5, v[84:85]
	v_lshl_add_u64 v[0:1], s[44:45], 0, v[0:1]
	global_load_dword v193, v[0:1], off
	v_lshlrev_b64 v[0:1], 9, v[84:85]
	v_or_b32_e32 v2, v0, v54
	v_mov_b32_e32 v3, v1
	v_lshlrev_b64 v[2:3], 2, v[2:3]
	v_lshl_add_u64 v[4:5], s[28:29], 0, v[2:3]
	v_lshl_add_u64 v[2:3], s[40:41], 0, v[2:3]
	global_load_dword v86, v[4:5], off
	global_load_dword v199, v[2:3], off
	v_mad_i64_i32 v[2:3], s[24:25], v84, s7, v[64:65]
	global_load_ushort v207, v[2:3], off offset:3328
	v_mov_b32_e32 v5, v1
	v_add_u32_e32 v78, 1, v84
	v_ashrrev_i32_e32 v79, 31, v78
	v_add_u32_e32 v72, 2, v84
	v_ashrrev_i32_e32 v73, 31, v72
	v_add_u32_e32 v66, 3, v84
	v_ashrrev_i32_e32 v67, 31, v66
	v_add_u32_e32 v190, v162, v16
	s_mov_b32 s0, 0x3a27c5ac
	v_lshlrev_b64 v[84:85], 11, v[84:85]
	v_lshl_add_u64 v[84:85], v[56:57], 0, v[84:85]
	s_add_i32 s17, s17, -1
	s_add_i32 s13, s13, 16
	v_add_u32_e32 v162, 0x1000, v162
	s_cmp_eq_u32 s17, 0
	v_or_b32_e32 v4, v0, v58
	v_lshlrev_b64 v[4:5], 2, v[4:5]
	v_lshl_add_u64 v[6:7], s[28:29], 0, v[4:5]
	v_lshl_add_u64 v[4:5], s[40:41], 0, v[4:5]
	global_load_dword v88, v[6:7], off
	global_load_dword v200, v[4:5], off
	s_nop 0
	global_load_ushort v206, v[2:3], off offset:3360
	v_mov_b32_e32 v5, v1
	v_or_b32_e32 v4, v0, v60
	v_lshlrev_b64 v[4:5], 2, v[4:5]
	v_lshl_add_u64 v[6:7], s[28:29], 0, v[4:5]
	v_lshl_add_u64 v[4:5], s[40:41], 0, v[4:5]
	global_load_dword v87, v[6:7], off
	global_load_dword v201, v[4:5], off
	s_nop 0
	global_load_ushort v205, v[2:3], off offset:3392
	v_or_b32_e32 v0, v0, v62
	v_lshlrev_b64 v[0:1], 2, v[0:1]
	v_lshl_add_u64 v[4:5], s[28:29], 0, v[0:1]
	v_lshl_add_u64 v[0:1], s[40:41], 0, v[0:1]
	global_load_dword v89, v[4:5], off
	global_load_dword v202, v[0:1], off
	s_nop 0
	global_load_ushort v204, v[2:3], off offset:3424
	v_lshlrev_b64 v[0:1], 5, v[78:79]
	v_lshl_add_u64 v[0:1], s[44:45], 0, v[0:1]
	global_load_dword v180, v[0:1], off
	v_lshlrev_b64 v[0:1], 9, v[78:79]
	v_or_b32_e32 v2, v0, v54
	v_mov_b32_e32 v3, v1
	v_lshlrev_b64 v[2:3], 2, v[2:3]
	v_lshl_add_u64 v[4:5], s[28:29], 0, v[2:3]
	v_lshl_add_u64 v[2:3], s[40:41], 0, v[2:3]
	global_load_dword v80, v[4:5], off
	global_load_dword v203, v[2:3], off
	v_mad_i64_i32 v[2:3], s[24:25], v78, s7, v[64:65]
	global_load_ushort v196, v[2:3], off offset:3328
	v_mov_b32_e32 v5, v1
	v_or_b32_e32 v4, v0, v58
	v_lshlrev_b64 v[4:5], 2, v[4:5]
	v_lshl_add_u64 v[6:7], s[28:29], 0, v[4:5]
	v_lshl_add_u64 v[4:5], s[40:41], 0, v[4:5]
	global_load_dword v82, v[6:7], off
	global_load_dword v198, v[4:5], off
	s_nop 0
	global_load_ushort v194, v[2:3], off offset:3360
	v_mov_b32_e32 v5, v1
	v_or_b32_e32 v4, v0, v60
	v_lshlrev_b64 v[4:5], 2, v[4:5]
	v_lshl_add_u64 v[6:7], s[28:29], 0, v[4:5]
	v_lshl_add_u64 v[4:5], s[40:41], 0, v[4:5]
	global_load_dword v81, v[6:7], off
	global_load_dword v195, v[4:5], off
	s_nop 0
	global_load_ushort v192, v[2:3], off offset:3392
	v_or_b32_e32 v0, v0, v62
	v_lshlrev_b64 v[0:1], 2, v[0:1]
	v_lshl_add_u64 v[4:5], s[28:29], 0, v[0:1]
	v_lshl_add_u64 v[0:1], s[40:41], 0, v[0:1]
	global_load_dword v83, v[4:5], off
	global_load_dword v183, v[0:1], off
	s_nop 0
	global_load_ushort v182, v[2:3], off offset:3424
	v_lshlrev_b64 v[0:1], 5, v[72:73]
	v_lshl_add_u64 v[0:1], s[44:45], 0, v[0:1]
	global_load_dword v171, v[0:1], off
	v_lshlrev_b64 v[0:1], 9, v[72:73]
	v_or_b32_e32 v2, v0, v54
	v_mov_b32_e32 v3, v1
	v_lshlrev_b64 v[2:3], 2, v[2:3]
	v_lshl_add_u64 v[4:5], s[28:29], 0, v[2:3]
	v_lshl_add_u64 v[2:3], s[40:41], 0, v[2:3]
	global_load_dword v74, v[4:5], off
	global_load_dword v172, v[2:3], off
	v_mad_i64_i32 v[2:3], s[24:25], v72, s7, v[64:65]
	global_load_ushort v181, v[2:3], off offset:3328
	v_mov_b32_e32 v5, v1
	v_or_b32_e32 v4, v0, v58
	v_lshlrev_b64 v[4:5], 2, v[4:5]
	v_lshl_add_u64 v[6:7], s[28:29], 0, v[4:5]
	v_lshl_add_u64 v[4:5], s[40:41], 0, v[4:5]
	global_load_dword v76, v[6:7], off
	global_load_dword v173, v[4:5], off
	s_nop 0
	global_load_ushort v179, v[2:3], off offset:3360
	v_mov_b32_e32 v5, v1
	v_or_b32_e32 v4, v0, v60
	v_lshlrev_b64 v[4:5], 2, v[4:5]
	v_lshl_add_u64 v[6:7], s[28:29], 0, v[4:5]
	v_lshl_add_u64 v[4:5], s[40:41], 0, v[4:5]
	global_load_dword v75, v[6:7], off
	global_load_dword v174, v[4:5], off
	s_nop 0
	global_load_ushort v178, v[2:3], off offset:3392
	v_or_b32_e32 v0, v0, v62
	v_lshlrev_b64 v[0:1], 2, v[0:1]
	v_lshl_add_u64 v[4:5], s[28:29], 0, v[0:1]
	v_lshl_add_u64 v[0:1], s[40:41], 0, v[0:1]
	global_load_dword v77, v[4:5], off
	global_load_dword v175, v[0:1], off
	s_nop 0
	global_load_ushort v177, v[2:3], off offset:3424
	v_lshlrev_b64 v[0:1], 5, v[66:67]
	v_lshl_add_u64 v[0:1], s[44:45], 0, v[0:1]
	global_load_dword v164, v[0:1], off
	v_lshlrev_b64 v[0:1], 9, v[66:67]
	v_or_b32_e32 v2, v0, v54
	v_mov_b32_e32 v3, v1
	v_lshlrev_b64 v[2:3], 2, v[2:3]
	v_lshl_add_u64 v[4:5], s[28:29], 0, v[2:3]
	v_lshl_add_u64 v[2:3], s[40:41], 0, v[2:3]
	global_load_dword v68, v[4:5], off
	global_load_dword v176, v[2:3], off
	v_mad_i64_i32 v[2:3], s[24:25], v66, s7, v[64:65]
	global_load_ushort v169, v[2:3], off offset:3328
	v_mov_b32_e32 v5, v1
	v_or_b32_e32 v4, v0, v58
	v_lshlrev_b64 v[4:5], 2, v[4:5]
	v_lshl_add_u64 v[6:7], s[28:29], 0, v[4:5]
	v_lshl_add_u64 v[4:5], s[40:41], 0, v[4:5]
	global_load_dword v70, v[6:7], off
	global_load_dword v170, v[4:5], off
	s_nop 0
	global_load_ushort v167, v[2:3], off offset:3360
	v_mov_b32_e32 v5, v1
	v_or_b32_e32 v4, v0, v60
	v_lshlrev_b64 v[4:5], 2, v[4:5]
	v_lshl_add_u64 v[6:7], s[28:29], 0, v[4:5]
	v_lshl_add_u64 v[4:5], s[40:41], 0, v[4:5]
	global_load_dword v69, v[6:7], off
	global_load_dword v168, v[4:5], off
	s_nop 0
	global_load_ushort v166, v[2:3], off offset:3392
	v_or_b32_e32 v0, v0, v62
	v_lshlrev_b64 v[0:1], 2, v[0:1]
	v_lshl_add_u64 v[4:5], s[28:29], 0, v[0:1]
	v_lshl_add_u64 v[0:1], s[40:41], 0, v[0:1]
	global_load_dword v71, v[4:5], off
	global_load_dword v165, v[0:1], off
	s_nop 0
	global_load_ushort v163, v[2:3], off offset:3424
	ds_read2_b32 v[186:187], v190 offset1:4
	ds_read2_b32 v[188:189], v190 offset0:8 offset1:12
	s_waitcnt lgkmcnt(1)
; __device__ __forceinline__ void even_fixup(const Params& p, int j, LAS unsigned char* lds, int gw, int NGW, int wave, int lane) {
;     ...
;             for (int kk = 0; kk < 16; ++kk) { const float av = qb[(tt * 16 + fr) * 64 + kk * 4 + g4];
; #pragma unroll
;                 for (int it = 0; it < 4; ++it) acc[it] = __builtin_amdgcn_mfma_f32_16x16x4f32(av, Sb[it][kk], acc[it], 0, 0, 0); }
; #pragma unroll
;             for (int r = 0; r < 4; ++r) {
;                 float y[4];
; #pragma unroll
;                 for (int it = 0; it < 4; ++it) y[it] = acc[it][r] + yl[r][it];
;                 const float mean = row16_sum((y[0] + y[1]) + (y[2] + y[3])) * (1.f / 64.f);
; #pragma unroll
;                 for (int it = 0; it < 4; ++it) y[it] -= mean;
	v_mfma_f32_16x16x4_f32 v[4:7], v186, v110, 0
	v_mfma_f32_16x16x4_f32 v[0:3], v186, v92, 0
	v_mfma_f32_16x16x4_f32 v[8:11], v186, v128, 0
	v_mfma_f32_16x16x4_f32 v[12:15], v186, v146, 0
	v_mfma_f32_16x16x4_f32 v[0:3], v187, v93, v[0:3]
	v_mfma_f32_16x16x4_f32 v[4:7], v187, v111, v[4:7]
	v_mfma_f32_16x16x4_f32 v[8:11], v187, v129, v[8:11]
	v_mfma_f32_16x16x4_f32 v[12:15], v187, v147, v[12:15]
	ds_read2_b32 v[186:187], v190 offset0:16 offset1:20
	s_waitcnt lgkmcnt(1)
	v_mfma_f32_16x16x4_f32 v[0:3], v188, v94, v[0:3]
	v_mfma_f32_16x16x4_f32 v[4:7], v188, v112, v[4:7]
	v_mfma_f32_16x16x4_f32 v[8:11], v188, v130, v[8:11]
	v_mfma_f32_16x16x4_f32 v[12:15], v188, v148, v[12:15]
	v_mfma_f32_16x16x4_f32 v[0:3], v189, v95, v[0:3]
	v_mfma_f32_16x16x4_f32 v[4:7], v189, v113, v[4:7]
	v_mfma_f32_16x16x4_f32 v[8:11], v189, v131, v[8:11]
	v_mfma_f32_16x16x4_f32 v[12:15], v189, v149, v[12:15]
	s_waitcnt lgkmcnt(0)
	v_mfma_f32_16x16x4_f32 v[0:3], v186, v96, v[0:3]
	v_mfma_f32_16x16x4_f32 v[4:7], v186, v114, v[4:7]
	v_mfma_f32_16x16x4_f32 v[8:11], v186, v132, v[8:11]
	v_mfma_f32_16x16x4_f32 v[12:15], v186, v150, v[12:15]
	v_mfma_f32_16x16x4_f32 v[0:3], v187, v97, v[0:3]
	v_mfma_f32_16x16x4_f32 v[4:7], v187, v115, v[4:7]
	v_mfma_f32_16x16x4_f32 v[8:11], v187, v133, v[8:11]
	v_mfma_f32_16x16x4_f32 v[12:15], v187, v151, v[12:15]
	ds_read2_b32 v[186:187], v190 offset0:24 offset1:28
	s_waitcnt lgkmcnt(0)
	v_mfma_f32_16x16x4_f32 v[0:3], v186, v98, v[0:3]
	v_mfma_f32_16x16x4_f32 v[4:7], v186, v116, v[4:7]
	v_mfma_f32_16x16x4_f32 v[8:11], v186, v134, v[8:11]
	v_mfma_f32_16x16x4_f32 v[12:15], v186, v152, v[12:15]
	v_mfma_f32_16x16x4_f32 v[0:3], v187, v99, v[0:3]
	v_mfma_f32_16x16x4_f32 v[4:7], v187, v117, v[4:7]
	v_mfma_f32_16x16x4_f32 v[8:11], v187, v135, v[8:11]
	v_mfma_f32_16x16x4_f32 v[12:15], v187, v153, v[12:15]
	ds_read2_b32 v[186:187], v190 offset0:32 offset1:36
	s_waitcnt lgkmcnt(0)
	v_mfma_f32_16x16x4_f32 v[0:3], v186, v100, v[0:3]
	v_mfma_f32_16x16x4_f32 v[4:7], v186, v118, v[4:7]
	v_mfma_f32_16x16x4_f32 v[8:11], v186, v136, v[8:11]
	v_mfma_f32_16x16x4_f32 v[12:15], v186, v154, v[12:15]
	v_mfma_f32_16x16x4_f32 v[0:3], v187, v101, v[0:3]
	v_mfma_f32_16x16x4_f32 v[4:7], v187, v119, v[4:7]
	v_mfma_f32_16x16x4_f32 v[8:11], v187, v137, v[8:11]
	v_mfma_f32_16x16x4_f32 v[12:15], v187, v155, v[12:15]
	ds_read2_b32 v[186:187], v190 offset0:40 offset1:44
	s_waitcnt lgkmcnt(0)
	v_mfma_f32_16x16x4_f32 v[0:3], v186, v102, v[0:3]
	v_mfma_f32_16x16x4_f32 v[4:7], v186, v120, v[4:7]
	v_mfma_f32_16x16x4_f32 v[8:11], v186, v138, v[8:11]
	v_mfma_f32_16x16x4_f32 v[12:15], v186, v156, v[12:15]
	v_mfma_f32_16x16x4_f32 v[0:3], v187, v103, v[0:3]
	v_mfma_f32_16x16x4_f32 v[4:7], v187, v121, v[4:7]
	v_mfma_f32_16x16x4_f32 v[8:11], v187, v139, v[8:11]
	v_mfma_f32_16x16x4_f32 v[12:15], v187, v157, v[12:15]
	ds_read2_b32 v[186:187], v190 offset0:48 offset1:52
	ds_read2_b32 v[190:191], v190 offset0:56 offset1:60
	s_waitcnt lgkmcnt(1)
	v_mfma_f32_16x16x4_f32 v[0:3], v186, v104, v[0:3]
	v_mfma_f32_16x16x4_f32 v[8:11], v186, v140, v[8:11]
	v_mfma_f32_16x16x4_f32 v[4:7], v186, v122, v[4:7]
	v_mfma_f32_16x16x4_f32 v[12:15], v186, v158, v[12:15]
	v_mfma_f32_16x16x4_f32 v[0:3], v187, v105, v[0:3]
	v_mfma_f32_16x16x4_f32 v[8:11], v187, v141, v[8:11]
	v_mfma_f32_16x16x4_f32 v[4:7], v187, v123, v[4:7]
	v_mfma_f32_16x16x4_f32 v[12:15], v187, v159, v[12:15]
	s_waitcnt lgkmcnt(0)
	v_mfma_f32_16x16x4_f32 v[0:3], v190, v106, v[0:3]
	v_mfma_f32_16x16x4_f32 v[8:11], v190, v142, v[8:11]
	v_mfma_f32_16x16x4_f32 v[186:189], v190, v124, v[4:7]
	v_mfma_f32_16x16x4_f32 v[208:211], v190, v160, v[12:15]
	v_mfma_f32_16x16x4_f32 v[4:7], v191, v107, v[0:3]
	v_mfma_f32_16x16x4_f32 v[12:15], v191, v143, v[8:11]
	v_mfma_f32_16x16x4_f32 v[0:3], v191, v125, v[186:189]
	s_nop 7
	s_waitcnt vmcnt(0)
	v_lshlrev_b32_e32 v207, 16, v207
	v_lshlrev_b32_e32 v206, 16, v206
	v_lshlrev_b32_e32 v205, 16, v205
	v_lshlrev_b32_e32 v204, 16, v204
	v_lshlrev_b32_e32 v196, 16, v196
	v_lshlrev_b32_e32 v194, 16, v194
	v_lshlrev_b32_e32 v192, 16, v192
	v_lshlrev_b32_e32 v182, 16, v182
	v_lshlrev_b32_e32 v181, 16, v181
	v_lshlrev_b32_e32 v179, 16, v179
	v_lshlrev_b32_e32 v178, 16, v178
	v_lshlrev_b32_e32 v177, 16, v177
	v_lshlrev_b32_e32 v169, 16, v169
	v_lshlrev_b32_e32 v167, 16, v167
	v_lshlrev_b32_e32 v166, 16, v166
	v_lshlrev_b32_e32 v163, 16, v163
	v_mov_b32_e32 v186, v4
	v_mov_b32_e32 v187, v12
	v_add_f32_e64 v86, v86, v186
	v_add_f32_e64 v87, v87, v187
	v_mfma_f32_16x16x4_f32 v[8:11], v191, v161, v[208:211]
	v_mov_b32_e32 v186, v0
	s_nop 8
	v_mov_b32_e32 v187, v8
	v_pk_add_f32 v[186:187], v[88:89], v[186:187]
	s_nop 0
	v_pk_add_f32 v[88:89], v[86:87], v[186:187]
	s_nop 0
	v_add_f32_e32 v0, v88, v89
	s_nop 1
	v_add_f32_dpp v0, v0, v0 row_ror:8 row_mask:0xf bank_mask:0xf bound_ctrl:1
	s_nop 1
	v_add_f32_dpp v0, v0, v0 row_ror:4 row_mask:0xf bank_mask:0xf bound_ctrl:1
	s_nop 1
	v_add_f32_dpp v0, v0, v0 row_ror:2 row_mask:0xf bank_mask:0xf bound_ctrl:1
	s_nop 1
	v_add_f32_dpp v0, v0, v0 row_ror:1 row_mask:0xf bank_mask:0xf bound_ctrl:1
	v_mul_f32_e32 v0, 0x3c800000, v0
	v_pk_add_f32 v[88:89], v[86:87], v[0:1] op_sel_hi:[1,0] neg_lo:[0,1] neg_hi:[0,1]
	v_pk_add_f32 v[86:87], v[186:187], v[0:1] op_sel_hi:[1,0] neg_lo:[0,1] neg_hi:[0,1]
	v_mul_f32_e32 v0, 0xbfb8aa3b, v207
	v_exp_f32_e32 v0, v0
	v_pk_mul_f32 v[186:187], v[86:87], v[86:87]
	v_add_f32_e32 v0, 1.0, v0
	v_div_scale_f32 v4, s[24:25], v0, v0, v207
	v_rcp_f32_e32 v8, v4
	v_pk_fma_f32 v[186:187], v[88:89], v[88:89], v[186:187]
	v_fma_f32 v12, -v4, v8, 1.0
	v_fmac_f32_e32 v8, v12, v8
	v_div_scale_f32 v12, vcc, v207, v0, v207
	v_mul_f32_e32 v188, v12, v8
	v_fma_f32 v189, -v4, v188, v12
; __device__ __forceinline__ unsigned f2bf(float f) { unsigned u = __float_as_uint(f); return (u + 0x7fffu + ((u >> 16) & 1u)) >> 16; }
; __device__ __forceinline__ float silu(float x) { return x / (1.f + __expf(-x)); }
; __device__ __forceinline__ void even_fixup(const Params& p, int j, LAS unsigned char* lds, int gw, int NGW, int wave, int lane) {
;     ...
;                 const float mean = row16_sum((y[0] + y[1]) + (y[2] + y[3])) * (1.f / 64.f);
; #pragma unroll
;                 for (int it = 0; it < 4; ++it) y[it] -= mean;
;                 const float var = row16_sum((y[0] * y[0] + y[1] * y[1]) + (y[2] * y[2] + y[3] * y[3])) * (1.f / 64.f);
;                 const float rs = rsqrtf(var + 64e-5f);
;                 const size_t n = (size_t)(nb + tt * 16 + g4 * 4 + r);
; #pragma unroll
;                 for (int it = 0; it < 4; ++it) { const float yn = y[it] * rs * gg[it] + gb[it] + bon[r] * vv[r][it];
;                     MIX[n * DM + h * 64 + it * 16 + fr] = (bf16_t)f2bf(yn * silu(za[r][it])); }
	v_fmac_f32_e32 v188, v189, v8
	v_fma_f32 v4, -v4, v188, v12
	v_div_fmas_f32 v4, v4, v8, v188
	v_div_fixup_f32 v190, v4, v0, v207
	v_mul_f32_e32 v0, 0xbfb8aa3b, v206
	v_exp_f32_e32 v0, v0
	s_nop 0
	v_add_f32_e32 v0, 1.0, v0
	v_div_scale_f32 v4, s[24:25], v0, v0, v206
	v_rcp_f32_e32 v8, v4
	s_nop 0
	v_fma_f32 v12, -v4, v8, 1.0
	v_fmac_f32_e32 v8, v12, v8
	v_div_scale_f32 v12, vcc, v206, v0, v206
	v_mul_f32_e32 v188, v12, v8
	v_fma_f32 v189, -v4, v188, v12
	v_fmac_f32_e32 v188, v189, v8
	v_fma_f32 v4, -v4, v188, v12
	v_div_fmas_f32 v4, v4, v8, v188
	v_div_fixup_f32 v191, v4, v0, v206
	v_mul_f32_e32 v0, 0xbfb8aa3b, v205
	v_exp_f32_e32 v0, v0
	s_nop 0
	v_add_f32_e32 v0, 1.0, v0
	v_div_scale_f32 v4, s[24:25], v0, v0, v205
	v_rcp_f32_e32 v8, v4
	s_nop 0
	v_fma_f32 v12, -v4, v8, 1.0
	v_fmac_f32_e32 v8, v12, v8
	v_div_scale_f32 v12, vcc, v205, v0, v205
	v_mul_f32_e32 v188, v12, v8
	v_fma_f32 v189, -v4, v188, v12
	v_fmac_f32_e32 v188, v189, v8
	v_fma_f32 v4, -v4, v188, v12
	v_div_fmas_f32 v4, v4, v8, v188
	v_div_fixup_f32 v205, v4, v0, v205
	v_mul_f32_e32 v0, 0xbfb8aa3b, v204
	v_exp_f32_e32 v0, v0
	s_nop 0
	v_add_f32_e32 v0, 1.0, v0
	v_div_scale_f32 v4, s[24:25], v0, v0, v204
	v_rcp_f32_e32 v8, v4
	s_nop 0
	v_fma_f32 v12, -v4, v8, 1.0
	v_fmac_f32_e32 v8, v12, v8
	v_div_scale_f32 v12, vcc, v204, v0, v204
	v_mul_f32_e32 v188, v12, v8
	v_fma_f32 v189, -v4, v188, v12
	v_fmac_f32_e32 v188, v189, v8
	v_fma_f32 v4, -v4, v188, v12
	v_div_fmas_f32 v4, v4, v8, v188
	v_mov_b32_e32 v12, v5
	v_mov_b32_e32 v8, v1
	v_div_fixup_f32 v204, v4, v0, v204
	v_pk_add_f32 v[4:5], v[80:81], v[12:13]
	v_pk_add_f32 v[0:1], v[82:83], v[8:9]
	s_nop 0
	v_pk_add_f32 v[8:9], v[4:5], v[0:1]
	s_nop 0
	v_add_f32_e32 v8, v8, v9
	s_nop 1
	v_add_f32_dpp v8, v8, v8 row_ror:8 row_mask:0xf bank_mask:0xf bound_ctrl:1
	s_nop 1
	v_add_f32_dpp v8, v8, v8 row_ror:4 row_mask:0xf bank_mask:0xf bound_ctrl:1
	s_nop 1
	v_add_f32_dpp v8, v8, v8 row_ror:2 row_mask:0xf bank_mask:0xf bound_ctrl:1
	s_nop 1
	v_add_f32_dpp v8, v8, v8 row_ror:1 row_mask:0xf bank_mask:0xf bound_ctrl:1
	v_mul_f32_e32 v12, 0x3c800000, v8
	v_pk_add_f32 v[0:1], v[0:1], v[12:13] op_sel_hi:[1,0] neg_lo:[0,1] neg_hi:[0,1]
	v_pk_add_f32 v[8:9], v[4:5], v[12:13] op_sel_hi:[1,0] neg_lo:[0,1] neg_hi:[0,1]
	v_pk_mul_f32 v[4:5], v[0:1], v[0:1]
	v_mov_b32_e32 v13, v186
	v_pk_fma_f32 v[4:5], v[8:9], v[8:9], v[4:5]
	s_nop 0
	v_mov_b32_e32 v12, v4
	v_mov_b32_e32 v186, v5
	v_pk_add_f32 v[4:5], v[12:13], v[186:187]
	v_mov_b32_e32 v13, 0
	v_mov_b32_e32 v12, 0
	s_nop 0
	v_mov_b32_dpp v13, v5 row_ror:8 row_mask:0xf bank_mask:0xf
	v_mov_b32_dpp v12, v4 row_ror:8 row_mask:0xf bank_mask:0xf
	v_pk_add_f32 v[4:5], v[4:5], v[12:13]
	v_mov_b32_e32 v13, 0
	v_mov_b32_e32 v12, 0
	s_nop 0
	v_mov_b32_dpp v13, v5 row_ror:4 row_mask:0xf bank_mask:0xf
	v_mov_b32_dpp v12, v4 row_ror:4 row_mask:0xf bank_mask:0xf
	v_pk_add_f32 v[4:5], v[4:5], v[12:13]
	v_mov_b32_e32 v13, 0
	v_mov_b32_e32 v12, 0
	s_nop 0
	v_mov_b32_dpp v13, v5 row_ror:2 row_mask:0xf bank_mask:0xf
	v_mov_b32_dpp v12, v4 row_ror:2 row_mask:0xf bank_mask:0xf
	v_pk_add_f32 v[4:5], v[4:5], v[12:13]
	v_mov_b32_e32 v13, 0
	v_mov_b32_e32 v12, 0
	s_nop 0
	v_mov_b32_dpp v13, v5 row_ror:1 row_mask:0xf bank_mask:0xf
	v_mov_b32_dpp v12, v4 row_ror:1 row_mask:0xf bank_mask:0xf
	v_pk_add_f32 v[12:13], v[4:5], v[12:13]
	v_mov_b64_e32 v[4:5], s[0:1]
	v_pk_fma_f32 v[12:13], v[12:13], s[26:27], v[4:5] op_sel_hi:[1,0,0]
	s_nop 0
	v_mul_f32_e32 v80, 0x4b800000, v13
	v_cmp_gt_f32_e64 s[38:39], s15, v13
	v_cmp_gt_f32_e32 vcc, s15, v12
	s_nop 0
	v_cndmask_b32_e64 v13, v13, v80, s[38:39]
	v_rsq_f32_e32 v13, v13
	s_nop 0
	v_mul_f32_e32 v80, 0x45800000, v13
	v_cndmask_b32_e64 v13, v13, v80, s[38:39]
	v_mul_f32_e32 v80, v88, v13
	v_fma_f32 v80, v90, v80, v91
	v_fmac_f32_e32 v80, v193, v199
	v_mul_f32_e32 v80, v190, v80
	v_bfe_u32 v81, v80, 16, 1
	v_add3_u32 v80, v80, v81, s6
	global_store_short_d16_hi v[84:85], v80, off
	v_mul_f32_e32 v80, v86, v13
	v_fma_f32 v80, v108, v80, v109
	v_fmac_f32_e32 v80, v193, v200
	v_mul_f32_e32 v80, v191, v80
	v_bfe_u32 v81, v80, 16, 1
	v_add3_u32 v80, v80, v81, s6
	global_store_short_d16_hi v[84:85], v80, off offset:32
	v_mul_f32_e32 v80, v89, v13
	v_fma_f32 v80, v126, v80, v127
	v_fmac_f32_e32 v80, v193, v201
	v_mul_f32_e32 v13, v87, v13
	v_mul_f32_e32 v80, v205, v80
	v_fma_f32 v13, v144, v13, v145
	v_bfe_u32 v81, v80, 16, 1
	v_fmac_f32_e32 v13, v193, v202
	v_add3_u32 v80, v80, v81, s6
	v_mul_f32_e32 v13, v204, v13
	global_store_short_d16_hi v[84:85], v80, off offset:64
	v_bfe_u32 v80, v13, 16, 1
	v_add3_u32 v13, v13, v80, s6
	global_store_short_d16_hi v[84:85], v13, off offset:96
	v_mul_f32_e32 v13, 0x4b800000, v12
	v_cndmask_b32_e32 v12, v12, v13, vcc
	v_rsq_f32_e32 v12, v12
	s_nop 0
	v_mul_f32_e32 v13, 0x45800000, v12
	v_cndmask_b32_e32 v80, v12, v13, vcc
	v_lshlrev_b64 v[12:13], 11, v[78:79]
	v_mul_f32_e32 v78, 0xbfb8aa3b, v196
	v_exp_f32_e32 v78, v78
	v_mul_f32_e32 v8, v8, v80
	v_fma_f32 v8, v90, v8, v91
	v_fmac_f32_e32 v8, v180, v203
	v_add_f32_e32 v78, 1.0, v78
	v_div_scale_f32 v79, s[24:25], v78, v78, v196
	v_rcp_f32_e32 v81, v79
	v_lshl_add_u64 v[12:13], v[56:57], 0, v[12:13]
	v_mul_f32_e32 v0, v0, v80
	v_fma_f32 v0, v108, v0, v109
	v_fma_f32 v82, -v79, v81, 1.0
	v_fmac_f32_e32 v81, v82, v81
	v_div_scale_f32 v82, vcc, v196, v78, v196
	v_mul_f32_e32 v83, v82, v81
	v_fma_f32 v84, -v79, v83, v82
	v_fmac_f32_e32 v83, v84, v81
	v_fma_f32 v79, -v79, v83, v82
	v_div_fmas_f32 v79, v79, v81, v83
	v_div_fixup_f32 v78, v79, v78, v196
	v_mul_f32_e32 v8, v78, v8
	v_bfe_u32 v78, v8, 16, 1
	v_add3_u32 v8, v8, v78, s6
	global_store_short_d16_hi v[12:13], v8, off
	v_mul_f32_e32 v8, 0xbfb8aa3b, v194
; __device__ __forceinline__ unsigned f2bf(float f) { unsigned u = __float_as_uint(f); return (u + 0x7fffu + ((u >> 16) & 1u)) >> 16; }
; __device__ __forceinline__ float silu(float x) { return x / (1.f + __expf(-x)); }
; __device__ __forceinline__ void even_fixup(const Params& p, int j, LAS unsigned char* lds, int gw, int NGW, int wave, int lane) {
;     ...
;             for (int r = 0; r < 4; ++r) {
;                 float y[4];
; #pragma unroll
;                 for (int it = 0; it < 4; ++it) y[it] = acc[it][r] + yl[r][it];
;                 const float mean = row16_sum((y[0] + y[1]) + (y[2] + y[3])) * (1.f / 64.f);
; #pragma unroll
;                 for (int it = 0; it < 4; ++it) y[it] -= mean;
;                 const float var = row16_sum((y[0] * y[0] + y[1] * y[1]) + (y[2] * y[2] + y[3] * y[3])) * (1.f / 64.f);
;                 const float rs = rsqrtf(var + 64e-5f);
;                 const size_t n = (size_t)(nb + tt * 16 + g4 * 4 + r);
; #pragma unroll
;                 for (int it = 0; it < 4; ++it) { const float yn = y[it] * rs * gg[it] + gb[it] + bon[r] * vv[r][it];
;                     MIX[n * DM + h * 64 + it * 16 + fr] = (bf16_t)f2bf(yn * silu(za[r][it])); }
	v_exp_f32_e32 v8, v8
	v_fmac_f32_e32 v0, v180, v198
	v_add_f32_e32 v8, 1.0, v8
	v_div_scale_f32 v78, s[24:25], v8, v8, v194
	v_rcp_f32_e32 v79, v78
	s_nop 0
	v_fma_f32 v81, -v78, v79, 1.0
	v_fmac_f32_e32 v79, v81, v79
	v_div_scale_f32 v81, vcc, v194, v8, v194
	v_mul_f32_e32 v82, v81, v79
	v_fma_f32 v83, -v78, v82, v81
	v_fmac_f32_e32 v82, v83, v79
	v_fma_f32 v78, -v78, v82, v81
	v_div_fmas_f32 v78, v78, v79, v82
	v_div_fixup_f32 v8, v78, v8, v194
	v_mul_f32_e32 v0, v8, v0
	v_bfe_u32 v8, v0, 16, 1
	v_add3_u32 v0, v0, v8, s6
	v_mul_f32_e32 v8, 0xbfb8aa3b, v192
	v_exp_f32_e32 v8, v8
	global_store_short_d16_hi v[12:13], v0, off offset:32
	v_mul_f32_e32 v0, v9, v80
	v_fma_f32 v0, v126, v0, v127
	v_add_f32_e32 v8, 1.0, v8
	v_div_scale_f32 v9, s[24:25], v8, v8, v192
	v_rcp_f32_e32 v78, v9
	v_fmac_f32_e32 v0, v180, v195
	v_fma_f32 v79, -v9, v78, 1.0
	v_fmac_f32_e32 v78, v79, v78
	v_div_scale_f32 v79, vcc, v192, v8, v192
	v_mul_f32_e32 v81, v79, v78
	v_fma_f32 v82, -v9, v81, v79
	v_fmac_f32_e32 v81, v82, v78
	v_fma_f32 v9, -v9, v81, v79
	v_div_fmas_f32 v9, v9, v78, v81
	v_div_fixup_f32 v8, v9, v8, v192
	v_mul_f32_e32 v0, v8, v0
	v_bfe_u32 v8, v0, 16, 1
	v_add3_u32 v0, v0, v8, s6
	global_store_short_d16_hi v[12:13], v0, off offset:64
	v_mul_f32_e32 v0, v1, v80
	v_mul_f32_e32 v1, 0xbfb8aa3b, v182
	v_exp_f32_e32 v1, v1
	v_fma_f32 v0, v144, v0, v145
	v_fmac_f32_e32 v0, v180, v183
	v_add_f32_e32 v1, 1.0, v1
	v_div_scale_f32 v8, s[24:25], v1, v1, v182
	v_rcp_f32_e32 v9, v8
	s_nop 0
	v_fma_f32 v78, -v8, v9, 1.0
	v_fmac_f32_e32 v9, v78, v9
	v_div_scale_f32 v78, vcc, v182, v1, v182
	v_mul_f32_e32 v79, v78, v9
	v_fma_f32 v80, -v8, v79, v78
	v_fmac_f32_e32 v79, v80, v9
	v_fma_f32 v8, -v8, v79, v78
	v_div_fmas_f32 v8, v8, v9, v79
	v_div_fixup_f32 v1, v8, v1, v182
	v_mul_f32_e32 v0, v1, v0
	v_bfe_u32 v1, v0, 16, 1
	v_add3_u32 v0, v0, v1, s6
	global_store_short_d16_hi v[12:13], v0, off offset:96
	v_mov_b32_e32 v0, v6
	v_mov_b32_e32 v1, v14
	v_mov_b32_e32 v8, v2
	v_mov_b32_e32 v9, v10
	v_pk_add_f32 v[0:1], v[74:75], v[0:1]
	v_pk_add_f32 v[8:9], v[76:77], v[8:9]
	s_nop 0
	v_pk_add_f32 v[12:13], v[0:1], v[8:9]
	s_nop 0
	v_add_f32_e32 v2, v12, v13
	s_nop 1
	v_add_f32_dpp v2, v2, v2 row_ror:8 row_mask:0xf bank_mask:0xf bound_ctrl:1
	s_nop 1
	v_add_f32_dpp v2, v2, v2 row_ror:4 row_mask:0xf bank_mask:0xf bound_ctrl:1
	s_nop 1
	v_add_f32_dpp v2, v2, v2 row_ror:2 row_mask:0xf bank_mask:0xf bound_ctrl:1
	s_nop 1
	v_add_f32_dpp v2, v2, v2 row_ror:1 row_mask:0xf bank_mask:0xf bound_ctrl:1
	v_mul_f32_e32 v2, 0x3c800000, v2
	v_pk_add_f32 v[12:13], v[8:9], v[2:3] op_sel_hi:[1,0] neg_lo:[0,1] neg_hi:[0,1]
	v_pk_add_f32 v[74:75], v[0:1], v[2:3] op_sel_hi:[1,0] neg_lo:[0,1] neg_hi:[0,1]
	v_pk_mul_f32 v[0:1], v[12:13], v[12:13]
	s_nop 0
	v_pk_fma_f32 v[78:79], v[74:75], v[74:75], v[0:1]
	v_lshlrev_b64 v[0:1], 11, v[72:73]
	v_lshl_add_u64 v[8:9], v[56:57], 0, v[0:1]
	v_mul_f32_e32 v0, 0xbfb8aa3b, v181
	v_exp_f32_e32 v0, v0
	s_nop 0
	v_add_f32_e32 v0, 1.0, v0
	v_div_scale_f32 v1, s[24:25], v0, v0, v181
	v_rcp_f32_e32 v2, v1
	s_nop 0
	v_fma_f32 v6, -v1, v2, 1.0
	v_fmac_f32_e32 v2, v6, v2
	v_div_scale_f32 v6, vcc, v181, v0, v181
	v_mul_f32_e32 v10, v6, v2
	v_fma_f32 v14, -v1, v10, v6
	v_fmac_f32_e32 v10, v14, v2
	v_fma_f32 v1, -v1, v10, v6
	v_div_fmas_f32 v1, v1, v2, v10
	v_div_fixup_f32 v72, v1, v0, v181
	v_mul_f32_e32 v0, 0xbfb8aa3b, v179
	v_exp_f32_e32 v0, v0
	s_nop 0
	v_add_f32_e32 v0, 1.0, v0
	v_div_scale_f32 v1, s[24:25], v0, v0, v179
	v_rcp_f32_e32 v2, v1
	s_nop 0
	v_fma_f32 v6, -v1, v2, 1.0
	v_fmac_f32_e32 v2, v6, v2
	v_div_scale_f32 v6, vcc, v179, v0, v179
	v_mul_f32_e32 v10, v6, v2
	v_fma_f32 v14, -v1, v10, v6
	v_fmac_f32_e32 v10, v14, v2
	v_fma_f32 v1, -v1, v10, v6
	v_div_fmas_f32 v1, v1, v2, v10
	v_div_fixup_f32 v73, v1, v0, v179
	v_mul_f32_e32 v0, 0xbfb8aa3b, v178
	v_exp_f32_e32 v0, v0
	s_nop 0
	v_add_f32_e32 v0, 1.0, v0
	v_div_scale_f32 v1, s[24:25], v0, v0, v178
	v_rcp_f32_e32 v2, v1
	s_nop 0
	v_fma_f32 v6, -v1, v2, 1.0
	v_fmac_f32_e32 v2, v6, v2
	v_div_scale_f32 v6, vcc, v178, v0, v178
	v_mul_f32_e32 v10, v6, v2
	v_fma_f32 v14, -v1, v10, v6
	v_fmac_f32_e32 v10, v14, v2
	v_fma_f32 v1, -v1, v10, v6
	v_div_fmas_f32 v1, v1, v2, v10
	v_div_fixup_f32 v76, v1, v0, v178
	v_mul_f32_e32 v0, 0xbfb8aa3b, v177
	v_exp_f32_e32 v0, v0
	s_nop 0
	v_add_f32_e32 v0, 1.0, v0
	v_div_scale_f32 v1, s[24:25], v0, v0, v177
	v_rcp_f32_e32 v2, v1
	s_nop 0
	v_fma_f32 v6, -v1, v2, 1.0
	v_fmac_f32_e32 v2, v6, v2
	v_div_scale_f32 v6, vcc, v177, v0, v177
	v_mul_f32_e32 v10, v6, v2
	v_fma_f32 v14, -v1, v10, v6
	v_fmac_f32_e32 v10, v14, v2
	v_fma_f32 v1, -v1, v10, v6
	v_div_fmas_f32 v1, v1, v2, v10
	v_mov_b32_e32 v14, v7
	v_mov_b32_e32 v10, v3
	v_div_fixup_f32 v77, v1, v0, v177
	v_pk_add_f32 v[0:1], v[68:69], v[14:15]
	v_pk_add_f32 v[6:7], v[70:71], v[10:11]
	s_nop 0
	v_pk_add_f32 v[2:3], v[0:1], v[6:7]
	s_nop 0
	v_add_f32_e32 v2, v2, v3
	s_nop 1
	v_add_f32_dpp v2, v2, v2 row_ror:8 row_mask:0xf bank_mask:0xf bound_ctrl:1
	s_nop 1
	v_add_f32_dpp v2, v2, v2 row_ror:4 row_mask:0xf bank_mask:0xf bound_ctrl:1
	s_nop 1
	v_add_f32_dpp v2, v2, v2 row_ror:2 row_mask:0xf bank_mask:0xf bound_ctrl:1
	s_nop 1
	v_add_f32_dpp v2, v2, v2 row_ror:1 row_mask:0xf bank_mask:0xf bound_ctrl:1
	v_mul_f32_e32 v10, 0x3c800000, v2
	v_pk_add_f32 v[2:3], v[0:1], v[10:11] op_sel_hi:[1,0] neg_lo:[0,1] neg_hi:[0,1]
	v_pk_add_f32 v[0:1], v[6:7], v[10:11] op_sel_hi:[1,0] neg_lo:[0,1] neg_hi:[0,1]
	v_mov_b32_e32 v11, v78
	v_pk_mul_f32 v[6:7], v[0:1], v[0:1]
	s_nop 0
	v_pk_fma_f32 v[6:7], v[2:3], v[2:3], v[6:7]
	s_nop 0
	v_mov_b32_e32 v10, v6
	v_mov_b32_e32 v78, v7
	v_pk_add_f32 v[6:7], v[10:11], v[78:79]
	v_mov_b32_e32 v11, 0
; __device__ __forceinline__ float bf2f(bf16_t h) { return __uint_as_float(((unsigned)h) << 16); }
; __device__ __forceinline__ unsigned f2bf(float f) { unsigned u = __float_as_uint(f); return (u + 0x7fffu + ((u >> 16) & 1u)) >> 16; }
; __device__ __forceinline__ float silu(float x) { return x / (1.f + __expf(-x)); }
; __device__ __forceinline__ void even_fixup(const Params& p, int j, LAS unsigned char* lds, int gw, int NGW, int wave, int lane) {
;     ...
;                 const float var = row16_sum((y[0] * y[0] + y[1] * y[1]) + (y[2] * y[2] + y[3] * y[3])) * (1.f / 64.f);
;                 const float rs = rsqrtf(var + 64e-5f);
;                 const size_t n = (size_t)(nb + tt * 16 + g4 * 4 + r);
; #pragma unroll
;                 for (int it = 0; it < 4; ++it) { const float yn = y[it] * rs * gg[it] + gb[it] + bon[r] * vv[r][it];
;                     MIX[n * DM + h * 64 + it * 16 + fr] = (bf16_t)f2bf(yn * silu(za[r][it])); }
;             }
;         }
;     }
;     for (int task = gw; task < NS * 8; task += NGW) {
;         const int n = NP + (task >> 3), h = task & 7, ch = h * 64 + lane;
;         even_finish_vals(YL[(size_t)n * 512 + ch], p.in[18][j * 512 + ch], p.in[19][j * 512 + ch], BON[(size_t)n * 8 + h], SV[(size_t)n * 512 + ch], bf2f(P[(size_t)n * EINP + ASW + ch]), MIX + (size_t)n * DM + ch);
	v_mov_b32_e32 v10, 0
	s_nop 0
	v_mov_b32_dpp v11, v7 row_ror:8 row_mask:0xf bank_mask:0xf
	v_mov_b32_dpp v10, v6 row_ror:8 row_mask:0xf bank_mask:0xf
	v_pk_add_f32 v[6:7], v[6:7], v[10:11]
	v_mov_b32_e32 v11, 0
	v_mov_b32_e32 v10, 0
	s_nop 0
	v_mov_b32_dpp v11, v7 row_ror:4 row_mask:0xf bank_mask:0xf
	v_mov_b32_dpp v10, v6 row_ror:4 row_mask:0xf bank_mask:0xf
	v_pk_add_f32 v[6:7], v[6:7], v[10:11]
	v_mov_b32_e32 v11, 0
	v_mov_b32_e32 v10, 0
	s_nop 0
	v_mov_b32_dpp v11, v7 row_ror:2 row_mask:0xf bank_mask:0xf
	v_mov_b32_dpp v10, v6 row_ror:2 row_mask:0xf bank_mask:0xf
	v_pk_add_f32 v[6:7], v[6:7], v[10:11]
	v_mov_b32_e32 v11, 0
	v_mov_b32_e32 v10, 0
	s_nop 0
	v_mov_b32_dpp v11, v7 row_ror:1 row_mask:0xf bank_mask:0xf
	v_mov_b32_dpp v10, v6 row_ror:1 row_mask:0xf bank_mask:0xf
	v_pk_add_f32 v[6:7], v[6:7], v[10:11]
	s_nop 0
	v_pk_fma_f32 v[4:5], v[6:7], s[26:27], v[4:5] op_sel_hi:[1,0,0]
	s_nop 0
	v_mul_f32_e32 v6, 0x4b800000, v5
	v_cmp_gt_f32_e64 s[38:39], s15, v5
	v_cmp_gt_f32_e32 vcc, s15, v4
	s_nop 0
	v_cndmask_b32_e64 v5, v5, v6, s[38:39]
	v_rsq_f32_e32 v5, v5
	s_nop 0
	v_mul_f32_e32 v6, 0x45800000, v5
	v_cndmask_b32_e64 v5, v5, v6, s[38:39]
	v_mul_f32_e32 v6, v74, v5
	v_fma_f32 v6, v90, v6, v91
	v_fmac_f32_e32 v6, v171, v172
	v_mul_f32_e32 v6, v72, v6
	v_bfe_u32 v7, v6, 16, 1
	v_add3_u32 v6, v6, v7, s6
	global_store_short_d16_hi v[8:9], v6, off
	v_mul_f32_e32 v6, v12, v5
	v_fma_f32 v6, v108, v6, v109
	v_fmac_f32_e32 v6, v171, v173
	v_mul_f32_e32 v6, v73, v6
	v_bfe_u32 v7, v6, 16, 1
	v_add3_u32 v6, v6, v7, s6
	global_store_short_d16_hi v[8:9], v6, off offset:32
	v_mul_f32_e32 v6, v75, v5
	v_fma_f32 v6, v126, v6, v127
	v_fmac_f32_e32 v6, v171, v174
	v_mul_f32_e32 v6, v76, v6
	v_bfe_u32 v7, v6, 16, 1
	v_mul_f32_e32 v5, v13, v5
	v_add3_u32 v6, v6, v7, s6
	v_fma_f32 v5, v144, v5, v145
	v_mul_f32_e32 v7, 0xbfb8aa3b, v169
	v_fmac_f32_e32 v5, v171, v175
	v_exp_f32_e32 v7, v7
	v_mul_f32_e32 v5, v77, v5
	global_store_short_d16_hi v[8:9], v6, off offset:64
	v_bfe_u32 v6, v5, 16, 1
	v_add3_u32 v5, v5, v6, s6
	global_store_short_d16_hi v[8:9], v5, off offset:96
	v_mul_f32_e32 v5, 0x4b800000, v4
	v_add_f32_e32 v7, 1.0, v7
	v_cndmask_b32_e32 v4, v4, v5, vcc
	v_div_scale_f32 v8, s[24:25], v7, v7, v169
	v_rsq_f32_e32 v4, v4
	v_rcp_f32_e32 v9, v8
	v_mul_f32_e32 v5, 0x45800000, v4
	v_fma_f32 v10, -v8, v9, 1.0
	v_cndmask_b32_e32 v6, v4, v5, vcc
	v_fmac_f32_e32 v9, v10, v9
	v_div_scale_f32 v10, vcc, v169, v7, v169
	v_mul_f32_e32 v11, v10, v9
	v_fma_f32 v12, -v8, v11, v10
	v_fmac_f32_e32 v11, v12, v9
	v_mul_f32_e32 v2, v2, v6
	v_fma_f32 v8, -v8, v11, v10
	v_fma_f32 v2, v90, v2, v91
	v_div_fmas_f32 v8, v8, v9, v11
	v_fmac_f32_e32 v2, v164, v176
	v_div_fixup_f32 v7, v8, v7, v169
	v_mul_f32_e32 v2, v7, v2
	v_lshlrev_b64 v[4:5], 11, v[66:67]
	v_bfe_u32 v7, v2, 16, 1
	v_lshl_add_u64 v[4:5], v[56:57], 0, v[4:5]
	v_add3_u32 v2, v2, v7, s6
	global_store_short_d16_hi v[4:5], v2, off
	v_mul_f32_e32 v2, 0xbfb8aa3b, v167
	v_exp_f32_e32 v2, v2
	v_mul_f32_e32 v0, v0, v6
	v_fma_f32 v0, v108, v0, v109
	v_fmac_f32_e32 v0, v164, v170
	v_add_f32_e32 v2, 1.0, v2
	v_div_scale_f32 v7, s[24:25], v2, v2, v167
	v_rcp_f32_e32 v8, v7
	s_nop 0
	v_fma_f32 v9, -v7, v8, 1.0
	v_fmac_f32_e32 v8, v9, v8
	v_div_scale_f32 v9, vcc, v167, v2, v167
	v_mul_f32_e32 v10, v9, v8
	v_fma_f32 v11, -v7, v10, v9
	v_fmac_f32_e32 v10, v11, v8
	v_fma_f32 v7, -v7, v10, v9
	v_div_fmas_f32 v7, v7, v8, v10
	v_div_fixup_f32 v2, v7, v2, v167
	v_mul_f32_e32 v0, v2, v0
	v_bfe_u32 v2, v0, 16, 1
	v_add3_u32 v0, v0, v2, s6
	v_mul_f32_e32 v2, 0xbfb8aa3b, v166
	v_exp_f32_e32 v2, v2
	global_store_short_d16_hi v[4:5], v0, off offset:32
	v_mul_f32_e32 v0, v3, v6
	v_fma_f32 v0, v126, v0, v127
	v_add_f32_e32 v2, 1.0, v2
	v_div_scale_f32 v3, s[24:25], v2, v2, v166
	v_rcp_f32_e32 v7, v3
	v_fmac_f32_e32 v0, v164, v168
	v_fma_f32 v8, -v3, v7, 1.0
	v_fmac_f32_e32 v7, v8, v7
	v_div_scale_f32 v8, vcc, v166, v2, v166
	v_mul_f32_e32 v9, v8, v7
	v_fma_f32 v10, -v3, v9, v8
	v_fmac_f32_e32 v9, v10, v7
	v_fma_f32 v3, -v3, v9, v8
	v_div_fmas_f32 v3, v3, v7, v9
	v_div_fixup_f32 v2, v3, v2, v166
	v_mul_f32_e32 v0, v2, v0
	v_bfe_u32 v2, v0, 16, 1
	v_add3_u32 v0, v0, v2, s6
	global_store_short_d16_hi v[4:5], v0, off offset:64
	v_mul_f32_e32 v0, v1, v6
	v_mul_f32_e32 v1, 0xbfb8aa3b, v163
	v_exp_f32_e32 v1, v1
	v_fma_f32 v0, v144, v0, v145
	v_fmac_f32_e32 v0, v164, v165
	v_add_f32_e32 v1, 1.0, v1
	v_div_scale_f32 v2, s[24:25], v1, v1, v163
	v_rcp_f32_e32 v3, v2
	s_nop 0
	v_fma_f32 v6, -v2, v3, 1.0
	v_fmac_f32_e32 v3, v6, v3
	v_div_scale_f32 v6, vcc, v163, v1, v163
	v_mul_f32_e32 v7, v6, v3
	v_fma_f32 v8, -v2, v7, v6
	v_fmac_f32_e32 v7, v8, v3
	v_fma_f32 v2, -v2, v7, v6
	v_div_fmas_f32 v2, v2, v3, v7
	v_div_fixup_f32 v1, v2, v1, v163
	v_mul_f32_e32 v0, v1, v0
	v_bfe_u32 v1, v0, 16, 1
	v_add3_u32 v0, v0, v1, s6
	global_store_short_d16_hi v[4:5], v0, off offset:96
	s_cbranch_scc0 .LBB0_1501
	v_readlane_b32 s24, v255, 13
	s_add_i32 s42, s42, s24
	s_cmpk_lt_i32 s42, 0x800
	v_readlane_b32 s25, v255, 14
	s_cbranch_scc1 .LBB0_1500
	s_and_b32 s0, s2, 7
	v_lshl_add_u32 v184, s0, 6, v55
	v_add_u32_e32 v0, s70, v184
	v_mov_b32_e32 v1, v185
	v_readlane_b32 s44, v251, 41
	v_lshlrev_b64 v[2:3], 2, v[0:1]
	v_readlane_b32 s48, v251, 45
	v_readlane_b32 s49, v251, 46
	v_readlane_b32 s50, v251, 47
	v_readlane_b32 s51, v251, 48
	v_lshl_add_u64 v[0:1], s[48:49], 0, v[2:3]
	global_load_dword v1, v[0:1], off
	v_lshl_add_u64 v[2:3], s[50:51], 0, v[2:3]
	global_load_dword v6, v[2:3], off
	s_lshl_b32 s0, s0, 2
	v_readlane_b32 s2, v253, 55
	s_add_u32 s0, s2, s0
	v_readlane_b32 s2, v253, 56
	s_addc_u32 s7, s2, 0
	v_readlane_b32 s2, v254, 4
	v_lshlrev_b32_e32 v4, 1, v184
	v_mov_b32_e32 v5, v185
	v_readlane_b32 s3, v254, 5
	v_readlane_b32 s24, v255, 13
	v_readlane_b32 s45, v251, 42
	v_lshl_add_u64 v[2:3], s[2:3], 0, v[4:5]
	v_readlane_b32 s2, v253, 23
	v_readlane_b32 s3, v253, 24
	v_readlane_b32 s46, v251, 43
	v_readlane_b32 s47, v251, 44
	v_lshl_add_u64 v[4:5], s[2:3], 0, v[4:5]
	v_readlane_b32 s52, v251, 49
	v_readlane_b32 s53, v251, 50
	v_readlane_b32 s54, v251, 51
	v_readlane_b32 s55, v251, 52
	v_readlane_b32 s56, v251, 53
	v_readlane_b32 s57, v251, 54
	v_readlane_b32 s58, v251, 55
	v_readlane_b32 s59, v251, 56
	v_readlane_b32 s25, v255, 14
